# phase 13 conv: loads of the up-projection rows without the nt hint (data was just written by the previous phase)
# speedup vs baseline: 1.1534x; 1.0004x over previous
.LBB0_2490:
	s_cmp_lt_i32 s68, 14
	s_cselect_b64 s[0:1], -1, 0
	s_cmp_gt_i32 s69, 13
	s_cselect_b64 s[2:3], -1, 0
	s_and_b64 s[0:1], s[0:1], s[2:3]
	s_andn2_b64 vcc, exec, s[0:1]
	s_cbranch_vccnz .LBB0_2582
	s_add_u32 s8, s34, 0xd322200
	s_mov_b32 s29, 0
	v_mov_b32_e32 v87, 0
	s_addc_u32 s9, s35, 0
	s_lshl_b64 s[0:1], s[28:29], 9
	v_mov_b32_e32 v35, v87
	v_lshl_add_u64 v[84:85], s[0:1], 0, v[34:35]
	s_mov_b32 s0, s88
	s_mov_b32 s1, s29
	s_lshl_b64 s[6:7], s[0:1], 9
	s_mov_b64 s[0:1], 0x58000
	v_cmp_gt_u64_e32 vcc, s[0:1], v[84:85]
	s_and_saveexec_b64 s[10:11], vcc
	s_cbranch_execz .LBB0_2504
	s_cmpk_lg_i32 s88, 0x100
	s_cbranch_scc1 .Lconv_orig
	v_readlane_b32 s12, v254, 62
	v_readlane_b32 s13, v254, 63
	v_readlane_b32 s24, v255, 0
	v_readlane_b32 s25, v255, 1
	s_add_u32 s36, s34, 0xd322200
	s_addc_u32 s37, s35, 0
	s_add_u32 s38, s34, 0x190e2200
	s_addc_u32 s39, s35, 0
	s_nop 0
	s_add_u32 s14, s12, 0x5800
	s_addc_u32 s15, s13, 0
	s_add_u32 s16, s12, 0xb000
	s_addc_u32 s17, s13, 0
	s_add_u32 s18, s12, 0x10800
	s_addc_u32 s19, s13, 0
	s_add_u32 s20, s12, 0x16000
	s_addc_u32 s21, s13, 0
	s_add_u32 s22, s12, 0x1b800
	s_addc_u32 s23, s13, 0
	s_add_u32 s26, s24, 0x5800
	s_addc_u32 s27, s25, 0
	v_mov_b32_e32 v164, 0x5800
	v_mov_b32_e32 v165, 0
	v_mov_b32_e32 v30, 0x2c00
	v_mov_b32_e32 v31, 0
	v_mov_b32_e32 v152, 0x5d1746
	v_mul_hi_u32 v157, v84, v152
	v_mul_u32_u24_e32 v152, 0x2c0, v157
	v_sub_u32_e32 v32, v84, v152
	v_mul_u32_u24_e32 v152, 0x58000, v157
	v_lshl_add_u32 v152, v32, 4, v152
	v_mov_b32_e32 v153, 0
	v_lshl_add_u64 v[158:159], s[36:37], 0, v[152:153]
	v_mul_u32_u24_e32 v152, 0x2c000, v157
	v_lshl_add_u32 v152, v32, 4, v152
	v_lshl_add_u64 v[162:163], s[38:39], 0, v[152:153]
	v_lshlrev_b32_e32 v33, 5, v32
	v_and_b32_e32 v152, 0x7f, v157
	v_cmp_eq_u32_e64 s[40:41], 0, v152
	v_mov_b32_e32 v152, 0x2c00
	v_lshl_add_u64 v[160:161], v[158:159], 0, v[152:153]
	global_load_dwordx4 v[104:107], v33, s[12:13]
	global_load_dwordx4 v[108:111], v33, s[12:13] offset:16
	global_load_dwordx4 v[112:115], v33, s[14:15]
	global_load_dwordx4 v[116:119], v33, s[14:15] offset:16
	global_load_dwordx4 v[120:123], v33, s[16:17]
	global_load_dwordx4 v[124:127], v33, s[16:17] offset:16
	global_load_dwordx4 v[128:131], v33, s[18:19]
	global_load_dwordx4 v[132:135], v33, s[18:19] offset:16
	global_load_dwordx4 v[136:139], v33, s[20:21]
	global_load_dwordx4 v[140:143], v33, s[20:21] offset:16
	global_load_dwordx4 v[144:147], v33, s[22:23]
	global_load_dwordx4 v[148:151], v33, s[22:23] offset:16
	global_load_dwordx4 v[174:177], v33, s[24:25]
	global_load_dwordx4 v[178:181], v33, s[24:25] offset:16
	global_load_dwordx4 v[182:185], v33, s[26:27]
	global_load_dwordx4 v[186:189], v33, s[26:27] offset:16
	v_mov_b32_e32 v152, 0xffffa800
	v_mov_b32_e32 v153, -1
	v_lshl_add_u64 v[154:155], v[158:159], 0, v[152:153]
	global_load_dwordx4 v[238:241], v[154:155], off
	v_lshl_add_u64 v[154:155], v[154:155], 0, v[152:153]
	global_load_dwordx4 v[246:249], v[154:155], off
	v_lshl_add_u64 v[154:155], v[160:161], 0, v[152:153]
	global_load_dwordx4 v[242:245], v[154:155], off
	v_lshl_add_u64 v[154:155], v[154:155], 0, v[152:153]
	global_load_dwordx4 v[250:253], v[154:155], off
	global_load_dwordx4 v[36:39], v[158:159], off
	global_load_dwordx4 v[40:43], v[160:161], off
	v_lshl_add_u64 v[158:159], v[158:159], 0, v[164:165]
	v_lshl_add_u64 v[160:161], v[160:161], 0, v[164:165]
	global_load_dwordx4 v[44:47], v[158:159], off
	global_load_dwordx4 v[48:51], v[160:161], off
	v_lshl_add_u64 v[158:159], v[158:159], 0, v[164:165]
	v_lshl_add_u64 v[160:161], v[160:161], 0, v[164:165]
	global_load_dwordx4 v[52:55], v[158:159], off
	global_load_dwordx4 v[56:59], v[160:161], off
	v_lshl_add_u64 v[158:159], v[158:159], 0, v[164:165]
	v_lshl_add_u64 v[160:161], v[160:161], 0, v[164:165]
	global_load_dwordx4 v[60:63], v[158:159], off
	global_load_dwordx4 v[64:67], v[160:161], off
	v_lshl_add_u64 v[158:159], v[158:159], 0, v[164:165]
	v_lshl_add_u64 v[160:161], v[160:161], 0, v[164:165]
	global_load_dwordx4 v[68:71], v[158:159], off
	global_load_dwordx4 v[72:75], v[160:161], off
	v_lshl_add_u64 v[158:159], v[158:159], 0, v[164:165]
	v_lshl_add_u64 v[160:161], v[160:161], 0, v[164:165]
	global_load_dwordx4 v[76:79], v[158:159], off
	global_load_dwordx4 v[80:83], v[160:161], off
	v_lshl_add_u64 v[158:159], v[158:159], 0, v[164:165]
	v_lshl_add_u64 v[160:161], v[160:161], 0, v[164:165]
	global_load_dwordx4 v[88:91], v[158:159], off
	global_load_dwordx4 v[92:95], v[160:161], off
	v_lshl_add_u64 v[158:159], v[158:159], 0, v[164:165]
	v_lshl_add_u64 v[160:161], v[160:161], 0, v[164:165]
	global_load_dwordx4 v[96:99], v[158:159], off
	global_load_dwordx4 v[100:103], v[160:161], off
	v_lshl_add_u64 v[158:159], v[158:159], 0, v[164:165]
	v_lshl_add_u64 v[160:161], v[160:161], 0, v[164:165]
	s_waitcnt vmcnt(8)
	v_lshlrev_b32_e32 v222, 16, v238
	v_and_b32_e32 v223, 0xffff0000, v238
	v_lshlrev_b32_e32 v224, 16, v239
	v_and_b32_e32 v225, 0xffff0000, v239
	v_lshlrev_b32_e32 v226, 16, v240
	v_and_b32_e32 v227, 0xffff0000, v240
	v_lshlrev_b32_e32 v228, 16, v241
	v_and_b32_e32 v229, 0xffff0000, v241
	v_lshlrev_b32_e32 v206, 16, v246
	v_and_b32_e32 v207, 0xffff0000, v246
	v_lshlrev_b32_e32 v208, 16, v247
	v_and_b32_e32 v209, 0xffff0000, v247
	v_lshlrev_b32_e32 v210, 16, v248
	v_and_b32_e32 v211, 0xffff0000, v248
	v_lshlrev_b32_e32 v212, 16, v249
	v_and_b32_e32 v213, 0xffff0000, v249
	v_lshlrev_b32_e32 v230, 16, v242
	v_and_b32_e32 v231, 0xffff0000, v242
	v_lshlrev_b32_e32 v232, 16, v243
	v_and_b32_e32 v233, 0xffff0000, v243
	v_lshlrev_b32_e32 v234, 16, v244
	v_and_b32_e32 v235, 0xffff0000, v244
	v_lshlrev_b32_e32 v236, 16, v245
	v_and_b32_e32 v237, 0xffff0000, v245
	v_lshlrev_b32_e32 v214, 16, v250
	v_and_b32_e32 v215, 0xffff0000, v250
	v_lshlrev_b32_e32 v216, 16, v251
	v_and_b32_e32 v217, 0xffff0000, v251
	v_lshlrev_b32_e32 v218, 16, v252
	v_and_b32_e32 v219, 0xffff0000, v252
	v_lshlrev_b32_e32 v220, 16, v253
	v_and_b32_e32 v221, 0xffff0000, v253
	v_cndmask_b32_e64 v206, v206, 0, s[40:41]
	v_cndmask_b32_e64 v207, v207, 0, s[40:41]
	v_cndmask_b32_e64 v208, v208, 0, s[40:41]
	v_cndmask_b32_e64 v209, v209, 0, s[40:41]
	v_cndmask_b32_e64 v210, v210, 0, s[40:41]
	v_cndmask_b32_e64 v211, v211, 0, s[40:41]
	v_cndmask_b32_e64 v212, v212, 0, s[40:41]
	v_cndmask_b32_e64 v213, v213, 0, s[40:41]
	v_cndmask_b32_e64 v214, v214, 0, s[40:41]
	v_cndmask_b32_e64 v215, v215, 0, s[40:41]
	v_cndmask_b32_e64 v216, v216, 0, s[40:41]
	v_cndmask_b32_e64 v217, v217, 0, s[40:41]
	v_cndmask_b32_e64 v218, v218, 0, s[40:41]
	v_cndmask_b32_e64 v219, v219, 0, s[40:41]
	v_cndmask_b32_e64 v220, v220, 0, s[40:41]
	v_cndmask_b32_e64 v221, v221, 0, s[40:41]
	v_cndmask_b32_e64 v222, v222, 0, s[40:41]
	v_cndmask_b32_e64 v223, v223, 0, s[40:41]
	v_cndmask_b32_e64 v224, v224, 0, s[40:41]
	v_cndmask_b32_e64 v225, v225, 0, s[40:41]
	v_cndmask_b32_e64 v226, v226, 0, s[40:41]
	v_cndmask_b32_e64 v227, v227, 0, s[40:41]
	v_cndmask_b32_e64 v228, v228, 0, s[40:41]
	v_cndmask_b32_e64 v229, v229, 0, s[40:41]
	v_cndmask_b32_e64 v230, v230, 0, s[40:41]
	v_cndmask_b32_e64 v231, v231, 0, s[40:41]
	v_cndmask_b32_e64 v232, v232, 0, s[40:41]
	v_cndmask_b32_e64 v233, v233, 0, s[40:41]
	v_cndmask_b32_e64 v234, v234, 0, s[40:41]
	v_cndmask_b32_e64 v235, v235, 0, s[40:41]
	v_cndmask_b32_e64 v236, v236, 0, s[40:41]
	v_cndmask_b32_e64 v237, v237, 0, s[40:41]
	v_lshlrev_b32_e32 v190, 16, v36
	v_and_b32_e32 v191, 0xffff0000, v36
	v_lshlrev_b32_e32 v192, 16, v37
	v_and_b32_e32 v193, 0xffff0000, v37
	v_lshlrev_b32_e32 v194, 16, v38
	v_and_b32_e32 v195, 0xffff0000, v38
	v_lshlrev_b32_e32 v196, 16, v39
	v_and_b32_e32 v197, 0xffff0000, v39
	v_lshlrev_b32_e32 v198, 16, v40
	v_and_b32_e32 v199, 0xffff0000, v40
	v_lshlrev_b32_e32 v200, 16, v41
	v_and_b32_e32 v201, 0xffff0000, v41
	v_lshlrev_b32_e32 v202, 16, v42
	v_and_b32_e32 v203, 0xffff0000, v42
	v_lshlrev_b32_e32 v204, 16, v43
	v_and_b32_e32 v205, 0xffff0000, v43
	v_pk_fma_f32 v[2:3], v[104:105], v[206:207], v[174:175]
	v_pk_fma_f32 v[4:5], v[106:107], v[208:209], v[176:177]
	v_pk_fma_f32 v[6:7], v[108:109], v[210:211], v[178:179]
	v_pk_fma_f32 v[8:9], v[110:111], v[212:213], v[180:181]
	v_pk_fma_f32 v[10:11], v[112:113], v[214:215], v[182:183]
	v_pk_fma_f32 v[12:13], v[114:115], v[216:217], v[184:185]
	v_pk_fma_f32 v[14:15], v[116:117], v[218:219], v[186:187]
	v_pk_fma_f32 v[16:17], v[118:119], v[220:221], v[188:189]
	v_pk_fma_f32 v[2:3], v[120:121], v[222:223], v[2:3]
	v_pk_fma_f32 v[4:5], v[122:123], v[224:225], v[4:5]
	v_pk_fma_f32 v[6:7], v[124:125], v[226:227], v[6:7]
	v_pk_fma_f32 v[8:9], v[126:127], v[228:229], v[8:9]
	v_pk_fma_f32 v[10:11], v[128:129], v[230:231], v[10:11]
	v_pk_fma_f32 v[12:13], v[130:131], v[232:233], v[12:13]
	v_pk_fma_f32 v[14:15], v[132:133], v[234:235], v[14:15]
	v_pk_fma_f32 v[16:17], v[134:135], v[236:237], v[16:17]
	v_pk_fma_f32 v[2:3], v[136:137], v[190:191], v[2:3]
	v_pk_fma_f32 v[4:5], v[138:139], v[192:193], v[4:5]
	v_pk_fma_f32 v[6:7], v[140:141], v[194:195], v[6:7]
	v_pk_fma_f32 v[8:9], v[142:143], v[196:197], v[8:9]
	v_pk_fma_f32 v[10:11], v[144:145], v[198:199], v[10:11]
	v_pk_fma_f32 v[12:13], v[146:147], v[200:201], v[12:13]
	v_pk_fma_f32 v[14:15], v[148:149], v[202:203], v[14:15]
	v_pk_fma_f32 v[16:17], v[150:151], v[204:205], v[16:17]
	v_mul_f32_e32 v18, 0xbfb8aa3b, v2
	v_mul_f32_e32 v19, 0xbfb8aa3b, v3
	v_mul_f32_e32 v20, 0xbfb8aa3b, v4
	v_mul_f32_e32 v21, 0xbfb8aa3b, v5
	v_mul_f32_e32 v22, 0xbfb8aa3b, v6
	v_mul_f32_e32 v23, 0xbfb8aa3b, v7
	v_mul_f32_e32 v24, 0xbfb8aa3b, v8
	v_mul_f32_e32 v25, 0xbfb8aa3b, v9
	v_exp_f32_e32 v18, v18
	v_exp_f32_e32 v19, v19
	v_exp_f32_e32 v20, v20
	v_exp_f32_e32 v21, v21
	v_exp_f32_e32 v22, v22
	v_exp_f32_e32 v23, v23
	v_exp_f32_e32 v24, v24
	v_exp_f32_e32 v25, v25
	v_add_f32_e32 v18, 1.0, v18
	v_add_f32_e32 v19, 1.0, v19
	v_add_f32_e32 v20, 1.0, v20
	v_add_f32_e32 v21, 1.0, v21
	v_add_f32_e32 v22, 1.0, v22
	v_add_f32_e32 v23, 1.0, v23
	v_add_f32_e32 v24, 1.0, v24
	v_add_f32_e32 v25, 1.0, v25
	v_rcp_f32_e32 v18, v18
	v_rcp_f32_e32 v19, v19
	v_rcp_f32_e32 v20, v20
	v_rcp_f32_e32 v21, v21
	v_rcp_f32_e32 v22, v22
	v_rcp_f32_e32 v23, v23
	v_rcp_f32_e32 v24, v24
	v_rcp_f32_e32 v25, v25
	v_mul_f32_e32 v18, v2, v18
	v_mul_f32_e32 v19, v3, v19
	v_mul_f32_e32 v20, v4, v20
	v_mul_f32_e32 v21, v5, v21
	v_mul_f32_e32 v22, v6, v22
	v_mul_f32_e32 v23, v7, v23
	v_mul_f32_e32 v24, v8, v24
	v_mul_f32_e32 v25, v9, v25
	v_mul_f32_e32 v18, v10, v18
	v_mul_f32_e32 v19, v11, v19
	v_mul_f32_e32 v20, v12, v20
	v_mul_f32_e32 v21, v13, v21
	v_mul_f32_e32 v22, v14, v22
	v_mul_f32_e32 v23, v15, v23
	v_mul_f32_e32 v24, v16, v24
	v_mul_f32_e32 v25, v17, v25
	v_cvt_pk_bf16_f32 v26, v18, v19
	v_cvt_pk_bf16_f32 v27, v20, v21
	v_cvt_pk_bf16_f32 v28, v22, v23
	v_cvt_pk_bf16_f32 v29, v24, v25
	global_store_dwordx4 v[162:163], v[26:29], off sc1
	v_lshl_add_u64 v[162:163], v[162:163], 0, v[30:31]
	v_lshlrev_b32_e32 v206, 16, v44
	v_and_b32_e32 v207, 0xffff0000, v44
	v_lshlrev_b32_e32 v208, 16, v45
	v_and_b32_e32 v209, 0xffff0000, v45
	v_lshlrev_b32_e32 v210, 16, v46
	v_and_b32_e32 v211, 0xffff0000, v46
	v_lshlrev_b32_e32 v212, 16, v47
	v_and_b32_e32 v213, 0xffff0000, v47
	v_lshlrev_b32_e32 v214, 16, v48
	v_and_b32_e32 v215, 0xffff0000, v48
	v_lshlrev_b32_e32 v216, 16, v49
	v_and_b32_e32 v217, 0xffff0000, v49
	v_lshlrev_b32_e32 v218, 16, v50
	v_and_b32_e32 v219, 0xffff0000, v50
	v_lshlrev_b32_e32 v220, 16, v51
	v_and_b32_e32 v221, 0xffff0000, v51
	v_pk_fma_f32 v[2:3], v[104:105], v[222:223], v[174:175]
	v_pk_fma_f32 v[4:5], v[106:107], v[224:225], v[176:177]
	v_pk_fma_f32 v[6:7], v[108:109], v[226:227], v[178:179]
	v_pk_fma_f32 v[8:9], v[110:111], v[228:229], v[180:181]
	v_pk_fma_f32 v[10:11], v[112:113], v[230:231], v[182:183]
	v_pk_fma_f32 v[12:13], v[114:115], v[232:233], v[184:185]
	v_pk_fma_f32 v[14:15], v[116:117], v[234:235], v[186:187]
	v_pk_fma_f32 v[16:17], v[118:119], v[236:237], v[188:189]
	v_pk_fma_f32 v[2:3], v[120:121], v[190:191], v[2:3]
	v_pk_fma_f32 v[4:5], v[122:123], v[192:193], v[4:5]
	v_pk_fma_f32 v[6:7], v[124:125], v[194:195], v[6:7]
	v_pk_fma_f32 v[8:9], v[126:127], v[196:197], v[8:9]
	v_pk_fma_f32 v[10:11], v[128:129], v[198:199], v[10:11]
	v_pk_fma_f32 v[12:13], v[130:131], v[200:201], v[12:13]
	v_pk_fma_f32 v[14:15], v[132:133], v[202:203], v[14:15]
	v_pk_fma_f32 v[16:17], v[134:135], v[204:205], v[16:17]
	v_pk_fma_f32 v[2:3], v[136:137], v[206:207], v[2:3]
	v_pk_fma_f32 v[4:5], v[138:139], v[208:209], v[4:5]
	v_pk_fma_f32 v[6:7], v[140:141], v[210:211], v[6:7]
	v_pk_fma_f32 v[8:9], v[142:143], v[212:213], v[8:9]
	v_pk_fma_f32 v[10:11], v[144:145], v[214:215], v[10:11]
	v_pk_fma_f32 v[12:13], v[146:147], v[216:217], v[12:13]
	v_pk_fma_f32 v[14:15], v[148:149], v[218:219], v[14:15]
	v_pk_fma_f32 v[16:17], v[150:151], v[220:221], v[16:17]
	v_mul_f32_e32 v18, 0xbfb8aa3b, v2
	v_mul_f32_e32 v19, 0xbfb8aa3b, v3
	v_mul_f32_e32 v20, 0xbfb8aa3b, v4
	v_mul_f32_e32 v21, 0xbfb8aa3b, v5
	v_mul_f32_e32 v22, 0xbfb8aa3b, v6
	v_mul_f32_e32 v23, 0xbfb8aa3b, v7
	v_mul_f32_e32 v24, 0xbfb8aa3b, v8
	v_mul_f32_e32 v25, 0xbfb8aa3b, v9
	v_exp_f32_e32 v18, v18
	v_exp_f32_e32 v19, v19
	v_exp_f32_e32 v20, v20
	v_exp_f32_e32 v21, v21
	v_exp_f32_e32 v22, v22
	v_exp_f32_e32 v23, v23
	v_exp_f32_e32 v24, v24
	v_exp_f32_e32 v25, v25
	v_add_f32_e32 v18, 1.0, v18
	v_add_f32_e32 v19, 1.0, v19
	v_add_f32_e32 v20, 1.0, v20
	v_add_f32_e32 v21, 1.0, v21
	v_add_f32_e32 v22, 1.0, v22
	v_add_f32_e32 v23, 1.0, v23
	v_add_f32_e32 v24, 1.0, v24
	v_add_f32_e32 v25, 1.0, v25
	v_rcp_f32_e32 v18, v18
	v_rcp_f32_e32 v19, v19
	v_rcp_f32_e32 v20, v20
	v_rcp_f32_e32 v21, v21
	v_rcp_f32_e32 v22, v22
	v_rcp_f32_e32 v23, v23
	v_rcp_f32_e32 v24, v24
	v_rcp_f32_e32 v25, v25
	v_mul_f32_e32 v18, v2, v18
	v_mul_f32_e32 v19, v3, v19
	v_mul_f32_e32 v20, v4, v20
	v_mul_f32_e32 v21, v5, v21
	v_mul_f32_e32 v22, v6, v22
	v_mul_f32_e32 v23, v7, v23
	v_mul_f32_e32 v24, v8, v24
	v_mul_f32_e32 v25, v9, v25
	v_mul_f32_e32 v18, v10, v18
	v_mul_f32_e32 v19, v11, v19
	v_mul_f32_e32 v20, v12, v20
	v_mul_f32_e32 v21, v13, v21
	v_mul_f32_e32 v22, v14, v22
	v_mul_f32_e32 v23, v15, v23
	v_mul_f32_e32 v24, v16, v24
	v_mul_f32_e32 v25, v17, v25
	v_cvt_pk_bf16_f32 v26, v18, v19
	v_cvt_pk_bf16_f32 v27, v20, v21
	v_cvt_pk_bf16_f32 v28, v22, v23
	v_cvt_pk_bf16_f32 v29, v24, v25
	global_store_dwordx4 v[162:163], v[26:29], off sc1
	v_lshl_add_u64 v[162:163], v[162:163], 0, v[30:31]
	v_lshlrev_b32_e32 v222, 16, v52
	v_and_b32_e32 v223, 0xffff0000, v52
	v_lshlrev_b32_e32 v224, 16, v53
	v_and_b32_e32 v225, 0xffff0000, v53
	v_lshlrev_b32_e32 v226, 16, v54
	v_and_b32_e32 v227, 0xffff0000, v54
	v_lshlrev_b32_e32 v228, 16, v55
	v_and_b32_e32 v229, 0xffff0000, v55
	v_lshlrev_b32_e32 v230, 16, v56
	v_and_b32_e32 v231, 0xffff0000, v56
	v_lshlrev_b32_e32 v232, 16, v57
	v_and_b32_e32 v233, 0xffff0000, v57
	v_lshlrev_b32_e32 v234, 16, v58
	v_and_b32_e32 v235, 0xffff0000, v58
	v_lshlrev_b32_e32 v236, 16, v59
	v_and_b32_e32 v237, 0xffff0000, v59
	v_pk_fma_f32 v[2:3], v[104:105], v[190:191], v[174:175]
	v_pk_fma_f32 v[4:5], v[106:107], v[192:193], v[176:177]
	v_pk_fma_f32 v[6:7], v[108:109], v[194:195], v[178:179]
	v_pk_fma_f32 v[8:9], v[110:111], v[196:197], v[180:181]
	v_pk_fma_f32 v[10:11], v[112:113], v[198:199], v[182:183]
	v_pk_fma_f32 v[12:13], v[114:115], v[200:201], v[184:185]
	v_pk_fma_f32 v[14:15], v[116:117], v[202:203], v[186:187]
	v_pk_fma_f32 v[16:17], v[118:119], v[204:205], v[188:189]
	v_pk_fma_f32 v[2:3], v[120:121], v[206:207], v[2:3]
	v_pk_fma_f32 v[4:5], v[122:123], v[208:209], v[4:5]
	v_pk_fma_f32 v[6:7], v[124:125], v[210:211], v[6:7]
	v_pk_fma_f32 v[8:9], v[126:127], v[212:213], v[8:9]
	v_pk_fma_f32 v[10:11], v[128:129], v[214:215], v[10:11]
	v_pk_fma_f32 v[12:13], v[130:131], v[216:217], v[12:13]
	v_pk_fma_f32 v[14:15], v[132:133], v[218:219], v[14:15]
	v_pk_fma_f32 v[16:17], v[134:135], v[220:221], v[16:17]
	v_pk_fma_f32 v[2:3], v[136:137], v[222:223], v[2:3]
	v_pk_fma_f32 v[4:5], v[138:139], v[224:225], v[4:5]
	v_pk_fma_f32 v[6:7], v[140:141], v[226:227], v[6:7]
	v_pk_fma_f32 v[8:9], v[142:143], v[228:229], v[8:9]
	v_pk_fma_f32 v[10:11], v[144:145], v[230:231], v[10:11]
	v_pk_fma_f32 v[12:13], v[146:147], v[232:233], v[12:13]
	v_pk_fma_f32 v[14:15], v[148:149], v[234:235], v[14:15]
	v_pk_fma_f32 v[16:17], v[150:151], v[236:237], v[16:17]
	v_mul_f32_e32 v18, 0xbfb8aa3b, v2
	v_mul_f32_e32 v19, 0xbfb8aa3b, v3
	v_mul_f32_e32 v20, 0xbfb8aa3b, v4
	v_mul_f32_e32 v21, 0xbfb8aa3b, v5
	v_mul_f32_e32 v22, 0xbfb8aa3b, v6
	v_mul_f32_e32 v23, 0xbfb8aa3b, v7
	v_mul_f32_e32 v24, 0xbfb8aa3b, v8
	v_mul_f32_e32 v25, 0xbfb8aa3b, v9
	v_exp_f32_e32 v18, v18
	v_exp_f32_e32 v19, v19
	v_exp_f32_e32 v20, v20
	v_exp_f32_e32 v21, v21
	v_exp_f32_e32 v22, v22
	v_exp_f32_e32 v23, v23
	v_exp_f32_e32 v24, v24
	v_exp_f32_e32 v25, v25
	v_add_f32_e32 v18, 1.0, v18
	v_add_f32_e32 v19, 1.0, v19
	v_add_f32_e32 v20, 1.0, v20
	v_add_f32_e32 v21, 1.0, v21
	v_add_f32_e32 v22, 1.0, v22
	v_add_f32_e32 v23, 1.0, v23
	v_add_f32_e32 v24, 1.0, v24
	v_add_f32_e32 v25, 1.0, v25
	v_rcp_f32_e32 v18, v18
	v_rcp_f32_e32 v19, v19
	v_rcp_f32_e32 v20, v20
	v_rcp_f32_e32 v21, v21
	v_rcp_f32_e32 v22, v22
	v_rcp_f32_e32 v23, v23
	v_rcp_f32_e32 v24, v24
	v_rcp_f32_e32 v25, v25
	v_mul_f32_e32 v18, v2, v18
	v_mul_f32_e32 v19, v3, v19
	v_mul_f32_e32 v20, v4, v20
	v_mul_f32_e32 v21, v5, v21
	v_mul_f32_e32 v22, v6, v22
	v_mul_f32_e32 v23, v7, v23
	v_mul_f32_e32 v24, v8, v24
	v_mul_f32_e32 v25, v9, v25
	v_mul_f32_e32 v18, v10, v18
	v_mul_f32_e32 v19, v11, v19
	v_mul_f32_e32 v20, v12, v20
	v_mul_f32_e32 v21, v13, v21
	v_mul_f32_e32 v22, v14, v22
	v_mul_f32_e32 v23, v15, v23
	v_mul_f32_e32 v24, v16, v24
	v_mul_f32_e32 v25, v17, v25
	v_cvt_pk_bf16_f32 v26, v18, v19
	v_cvt_pk_bf16_f32 v27, v20, v21
	v_cvt_pk_bf16_f32 v28, v22, v23
	v_cvt_pk_bf16_f32 v29, v24, v25
	global_store_dwordx4 v[162:163], v[26:29], off sc1
	v_lshl_add_u64 v[162:163], v[162:163], 0, v[30:31]
	v_lshlrev_b32_e32 v190, 16, v60
	v_and_b32_e32 v191, 0xffff0000, v60
	v_lshlrev_b32_e32 v192, 16, v61
	v_and_b32_e32 v193, 0xffff0000, v61
	v_lshlrev_b32_e32 v194, 16, v62
	v_and_b32_e32 v195, 0xffff0000, v62
	v_lshlrev_b32_e32 v196, 16, v63
	v_and_b32_e32 v197, 0xffff0000, v63
	v_lshlrev_b32_e32 v198, 16, v64
	v_and_b32_e32 v199, 0xffff0000, v64
	v_lshlrev_b32_e32 v200, 16, v65
	v_and_b32_e32 v201, 0xffff0000, v65
	v_lshlrev_b32_e32 v202, 16, v66
	v_and_b32_e32 v203, 0xffff0000, v66
	v_lshlrev_b32_e32 v204, 16, v67
	v_and_b32_e32 v205, 0xffff0000, v67
	v_pk_fma_f32 v[2:3], v[104:105], v[206:207], v[174:175]
	v_pk_fma_f32 v[4:5], v[106:107], v[208:209], v[176:177]
	v_pk_fma_f32 v[6:7], v[108:109], v[210:211], v[178:179]
	v_pk_fma_f32 v[8:9], v[110:111], v[212:213], v[180:181]
	v_pk_fma_f32 v[10:11], v[112:113], v[214:215], v[182:183]
	v_pk_fma_f32 v[12:13], v[114:115], v[216:217], v[184:185]
	v_pk_fma_f32 v[14:15], v[116:117], v[218:219], v[186:187]
	v_pk_fma_f32 v[16:17], v[118:119], v[220:221], v[188:189]
	v_pk_fma_f32 v[2:3], v[120:121], v[222:223], v[2:3]
	v_pk_fma_f32 v[4:5], v[122:123], v[224:225], v[4:5]
	v_pk_fma_f32 v[6:7], v[124:125], v[226:227], v[6:7]
	v_pk_fma_f32 v[8:9], v[126:127], v[228:229], v[8:9]
	v_pk_fma_f32 v[10:11], v[128:129], v[230:231], v[10:11]
	v_pk_fma_f32 v[12:13], v[130:131], v[232:233], v[12:13]
	v_pk_fma_f32 v[14:15], v[132:133], v[234:235], v[14:15]
	v_pk_fma_f32 v[16:17], v[134:135], v[236:237], v[16:17]
	v_pk_fma_f32 v[2:3], v[136:137], v[190:191], v[2:3]
	v_pk_fma_f32 v[4:5], v[138:139], v[192:193], v[4:5]
	v_pk_fma_f32 v[6:7], v[140:141], v[194:195], v[6:7]
	v_pk_fma_f32 v[8:9], v[142:143], v[196:197], v[8:9]
	v_pk_fma_f32 v[10:11], v[144:145], v[198:199], v[10:11]
	v_pk_fma_f32 v[12:13], v[146:147], v[200:201], v[12:13]
	v_pk_fma_f32 v[14:15], v[148:149], v[202:203], v[14:15]
	v_pk_fma_f32 v[16:17], v[150:151], v[204:205], v[16:17]
	v_mul_f32_e32 v18, 0xbfb8aa3b, v2
	v_mul_f32_e32 v19, 0xbfb8aa3b, v3
	v_mul_f32_e32 v20, 0xbfb8aa3b, v4
	v_mul_f32_e32 v21, 0xbfb8aa3b, v5
	v_mul_f32_e32 v22, 0xbfb8aa3b, v6
	v_mul_f32_e32 v23, 0xbfb8aa3b, v7
	v_mul_f32_e32 v24, 0xbfb8aa3b, v8
	v_mul_f32_e32 v25, 0xbfb8aa3b, v9
	v_exp_f32_e32 v18, v18
	v_exp_f32_e32 v19, v19
	v_exp_f32_e32 v20, v20
	v_exp_f32_e32 v21, v21
	v_exp_f32_e32 v22, v22
	v_exp_f32_e32 v23, v23
	v_exp_f32_e32 v24, v24
	v_exp_f32_e32 v25, v25
	v_add_f32_e32 v18, 1.0, v18
	v_add_f32_e32 v19, 1.0, v19
	v_add_f32_e32 v20, 1.0, v20
	v_add_f32_e32 v21, 1.0, v21
	v_add_f32_e32 v22, 1.0, v22
	v_add_f32_e32 v23, 1.0, v23
	v_add_f32_e32 v24, 1.0, v24
	v_add_f32_e32 v25, 1.0, v25
	v_rcp_f32_e32 v18, v18
	v_rcp_f32_e32 v19, v19
	v_rcp_f32_e32 v20, v20
	v_rcp_f32_e32 v21, v21
	v_rcp_f32_e32 v22, v22
	v_rcp_f32_e32 v23, v23
	v_rcp_f32_e32 v24, v24
	v_rcp_f32_e32 v25, v25
	v_mul_f32_e32 v18, v2, v18
	v_mul_f32_e32 v19, v3, v19
	v_mul_f32_e32 v20, v4, v20
	v_mul_f32_e32 v21, v5, v21
	v_mul_f32_e32 v22, v6, v22
	v_mul_f32_e32 v23, v7, v23
	v_mul_f32_e32 v24, v8, v24
	v_mul_f32_e32 v25, v9, v25
	v_mul_f32_e32 v18, v10, v18
	v_mul_f32_e32 v19, v11, v19
	v_mul_f32_e32 v20, v12, v20
	v_mul_f32_e32 v21, v13, v21
	v_mul_f32_e32 v22, v14, v22
	v_mul_f32_e32 v23, v15, v23
	v_mul_f32_e32 v24, v16, v24
	v_mul_f32_e32 v25, v17, v25
	v_cvt_pk_bf16_f32 v26, v18, v19
	v_cvt_pk_bf16_f32 v27, v20, v21
	v_cvt_pk_bf16_f32 v28, v22, v23
	v_cvt_pk_bf16_f32 v29, v24, v25
	global_store_dwordx4 v[162:163], v[26:29], off sc1
	v_lshl_add_u64 v[162:163], v[162:163], 0, v[30:31]
	global_load_dwordx4 v[36:39], v[158:159], off
	global_load_dwordx4 v[40:43], v[160:161], off
	v_lshl_add_u64 v[158:159], v[158:159], 0, v[164:165]
	v_lshl_add_u64 v[160:161], v[160:161], 0, v[164:165]
	global_load_dwordx4 v[44:47], v[158:159], off
	global_load_dwordx4 v[48:51], v[160:161], off
	v_lshl_add_u64 v[158:159], v[158:159], 0, v[164:165]
	v_lshl_add_u64 v[160:161], v[160:161], 0, v[164:165]
	global_load_dwordx4 v[52:55], v[158:159], off
	global_load_dwordx4 v[56:59], v[160:161], off
	v_lshl_add_u64 v[158:159], v[158:159], 0, v[164:165]
	v_lshl_add_u64 v[160:161], v[160:161], 0, v[164:165]
	global_load_dwordx4 v[60:63], v[158:159], off
	global_load_dwordx4 v[64:67], v[160:161], off
	v_lshl_add_u64 v[158:159], v[158:159], 0, v[164:165]
	v_lshl_add_u64 v[160:161], v[160:161], 0, v[164:165]
	s_waitcnt vmcnt(12)
	v_lshlrev_b32_e32 v206, 16, v68
	v_and_b32_e32 v207, 0xffff0000, v68
	v_lshlrev_b32_e32 v208, 16, v69
	v_and_b32_e32 v209, 0xffff0000, v69
	v_lshlrev_b32_e32 v210, 16, v70
	v_and_b32_e32 v211, 0xffff0000, v70
	v_lshlrev_b32_e32 v212, 16, v71
	v_and_b32_e32 v213, 0xffff0000, v71
	v_lshlrev_b32_e32 v214, 16, v72
	v_and_b32_e32 v215, 0xffff0000, v72
	v_lshlrev_b32_e32 v216, 16, v73
	v_and_b32_e32 v217, 0xffff0000, v73
	v_lshlrev_b32_e32 v218, 16, v74
	v_and_b32_e32 v219, 0xffff0000, v74
	v_lshlrev_b32_e32 v220, 16, v75
	v_and_b32_e32 v221, 0xffff0000, v75
	v_pk_fma_f32 v[2:3], v[104:105], v[222:223], v[174:175]
	v_pk_fma_f32 v[4:5], v[106:107], v[224:225], v[176:177]
	v_pk_fma_f32 v[6:7], v[108:109], v[226:227], v[178:179]
	v_pk_fma_f32 v[8:9], v[110:111], v[228:229], v[180:181]
	v_pk_fma_f32 v[10:11], v[112:113], v[230:231], v[182:183]
	v_pk_fma_f32 v[12:13], v[114:115], v[232:233], v[184:185]
	v_pk_fma_f32 v[14:15], v[116:117], v[234:235], v[186:187]
	v_pk_fma_f32 v[16:17], v[118:119], v[236:237], v[188:189]
	v_pk_fma_f32 v[2:3], v[120:121], v[190:191], v[2:3]
	v_pk_fma_f32 v[4:5], v[122:123], v[192:193], v[4:5]
	v_pk_fma_f32 v[6:7], v[124:125], v[194:195], v[6:7]
	v_pk_fma_f32 v[8:9], v[126:127], v[196:197], v[8:9]
	v_pk_fma_f32 v[10:11], v[128:129], v[198:199], v[10:11]
	v_pk_fma_f32 v[12:13], v[130:131], v[200:201], v[12:13]
	v_pk_fma_f32 v[14:15], v[132:133], v[202:203], v[14:15]
	v_pk_fma_f32 v[16:17], v[134:135], v[204:205], v[16:17]
	v_pk_fma_f32 v[2:3], v[136:137], v[206:207], v[2:3]
	v_pk_fma_f32 v[4:5], v[138:139], v[208:209], v[4:5]
	v_pk_fma_f32 v[6:7], v[140:141], v[210:211], v[6:7]
	v_pk_fma_f32 v[8:9], v[142:143], v[212:213], v[8:9]
	v_pk_fma_f32 v[10:11], v[144:145], v[214:215], v[10:11]
	v_pk_fma_f32 v[12:13], v[146:147], v[216:217], v[12:13]
	v_pk_fma_f32 v[14:15], v[148:149], v[218:219], v[14:15]
	v_pk_fma_f32 v[16:17], v[150:151], v[220:221], v[16:17]
	v_mul_f32_e32 v18, 0xbfb8aa3b, v2
	v_mul_f32_e32 v19, 0xbfb8aa3b, v3
	v_mul_f32_e32 v20, 0xbfb8aa3b, v4
	v_mul_f32_e32 v21, 0xbfb8aa3b, v5
	v_mul_f32_e32 v22, 0xbfb8aa3b, v6
	v_mul_f32_e32 v23, 0xbfb8aa3b, v7
	v_mul_f32_e32 v24, 0xbfb8aa3b, v8
	v_mul_f32_e32 v25, 0xbfb8aa3b, v9
	v_exp_f32_e32 v18, v18
	v_exp_f32_e32 v19, v19
	v_exp_f32_e32 v20, v20
	v_exp_f32_e32 v21, v21
	v_exp_f32_e32 v22, v22
	v_exp_f32_e32 v23, v23
	v_exp_f32_e32 v24, v24
	v_exp_f32_e32 v25, v25
	v_add_f32_e32 v18, 1.0, v18
	v_add_f32_e32 v19, 1.0, v19
	v_add_f32_e32 v20, 1.0, v20
	v_add_f32_e32 v21, 1.0, v21
	v_add_f32_e32 v22, 1.0, v22
	v_add_f32_e32 v23, 1.0, v23
	v_add_f32_e32 v24, 1.0, v24
	v_add_f32_e32 v25, 1.0, v25
	v_rcp_f32_e32 v18, v18
	v_rcp_f32_e32 v19, v19
	v_rcp_f32_e32 v20, v20
	v_rcp_f32_e32 v21, v21
	v_rcp_f32_e32 v22, v22
	v_rcp_f32_e32 v23, v23
	v_rcp_f32_e32 v24, v24
	v_rcp_f32_e32 v25, v25
	v_mul_f32_e32 v18, v2, v18
	v_mul_f32_e32 v19, v3, v19
	v_mul_f32_e32 v20, v4, v20
	v_mul_f32_e32 v21, v5, v21
	v_mul_f32_e32 v22, v6, v22
	v_mul_f32_e32 v23, v7, v23
	v_mul_f32_e32 v24, v8, v24
	v_mul_f32_e32 v25, v9, v25
	v_mul_f32_e32 v18, v10, v18
	v_mul_f32_e32 v19, v11, v19
	v_mul_f32_e32 v20, v12, v20
	v_mul_f32_e32 v21, v13, v21
	v_mul_f32_e32 v22, v14, v22
	v_mul_f32_e32 v23, v15, v23
	v_mul_f32_e32 v24, v16, v24
	v_mul_f32_e32 v25, v17, v25
	v_cvt_pk_bf16_f32 v26, v18, v19
	v_cvt_pk_bf16_f32 v27, v20, v21
	v_cvt_pk_bf16_f32 v28, v22, v23
	v_cvt_pk_bf16_f32 v29, v24, v25
	global_store_dwordx4 v[162:163], v[26:29], off sc1
	v_lshl_add_u64 v[162:163], v[162:163], 0, v[30:31]
	v_lshlrev_b32_e32 v222, 16, v76
	v_and_b32_e32 v223, 0xffff0000, v76
	v_lshlrev_b32_e32 v224, 16, v77
	v_and_b32_e32 v225, 0xffff0000, v77
	v_lshlrev_b32_e32 v226, 16, v78
	v_and_b32_e32 v227, 0xffff0000, v78
	v_lshlrev_b32_e32 v228, 16, v79
	v_and_b32_e32 v229, 0xffff0000, v79
	v_lshlrev_b32_e32 v230, 16, v80
	v_and_b32_e32 v231, 0xffff0000, v80
	v_lshlrev_b32_e32 v232, 16, v81
	v_and_b32_e32 v233, 0xffff0000, v81
	v_lshlrev_b32_e32 v234, 16, v82
	v_and_b32_e32 v235, 0xffff0000, v82
	v_lshlrev_b32_e32 v236, 16, v83
	v_and_b32_e32 v237, 0xffff0000, v83
	v_pk_fma_f32 v[2:3], v[104:105], v[190:191], v[174:175]
	v_pk_fma_f32 v[4:5], v[106:107], v[192:193], v[176:177]
	v_pk_fma_f32 v[6:7], v[108:109], v[194:195], v[178:179]
	v_pk_fma_f32 v[8:9], v[110:111], v[196:197], v[180:181]
	v_pk_fma_f32 v[10:11], v[112:113], v[198:199], v[182:183]
	v_pk_fma_f32 v[12:13], v[114:115], v[200:201], v[184:185]
	v_pk_fma_f32 v[14:15], v[116:117], v[202:203], v[186:187]
	v_pk_fma_f32 v[16:17], v[118:119], v[204:205], v[188:189]
	v_pk_fma_f32 v[2:3], v[120:121], v[206:207], v[2:3]
	v_pk_fma_f32 v[4:5], v[122:123], v[208:209], v[4:5]
	v_pk_fma_f32 v[6:7], v[124:125], v[210:211], v[6:7]
	v_pk_fma_f32 v[8:9], v[126:127], v[212:213], v[8:9]
	v_pk_fma_f32 v[10:11], v[128:129], v[214:215], v[10:11]
	v_pk_fma_f32 v[12:13], v[130:131], v[216:217], v[12:13]
	v_pk_fma_f32 v[14:15], v[132:133], v[218:219], v[14:15]
	v_pk_fma_f32 v[16:17], v[134:135], v[220:221], v[16:17]
	v_pk_fma_f32 v[2:3], v[136:137], v[222:223], v[2:3]
	v_pk_fma_f32 v[4:5], v[138:139], v[224:225], v[4:5]
	v_pk_fma_f32 v[6:7], v[140:141], v[226:227], v[6:7]
	v_pk_fma_f32 v[8:9], v[142:143], v[228:229], v[8:9]
	v_pk_fma_f32 v[10:11], v[144:145], v[230:231], v[10:11]
	v_pk_fma_f32 v[12:13], v[146:147], v[232:233], v[12:13]
	v_pk_fma_f32 v[14:15], v[148:149], v[234:235], v[14:15]
	v_pk_fma_f32 v[16:17], v[150:151], v[236:237], v[16:17]
	v_mul_f32_e32 v18, 0xbfb8aa3b, v2
	v_mul_f32_e32 v19, 0xbfb8aa3b, v3
	v_mul_f32_e32 v20, 0xbfb8aa3b, v4
	v_mul_f32_e32 v21, 0xbfb8aa3b, v5
	v_mul_f32_e32 v22, 0xbfb8aa3b, v6
	v_mul_f32_e32 v23, 0xbfb8aa3b, v7
	v_mul_f32_e32 v24, 0xbfb8aa3b, v8
	v_mul_f32_e32 v25, 0xbfb8aa3b, v9
	v_exp_f32_e32 v18, v18
	v_exp_f32_e32 v19, v19
	v_exp_f32_e32 v20, v20
	v_exp_f32_e32 v21, v21
	v_exp_f32_e32 v22, v22
	v_exp_f32_e32 v23, v23
	v_exp_f32_e32 v24, v24
	v_exp_f32_e32 v25, v25
	v_add_f32_e32 v18, 1.0, v18
	v_add_f32_e32 v19, 1.0, v19
	v_add_f32_e32 v20, 1.0, v20
	v_add_f32_e32 v21, 1.0, v21
	v_add_f32_e32 v22, 1.0, v22
	v_add_f32_e32 v23, 1.0, v23
	v_add_f32_e32 v24, 1.0, v24
	v_add_f32_e32 v25, 1.0, v25
	v_rcp_f32_e32 v18, v18
	v_rcp_f32_e32 v19, v19
	v_rcp_f32_e32 v20, v20
	v_rcp_f32_e32 v21, v21
	v_rcp_f32_e32 v22, v22
	v_rcp_f32_e32 v23, v23
	v_rcp_f32_e32 v24, v24
	v_rcp_f32_e32 v25, v25
	v_mul_f32_e32 v18, v2, v18
	v_mul_f32_e32 v19, v3, v19
	v_mul_f32_e32 v20, v4, v20
	v_mul_f32_e32 v21, v5, v21
	v_mul_f32_e32 v22, v6, v22
	v_mul_f32_e32 v23, v7, v23
	v_mul_f32_e32 v24, v8, v24
	v_mul_f32_e32 v25, v9, v25
	v_mul_f32_e32 v18, v10, v18
	v_mul_f32_e32 v19, v11, v19
	v_mul_f32_e32 v20, v12, v20
	v_mul_f32_e32 v21, v13, v21
	v_mul_f32_e32 v22, v14, v22
	v_mul_f32_e32 v23, v15, v23
	v_mul_f32_e32 v24, v16, v24
	v_mul_f32_e32 v25, v17, v25
	v_cvt_pk_bf16_f32 v26, v18, v19
	v_cvt_pk_bf16_f32 v27, v20, v21
	v_cvt_pk_bf16_f32 v28, v22, v23
	v_cvt_pk_bf16_f32 v29, v24, v25
	global_store_dwordx4 v[162:163], v[26:29], off sc1
	v_lshl_add_u64 v[162:163], v[162:163], 0, v[30:31]
	v_lshlrev_b32_e32 v190, 16, v88
	v_and_b32_e32 v191, 0xffff0000, v88
	v_lshlrev_b32_e32 v192, 16, v89
	v_and_b32_e32 v193, 0xffff0000, v89
	v_lshlrev_b32_e32 v194, 16, v90
	v_and_b32_e32 v195, 0xffff0000, v90
	v_lshlrev_b32_e32 v196, 16, v91
	v_and_b32_e32 v197, 0xffff0000, v91
	v_lshlrev_b32_e32 v198, 16, v92
	v_and_b32_e32 v199, 0xffff0000, v92
	v_lshlrev_b32_e32 v200, 16, v93
	v_and_b32_e32 v201, 0xffff0000, v93
	v_lshlrev_b32_e32 v202, 16, v94
	v_and_b32_e32 v203, 0xffff0000, v94
	v_lshlrev_b32_e32 v204, 16, v95
	v_and_b32_e32 v205, 0xffff0000, v95
	v_pk_fma_f32 v[2:3], v[104:105], v[206:207], v[174:175]
	v_pk_fma_f32 v[4:5], v[106:107], v[208:209], v[176:177]
	v_pk_fma_f32 v[6:7], v[108:109], v[210:211], v[178:179]
	v_pk_fma_f32 v[8:9], v[110:111], v[212:213], v[180:181]
	v_pk_fma_f32 v[10:11], v[112:113], v[214:215], v[182:183]
	v_pk_fma_f32 v[12:13], v[114:115], v[216:217], v[184:185]
	v_pk_fma_f32 v[14:15], v[116:117], v[218:219], v[186:187]
	v_pk_fma_f32 v[16:17], v[118:119], v[220:221], v[188:189]
	v_pk_fma_f32 v[2:3], v[120:121], v[222:223], v[2:3]
	v_pk_fma_f32 v[4:5], v[122:123], v[224:225], v[4:5]
	v_pk_fma_f32 v[6:7], v[124:125], v[226:227], v[6:7]
	v_pk_fma_f32 v[8:9], v[126:127], v[228:229], v[8:9]
	v_pk_fma_f32 v[10:11], v[128:129], v[230:231], v[10:11]
	v_pk_fma_f32 v[12:13], v[130:131], v[232:233], v[12:13]
	v_pk_fma_f32 v[14:15], v[132:133], v[234:235], v[14:15]
	v_pk_fma_f32 v[16:17], v[134:135], v[236:237], v[16:17]
	v_pk_fma_f32 v[2:3], v[136:137], v[190:191], v[2:3]
	v_pk_fma_f32 v[4:5], v[138:139], v[192:193], v[4:5]
	v_pk_fma_f32 v[6:7], v[140:141], v[194:195], v[6:7]
	v_pk_fma_f32 v[8:9], v[142:143], v[196:197], v[8:9]
	v_pk_fma_f32 v[10:11], v[144:145], v[198:199], v[10:11]
	v_pk_fma_f32 v[12:13], v[146:147], v[200:201], v[12:13]
	v_pk_fma_f32 v[14:15], v[148:149], v[202:203], v[14:15]
	v_pk_fma_f32 v[16:17], v[150:151], v[204:205], v[16:17]
	v_mul_f32_e32 v18, 0xbfb8aa3b, v2
	v_mul_f32_e32 v19, 0xbfb8aa3b, v3
	v_mul_f32_e32 v20, 0xbfb8aa3b, v4
	v_mul_f32_e32 v21, 0xbfb8aa3b, v5
	v_mul_f32_e32 v22, 0xbfb8aa3b, v6
	v_mul_f32_e32 v23, 0xbfb8aa3b, v7
	v_mul_f32_e32 v24, 0xbfb8aa3b, v8
	v_mul_f32_e32 v25, 0xbfb8aa3b, v9
	v_exp_f32_e32 v18, v18
	v_exp_f32_e32 v19, v19
	v_exp_f32_e32 v20, v20
	v_exp_f32_e32 v21, v21
	v_exp_f32_e32 v22, v22
	v_exp_f32_e32 v23, v23
	v_exp_f32_e32 v24, v24
	v_exp_f32_e32 v25, v25
	v_add_f32_e32 v18, 1.0, v18
	v_add_f32_e32 v19, 1.0, v19
	v_add_f32_e32 v20, 1.0, v20
	v_add_f32_e32 v21, 1.0, v21
	v_add_f32_e32 v22, 1.0, v22
	v_add_f32_e32 v23, 1.0, v23
	v_add_f32_e32 v24, 1.0, v24
	v_add_f32_e32 v25, 1.0, v25
	v_rcp_f32_e32 v18, v18
	v_rcp_f32_e32 v19, v19
	v_rcp_f32_e32 v20, v20
	v_rcp_f32_e32 v21, v21
	v_rcp_f32_e32 v22, v22
	v_rcp_f32_e32 v23, v23
	v_rcp_f32_e32 v24, v24
	v_rcp_f32_e32 v25, v25
	v_mul_f32_e32 v18, v2, v18
	v_mul_f32_e32 v19, v3, v19
	v_mul_f32_e32 v20, v4, v20
	v_mul_f32_e32 v21, v5, v21
	v_mul_f32_e32 v22, v6, v22
	v_mul_f32_e32 v23, v7, v23
	v_mul_f32_e32 v24, v8, v24
	v_mul_f32_e32 v25, v9, v25
	v_mul_f32_e32 v18, v10, v18
	v_mul_f32_e32 v19, v11, v19
	v_mul_f32_e32 v20, v12, v20
	v_mul_f32_e32 v21, v13, v21
	v_mul_f32_e32 v22, v14, v22
	v_mul_f32_e32 v23, v15, v23
	v_mul_f32_e32 v24, v16, v24
	v_mul_f32_e32 v25, v17, v25
	v_cvt_pk_bf16_f32 v26, v18, v19
	v_cvt_pk_bf16_f32 v27, v20, v21
	v_cvt_pk_bf16_f32 v28, v22, v23
	v_cvt_pk_bf16_f32 v29, v24, v25
	global_store_dwordx4 v[162:163], v[26:29], off sc1
	v_lshl_add_u64 v[162:163], v[162:163], 0, v[30:31]
	v_lshlrev_b32_e32 v206, 16, v96
	v_and_b32_e32 v207, 0xffff0000, v96
	v_lshlrev_b32_e32 v208, 16, v97
	v_and_b32_e32 v209, 0xffff0000, v97
	v_lshlrev_b32_e32 v210, 16, v98
	v_and_b32_e32 v211, 0xffff0000, v98
	v_lshlrev_b32_e32 v212, 16, v99
	v_and_b32_e32 v213, 0xffff0000, v99
	v_lshlrev_b32_e32 v214, 16, v100
	v_and_b32_e32 v215, 0xffff0000, v100
	v_lshlrev_b32_e32 v216, 16, v101
	v_and_b32_e32 v217, 0xffff0000, v101
	v_lshlrev_b32_e32 v218, 16, v102
	v_and_b32_e32 v219, 0xffff0000, v102
	v_lshlrev_b32_e32 v220, 16, v103
	v_and_b32_e32 v221, 0xffff0000, v103
	v_pk_fma_f32 v[2:3], v[104:105], v[222:223], v[174:175]
	v_pk_fma_f32 v[4:5], v[106:107], v[224:225], v[176:177]
	v_pk_fma_f32 v[6:7], v[108:109], v[226:227], v[178:179]
	v_pk_fma_f32 v[8:9], v[110:111], v[228:229], v[180:181]
	v_pk_fma_f32 v[10:11], v[112:113], v[230:231], v[182:183]
	v_pk_fma_f32 v[12:13], v[114:115], v[232:233], v[184:185]
	v_pk_fma_f32 v[14:15], v[116:117], v[234:235], v[186:187]
	v_pk_fma_f32 v[16:17], v[118:119], v[236:237], v[188:189]
	v_pk_fma_f32 v[2:3], v[120:121], v[190:191], v[2:3]
	v_pk_fma_f32 v[4:5], v[122:123], v[192:193], v[4:5]
	v_pk_fma_f32 v[6:7], v[124:125], v[194:195], v[6:7]
	v_pk_fma_f32 v[8:9], v[126:127], v[196:197], v[8:9]
	v_pk_fma_f32 v[10:11], v[128:129], v[198:199], v[10:11]
	v_pk_fma_f32 v[12:13], v[130:131], v[200:201], v[12:13]
	v_pk_fma_f32 v[14:15], v[132:133], v[202:203], v[14:15]
	v_pk_fma_f32 v[16:17], v[134:135], v[204:205], v[16:17]
	v_pk_fma_f32 v[2:3], v[136:137], v[206:207], v[2:3]
	v_pk_fma_f32 v[4:5], v[138:139], v[208:209], v[4:5]
	v_pk_fma_f32 v[6:7], v[140:141], v[210:211], v[6:7]
	v_pk_fma_f32 v[8:9], v[142:143], v[212:213], v[8:9]
	v_pk_fma_f32 v[10:11], v[144:145], v[214:215], v[10:11]
	v_pk_fma_f32 v[12:13], v[146:147], v[216:217], v[12:13]
	v_pk_fma_f32 v[14:15], v[148:149], v[218:219], v[14:15]
	v_pk_fma_f32 v[16:17], v[150:151], v[220:221], v[16:17]
	v_mul_f32_e32 v18, 0xbfb8aa3b, v2
	v_mul_f32_e32 v19, 0xbfb8aa3b, v3
	v_mul_f32_e32 v20, 0xbfb8aa3b, v4
	v_mul_f32_e32 v21, 0xbfb8aa3b, v5
	v_mul_f32_e32 v22, 0xbfb8aa3b, v6
	v_mul_f32_e32 v23, 0xbfb8aa3b, v7
	v_mul_f32_e32 v24, 0xbfb8aa3b, v8
	v_mul_f32_e32 v25, 0xbfb8aa3b, v9
	v_exp_f32_e32 v18, v18
	v_exp_f32_e32 v19, v19
	v_exp_f32_e32 v20, v20
	v_exp_f32_e32 v21, v21
	v_exp_f32_e32 v22, v22
	v_exp_f32_e32 v23, v23
	v_exp_f32_e32 v24, v24
	v_exp_f32_e32 v25, v25
	v_add_f32_e32 v18, 1.0, v18
	v_add_f32_e32 v19, 1.0, v19
	v_add_f32_e32 v20, 1.0, v20
	v_add_f32_e32 v21, 1.0, v21
	v_add_f32_e32 v22, 1.0, v22
	v_add_f32_e32 v23, 1.0, v23
	v_add_f32_e32 v24, 1.0, v24
	v_add_f32_e32 v25, 1.0, v25
	v_rcp_f32_e32 v18, v18
	v_rcp_f32_e32 v19, v19
	v_rcp_f32_e32 v20, v20
	v_rcp_f32_e32 v21, v21
	v_rcp_f32_e32 v22, v22
	v_rcp_f32_e32 v23, v23
	v_rcp_f32_e32 v24, v24
	v_rcp_f32_e32 v25, v25
	v_mul_f32_e32 v18, v2, v18
	v_mul_f32_e32 v19, v3, v19
	v_mul_f32_e32 v20, v4, v20
	v_mul_f32_e32 v21, v5, v21
	v_mul_f32_e32 v22, v6, v22
	v_mul_f32_e32 v23, v7, v23
	v_mul_f32_e32 v24, v8, v24
	v_mul_f32_e32 v25, v9, v25
	v_mul_f32_e32 v18, v10, v18
	v_mul_f32_e32 v19, v11, v19
	v_mul_f32_e32 v20, v12, v20
	v_mul_f32_e32 v21, v13, v21
	v_mul_f32_e32 v22, v14, v22
	v_mul_f32_e32 v23, v15, v23
	v_mul_f32_e32 v24, v16, v24
	v_mul_f32_e32 v25, v17, v25
	v_cvt_pk_bf16_f32 v26, v18, v19
	v_cvt_pk_bf16_f32 v27, v20, v21
	v_cvt_pk_bf16_f32 v28, v22, v23
	v_cvt_pk_bf16_f32 v29, v24, v25
	global_store_dwordx4 v[162:163], v[26:29], off sc1
	v_lshl_add_u64 v[162:163], v[162:163], 0, v[30:31]
	global_load_dwordx4 v[68:71], v[158:159], off
	global_load_dwordx4 v[72:75], v[160:161], off
	v_lshl_add_u64 v[158:159], v[158:159], 0, v[164:165]
	v_lshl_add_u64 v[160:161], v[160:161], 0, v[164:165]
	global_load_dwordx4 v[76:79], v[158:159], off
	global_load_dwordx4 v[80:83], v[160:161], off
	v_lshl_add_u64 v[158:159], v[158:159], 0, v[164:165]
	v_lshl_add_u64 v[160:161], v[160:161], 0, v[164:165]
	global_load_dwordx4 v[88:91], v[158:159], off
	global_load_dwordx4 v[92:95], v[160:161], off
	v_lshl_add_u64 v[158:159], v[158:159], 0, v[164:165]
	v_lshl_add_u64 v[160:161], v[160:161], 0, v[164:165]
	global_load_dwordx4 v[96:99], v[158:159], off
	global_load_dwordx4 v[100:103], v[160:161], off
	v_lshl_add_u64 v[158:159], v[158:159], 0, v[164:165]
	v_lshl_add_u64 v[160:161], v[160:161], 0, v[164:165]
	s_waitcnt vmcnt(12)
	v_lshlrev_b32_e32 v222, 16, v36
	v_and_b32_e32 v223, 0xffff0000, v36
	v_lshlrev_b32_e32 v224, 16, v37
	v_and_b32_e32 v225, 0xffff0000, v37
	v_lshlrev_b32_e32 v226, 16, v38
	v_and_b32_e32 v227, 0xffff0000, v38
	v_lshlrev_b32_e32 v228, 16, v39
	v_and_b32_e32 v229, 0xffff0000, v39
	v_lshlrev_b32_e32 v230, 16, v40
	v_and_b32_e32 v231, 0xffff0000, v40
	v_lshlrev_b32_e32 v232, 16, v41
	v_and_b32_e32 v233, 0xffff0000, v41
	v_lshlrev_b32_e32 v234, 16, v42
	v_and_b32_e32 v235, 0xffff0000, v42
	v_lshlrev_b32_e32 v236, 16, v43
	v_and_b32_e32 v237, 0xffff0000, v43
	v_pk_fma_f32 v[2:3], v[104:105], v[190:191], v[174:175]
	v_pk_fma_f32 v[4:5], v[106:107], v[192:193], v[176:177]
	v_pk_fma_f32 v[6:7], v[108:109], v[194:195], v[178:179]
	v_pk_fma_f32 v[8:9], v[110:111], v[196:197], v[180:181]
	v_pk_fma_f32 v[10:11], v[112:113], v[198:199], v[182:183]
	v_pk_fma_f32 v[12:13], v[114:115], v[200:201], v[184:185]
	v_pk_fma_f32 v[14:15], v[116:117], v[202:203], v[186:187]
	v_pk_fma_f32 v[16:17], v[118:119], v[204:205], v[188:189]
	v_pk_fma_f32 v[2:3], v[120:121], v[206:207], v[2:3]
	v_pk_fma_f32 v[4:5], v[122:123], v[208:209], v[4:5]
	v_pk_fma_f32 v[6:7], v[124:125], v[210:211], v[6:7]
	v_pk_fma_f32 v[8:9], v[126:127], v[212:213], v[8:9]
	v_pk_fma_f32 v[10:11], v[128:129], v[214:215], v[10:11]
	v_pk_fma_f32 v[12:13], v[130:131], v[216:217], v[12:13]
	v_pk_fma_f32 v[14:15], v[132:133], v[218:219], v[14:15]
	v_pk_fma_f32 v[16:17], v[134:135], v[220:221], v[16:17]
	v_pk_fma_f32 v[2:3], v[136:137], v[222:223], v[2:3]
	v_pk_fma_f32 v[4:5], v[138:139], v[224:225], v[4:5]
	v_pk_fma_f32 v[6:7], v[140:141], v[226:227], v[6:7]
	v_pk_fma_f32 v[8:9], v[142:143], v[228:229], v[8:9]
	v_pk_fma_f32 v[10:11], v[144:145], v[230:231], v[10:11]
	v_pk_fma_f32 v[12:13], v[146:147], v[232:233], v[12:13]
	v_pk_fma_f32 v[14:15], v[148:149], v[234:235], v[14:15]
	v_pk_fma_f32 v[16:17], v[150:151], v[236:237], v[16:17]
	v_mul_f32_e32 v18, 0xbfb8aa3b, v2
	v_mul_f32_e32 v19, 0xbfb8aa3b, v3
	v_mul_f32_e32 v20, 0xbfb8aa3b, v4
	v_mul_f32_e32 v21, 0xbfb8aa3b, v5
	v_mul_f32_e32 v22, 0xbfb8aa3b, v6
	v_mul_f32_e32 v23, 0xbfb8aa3b, v7
	v_mul_f32_e32 v24, 0xbfb8aa3b, v8
	v_mul_f32_e32 v25, 0xbfb8aa3b, v9
	v_exp_f32_e32 v18, v18
	v_exp_f32_e32 v19, v19
	v_exp_f32_e32 v20, v20
	v_exp_f32_e32 v21, v21
	v_exp_f32_e32 v22, v22
	v_exp_f32_e32 v23, v23
	v_exp_f32_e32 v24, v24
	v_exp_f32_e32 v25, v25
	v_add_f32_e32 v18, 1.0, v18
	v_add_f32_e32 v19, 1.0, v19
	v_add_f32_e32 v20, 1.0, v20
	v_add_f32_e32 v21, 1.0, v21
	v_add_f32_e32 v22, 1.0, v22
	v_add_f32_e32 v23, 1.0, v23
	v_add_f32_e32 v24, 1.0, v24
	v_add_f32_e32 v25, 1.0, v25
	v_rcp_f32_e32 v18, v18
	v_rcp_f32_e32 v19, v19
	v_rcp_f32_e32 v20, v20
	v_rcp_f32_e32 v21, v21
	v_rcp_f32_e32 v22, v22
	v_rcp_f32_e32 v23, v23
	v_rcp_f32_e32 v24, v24
	v_rcp_f32_e32 v25, v25
	v_mul_f32_e32 v18, v2, v18
	v_mul_f32_e32 v19, v3, v19
	v_mul_f32_e32 v20, v4, v20
	v_mul_f32_e32 v21, v5, v21
	v_mul_f32_e32 v22, v6, v22
	v_mul_f32_e32 v23, v7, v23
	v_mul_f32_e32 v24, v8, v24
	v_mul_f32_e32 v25, v9, v25
	v_mul_f32_e32 v18, v10, v18
	v_mul_f32_e32 v19, v11, v19
	v_mul_f32_e32 v20, v12, v20
	v_mul_f32_e32 v21, v13, v21
	v_mul_f32_e32 v22, v14, v22
	v_mul_f32_e32 v23, v15, v23
	v_mul_f32_e32 v24, v16, v24
	v_mul_f32_e32 v25, v17, v25
	v_cvt_pk_bf16_f32 v26, v18, v19
	v_cvt_pk_bf16_f32 v27, v20, v21
	v_cvt_pk_bf16_f32 v28, v22, v23
	v_cvt_pk_bf16_f32 v29, v24, v25
	global_store_dwordx4 v[162:163], v[26:29], off sc1
	v_lshl_add_u64 v[162:163], v[162:163], 0, v[30:31]
	v_lshlrev_b32_e32 v190, 16, v44
	v_and_b32_e32 v191, 0xffff0000, v44
	v_lshlrev_b32_e32 v192, 16, v45
	v_and_b32_e32 v193, 0xffff0000, v45
	v_lshlrev_b32_e32 v194, 16, v46
	v_and_b32_e32 v195, 0xffff0000, v46
	v_lshlrev_b32_e32 v196, 16, v47
	v_and_b32_e32 v197, 0xffff0000, v47
	v_lshlrev_b32_e32 v198, 16, v48
	v_and_b32_e32 v199, 0xffff0000, v48
	v_lshlrev_b32_e32 v200, 16, v49
	v_and_b32_e32 v201, 0xffff0000, v49
	v_lshlrev_b32_e32 v202, 16, v50
	v_and_b32_e32 v203, 0xffff0000, v50
	v_lshlrev_b32_e32 v204, 16, v51
	v_and_b32_e32 v205, 0xffff0000, v51
	v_pk_fma_f32 v[2:3], v[104:105], v[206:207], v[174:175]
	v_pk_fma_f32 v[4:5], v[106:107], v[208:209], v[176:177]
	v_pk_fma_f32 v[6:7], v[108:109], v[210:211], v[178:179]
	v_pk_fma_f32 v[8:9], v[110:111], v[212:213], v[180:181]
	v_pk_fma_f32 v[10:11], v[112:113], v[214:215], v[182:183]
	v_pk_fma_f32 v[12:13], v[114:115], v[216:217], v[184:185]
	v_pk_fma_f32 v[14:15], v[116:117], v[218:219], v[186:187]
	v_pk_fma_f32 v[16:17], v[118:119], v[220:221], v[188:189]
	v_pk_fma_f32 v[2:3], v[120:121], v[222:223], v[2:3]
	v_pk_fma_f32 v[4:5], v[122:123], v[224:225], v[4:5]
	v_pk_fma_f32 v[6:7], v[124:125], v[226:227], v[6:7]
	v_pk_fma_f32 v[8:9], v[126:127], v[228:229], v[8:9]
	v_pk_fma_f32 v[10:11], v[128:129], v[230:231], v[10:11]
	v_pk_fma_f32 v[12:13], v[130:131], v[232:233], v[12:13]
	v_pk_fma_f32 v[14:15], v[132:133], v[234:235], v[14:15]
	v_pk_fma_f32 v[16:17], v[134:135], v[236:237], v[16:17]
	v_pk_fma_f32 v[2:3], v[136:137], v[190:191], v[2:3]
	v_pk_fma_f32 v[4:5], v[138:139], v[192:193], v[4:5]
	v_pk_fma_f32 v[6:7], v[140:141], v[194:195], v[6:7]
	v_pk_fma_f32 v[8:9], v[142:143], v[196:197], v[8:9]
	v_pk_fma_f32 v[10:11], v[144:145], v[198:199], v[10:11]
	v_pk_fma_f32 v[12:13], v[146:147], v[200:201], v[12:13]
	v_pk_fma_f32 v[14:15], v[148:149], v[202:203], v[14:15]
	v_pk_fma_f32 v[16:17], v[150:151], v[204:205], v[16:17]
	v_mul_f32_e32 v18, 0xbfb8aa3b, v2
	v_mul_f32_e32 v19, 0xbfb8aa3b, v3
	v_mul_f32_e32 v20, 0xbfb8aa3b, v4
	v_mul_f32_e32 v21, 0xbfb8aa3b, v5
	v_mul_f32_e32 v22, 0xbfb8aa3b, v6
	v_mul_f32_e32 v23, 0xbfb8aa3b, v7
	v_mul_f32_e32 v24, 0xbfb8aa3b, v8
	v_mul_f32_e32 v25, 0xbfb8aa3b, v9
	v_exp_f32_e32 v18, v18
	v_exp_f32_e32 v19, v19
	v_exp_f32_e32 v20, v20
	v_exp_f32_e32 v21, v21
	v_exp_f32_e32 v22, v22
	v_exp_f32_e32 v23, v23
	v_exp_f32_e32 v24, v24
	v_exp_f32_e32 v25, v25
	v_add_f32_e32 v18, 1.0, v18
	v_add_f32_e32 v19, 1.0, v19
	v_add_f32_e32 v20, 1.0, v20
	v_add_f32_e32 v21, 1.0, v21
	v_add_f32_e32 v22, 1.0, v22
	v_add_f32_e32 v23, 1.0, v23
	v_add_f32_e32 v24, 1.0, v24
	v_add_f32_e32 v25, 1.0, v25
	v_rcp_f32_e32 v18, v18
	v_rcp_f32_e32 v19, v19
	v_rcp_f32_e32 v20, v20
	v_rcp_f32_e32 v21, v21
	v_rcp_f32_e32 v22, v22
	v_rcp_f32_e32 v23, v23
	v_rcp_f32_e32 v24, v24
	v_rcp_f32_e32 v25, v25
	v_mul_f32_e32 v18, v2, v18
	v_mul_f32_e32 v19, v3, v19
	v_mul_f32_e32 v20, v4, v20
	v_mul_f32_e32 v21, v5, v21
	v_mul_f32_e32 v22, v6, v22
	v_mul_f32_e32 v23, v7, v23
	v_mul_f32_e32 v24, v8, v24
	v_mul_f32_e32 v25, v9, v25
	v_mul_f32_e32 v18, v10, v18
	v_mul_f32_e32 v19, v11, v19
	v_mul_f32_e32 v20, v12, v20
	v_mul_f32_e32 v21, v13, v21
	v_mul_f32_e32 v22, v14, v22
	v_mul_f32_e32 v23, v15, v23
	v_mul_f32_e32 v24, v16, v24
	v_mul_f32_e32 v25, v17, v25
	v_cvt_pk_bf16_f32 v26, v18, v19
	v_cvt_pk_bf16_f32 v27, v20, v21
	v_cvt_pk_bf16_f32 v28, v22, v23
	v_cvt_pk_bf16_f32 v29, v24, v25
	global_store_dwordx4 v[162:163], v[26:29], off sc1
	v_lshl_add_u64 v[162:163], v[162:163], 0, v[30:31]
	v_lshlrev_b32_e32 v206, 16, v52
	v_and_b32_e32 v207, 0xffff0000, v52
	v_lshlrev_b32_e32 v208, 16, v53
	v_and_b32_e32 v209, 0xffff0000, v53
	v_lshlrev_b32_e32 v210, 16, v54
	v_and_b32_e32 v211, 0xffff0000, v54
	v_lshlrev_b32_e32 v212, 16, v55
	v_and_b32_e32 v213, 0xffff0000, v55
	v_lshlrev_b32_e32 v214, 16, v56
	v_and_b32_e32 v215, 0xffff0000, v56
	v_lshlrev_b32_e32 v216, 16, v57
	v_and_b32_e32 v217, 0xffff0000, v57
	v_lshlrev_b32_e32 v218, 16, v58
	v_and_b32_e32 v219, 0xffff0000, v58
	v_lshlrev_b32_e32 v220, 16, v59
	v_and_b32_e32 v221, 0xffff0000, v59
	v_pk_fma_f32 v[2:3], v[104:105], v[222:223], v[174:175]
	v_pk_fma_f32 v[4:5], v[106:107], v[224:225], v[176:177]
	v_pk_fma_f32 v[6:7], v[108:109], v[226:227], v[178:179]
	v_pk_fma_f32 v[8:9], v[110:111], v[228:229], v[180:181]
	v_pk_fma_f32 v[10:11], v[112:113], v[230:231], v[182:183]
	v_pk_fma_f32 v[12:13], v[114:115], v[232:233], v[184:185]
	v_pk_fma_f32 v[14:15], v[116:117], v[234:235], v[186:187]
	v_pk_fma_f32 v[16:17], v[118:119], v[236:237], v[188:189]
	v_pk_fma_f32 v[2:3], v[120:121], v[190:191], v[2:3]
	v_pk_fma_f32 v[4:5], v[122:123], v[192:193], v[4:5]
	v_pk_fma_f32 v[6:7], v[124:125], v[194:195], v[6:7]
	v_pk_fma_f32 v[8:9], v[126:127], v[196:197], v[8:9]
	v_pk_fma_f32 v[10:11], v[128:129], v[198:199], v[10:11]
	v_pk_fma_f32 v[12:13], v[130:131], v[200:201], v[12:13]
	v_pk_fma_f32 v[14:15], v[132:133], v[202:203], v[14:15]
	v_pk_fma_f32 v[16:17], v[134:135], v[204:205], v[16:17]
	v_pk_fma_f32 v[2:3], v[136:137], v[206:207], v[2:3]
	v_pk_fma_f32 v[4:5], v[138:139], v[208:209], v[4:5]
	v_pk_fma_f32 v[6:7], v[140:141], v[210:211], v[6:7]
	v_pk_fma_f32 v[8:9], v[142:143], v[212:213], v[8:9]
	v_pk_fma_f32 v[10:11], v[144:145], v[214:215], v[10:11]
	v_pk_fma_f32 v[12:13], v[146:147], v[216:217], v[12:13]
	v_pk_fma_f32 v[14:15], v[148:149], v[218:219], v[14:15]
	v_pk_fma_f32 v[16:17], v[150:151], v[220:221], v[16:17]
	v_mul_f32_e32 v18, 0xbfb8aa3b, v2
	v_mul_f32_e32 v19, 0xbfb8aa3b, v3
	v_mul_f32_e32 v20, 0xbfb8aa3b, v4
	v_mul_f32_e32 v21, 0xbfb8aa3b, v5
	v_mul_f32_e32 v22, 0xbfb8aa3b, v6
	v_mul_f32_e32 v23, 0xbfb8aa3b, v7
	v_mul_f32_e32 v24, 0xbfb8aa3b, v8
	v_mul_f32_e32 v25, 0xbfb8aa3b, v9
	v_exp_f32_e32 v18, v18
	v_exp_f32_e32 v19, v19
	v_exp_f32_e32 v20, v20
	v_exp_f32_e32 v21, v21
	v_exp_f32_e32 v22, v22
	v_exp_f32_e32 v23, v23
	v_exp_f32_e32 v24, v24
	v_exp_f32_e32 v25, v25
	v_add_f32_e32 v18, 1.0, v18
	v_add_f32_e32 v19, 1.0, v19
	v_add_f32_e32 v20, 1.0, v20
	v_add_f32_e32 v21, 1.0, v21
	v_add_f32_e32 v22, 1.0, v22
	v_add_f32_e32 v23, 1.0, v23
	v_add_f32_e32 v24, 1.0, v24
	v_add_f32_e32 v25, 1.0, v25
	v_rcp_f32_e32 v18, v18
	v_rcp_f32_e32 v19, v19
	v_rcp_f32_e32 v20, v20
	v_rcp_f32_e32 v21, v21
	v_rcp_f32_e32 v22, v22
	v_rcp_f32_e32 v23, v23
	v_rcp_f32_e32 v24, v24
	v_rcp_f32_e32 v25, v25
	v_mul_f32_e32 v18, v2, v18
	v_mul_f32_e32 v19, v3, v19
	v_mul_f32_e32 v20, v4, v20
	v_mul_f32_e32 v21, v5, v21
	v_mul_f32_e32 v22, v6, v22
	v_mul_f32_e32 v23, v7, v23
	v_mul_f32_e32 v24, v8, v24
	v_mul_f32_e32 v25, v9, v25
	v_mul_f32_e32 v18, v10, v18
	v_mul_f32_e32 v19, v11, v19
	v_mul_f32_e32 v20, v12, v20
	v_mul_f32_e32 v21, v13, v21
	v_mul_f32_e32 v22, v14, v22
	v_mul_f32_e32 v23, v15, v23
	v_mul_f32_e32 v24, v16, v24
	v_mul_f32_e32 v25, v17, v25
	v_cvt_pk_bf16_f32 v26, v18, v19
	v_cvt_pk_bf16_f32 v27, v20, v21
	v_cvt_pk_bf16_f32 v28, v22, v23
	v_cvt_pk_bf16_f32 v29, v24, v25
	global_store_dwordx4 v[162:163], v[26:29], off sc1
	v_lshl_add_u64 v[162:163], v[162:163], 0, v[30:31]
	v_lshlrev_b32_e32 v222, 16, v60
	v_and_b32_e32 v223, 0xffff0000, v60
	v_lshlrev_b32_e32 v224, 16, v61
	v_and_b32_e32 v225, 0xffff0000, v61
	v_lshlrev_b32_e32 v226, 16, v62
	v_and_b32_e32 v227, 0xffff0000, v62
	v_lshlrev_b32_e32 v228, 16, v63
	v_and_b32_e32 v229, 0xffff0000, v63
	v_lshlrev_b32_e32 v230, 16, v64
	v_and_b32_e32 v231, 0xffff0000, v64
	v_lshlrev_b32_e32 v232, 16, v65
	v_and_b32_e32 v233, 0xffff0000, v65
	v_lshlrev_b32_e32 v234, 16, v66
	v_and_b32_e32 v235, 0xffff0000, v66
	v_lshlrev_b32_e32 v236, 16, v67
	v_and_b32_e32 v237, 0xffff0000, v67
	v_pk_fma_f32 v[2:3], v[104:105], v[190:191], v[174:175]
	v_pk_fma_f32 v[4:5], v[106:107], v[192:193], v[176:177]
	v_pk_fma_f32 v[6:7], v[108:109], v[194:195], v[178:179]
	v_pk_fma_f32 v[8:9], v[110:111], v[196:197], v[180:181]
	v_pk_fma_f32 v[10:11], v[112:113], v[198:199], v[182:183]
	v_pk_fma_f32 v[12:13], v[114:115], v[200:201], v[184:185]
	v_pk_fma_f32 v[14:15], v[116:117], v[202:203], v[186:187]
	v_pk_fma_f32 v[16:17], v[118:119], v[204:205], v[188:189]
	v_pk_fma_f32 v[2:3], v[120:121], v[206:207], v[2:3]
	v_pk_fma_f32 v[4:5], v[122:123], v[208:209], v[4:5]
	v_pk_fma_f32 v[6:7], v[124:125], v[210:211], v[6:7]
	v_pk_fma_f32 v[8:9], v[126:127], v[212:213], v[8:9]
	v_pk_fma_f32 v[10:11], v[128:129], v[214:215], v[10:11]
	v_pk_fma_f32 v[12:13], v[130:131], v[216:217], v[12:13]
	v_pk_fma_f32 v[14:15], v[132:133], v[218:219], v[14:15]
	v_pk_fma_f32 v[16:17], v[134:135], v[220:221], v[16:17]
	v_pk_fma_f32 v[2:3], v[136:137], v[222:223], v[2:3]
	v_pk_fma_f32 v[4:5], v[138:139], v[224:225], v[4:5]
	v_pk_fma_f32 v[6:7], v[140:141], v[226:227], v[6:7]
	v_pk_fma_f32 v[8:9], v[142:143], v[228:229], v[8:9]
	v_pk_fma_f32 v[10:11], v[144:145], v[230:231], v[10:11]
	v_pk_fma_f32 v[12:13], v[146:147], v[232:233], v[12:13]
	v_pk_fma_f32 v[14:15], v[148:149], v[234:235], v[14:15]
	v_pk_fma_f32 v[16:17], v[150:151], v[236:237], v[16:17]
	v_mul_f32_e32 v18, 0xbfb8aa3b, v2
	v_mul_f32_e32 v19, 0xbfb8aa3b, v3
	v_mul_f32_e32 v20, 0xbfb8aa3b, v4
	v_mul_f32_e32 v21, 0xbfb8aa3b, v5
	v_mul_f32_e32 v22, 0xbfb8aa3b, v6
	v_mul_f32_e32 v23, 0xbfb8aa3b, v7
	v_mul_f32_e32 v24, 0xbfb8aa3b, v8
	v_mul_f32_e32 v25, 0xbfb8aa3b, v9
	v_exp_f32_e32 v18, v18
	v_exp_f32_e32 v19, v19
	v_exp_f32_e32 v20, v20
	v_exp_f32_e32 v21, v21
	v_exp_f32_e32 v22, v22
	v_exp_f32_e32 v23, v23
	v_exp_f32_e32 v24, v24
	v_exp_f32_e32 v25, v25
	v_add_f32_e32 v18, 1.0, v18
	v_add_f32_e32 v19, 1.0, v19
	v_add_f32_e32 v20, 1.0, v20
	v_add_f32_e32 v21, 1.0, v21
	v_add_f32_e32 v22, 1.0, v22
	v_add_f32_e32 v23, 1.0, v23
	v_add_f32_e32 v24, 1.0, v24
	v_add_f32_e32 v25, 1.0, v25
	v_rcp_f32_e32 v18, v18
	v_rcp_f32_e32 v19, v19
	v_rcp_f32_e32 v20, v20
	v_rcp_f32_e32 v21, v21
	v_rcp_f32_e32 v22, v22
	v_rcp_f32_e32 v23, v23
	v_rcp_f32_e32 v24, v24
	v_rcp_f32_e32 v25, v25
	v_mul_f32_e32 v18, v2, v18
	v_mul_f32_e32 v19, v3, v19
	v_mul_f32_e32 v20, v4, v20
	v_mul_f32_e32 v21, v5, v21
	v_mul_f32_e32 v22, v6, v22
	v_mul_f32_e32 v23, v7, v23
	v_mul_f32_e32 v24, v8, v24
	v_mul_f32_e32 v25, v9, v25
	v_mul_f32_e32 v18, v10, v18
	v_mul_f32_e32 v19, v11, v19
	v_mul_f32_e32 v20, v12, v20
	v_mul_f32_e32 v21, v13, v21
	v_mul_f32_e32 v22, v14, v22
	v_mul_f32_e32 v23, v15, v23
	v_mul_f32_e32 v24, v16, v24
	v_mul_f32_e32 v25, v17, v25
	v_cvt_pk_bf16_f32 v26, v18, v19
	v_cvt_pk_bf16_f32 v27, v20, v21
	v_cvt_pk_bf16_f32 v28, v22, v23
	v_cvt_pk_bf16_f32 v29, v24, v25
	global_store_dwordx4 v[162:163], v[26:29], off sc1
	v_lshl_add_u64 v[162:163], v[162:163], 0, v[30:31]
	s_waitcnt vmcnt(4)
	v_lshlrev_b32_e32 v190, 16, v68
	v_and_b32_e32 v191, 0xffff0000, v68
	v_lshlrev_b32_e32 v192, 16, v69
	v_and_b32_e32 v193, 0xffff0000, v69
	v_lshlrev_b32_e32 v194, 16, v70
	v_and_b32_e32 v195, 0xffff0000, v70
	v_lshlrev_b32_e32 v196, 16, v71
	v_and_b32_e32 v197, 0xffff0000, v71
	v_lshlrev_b32_e32 v198, 16, v72
	v_and_b32_e32 v199, 0xffff0000, v72
	v_lshlrev_b32_e32 v200, 16, v73
	v_and_b32_e32 v201, 0xffff0000, v73
	v_lshlrev_b32_e32 v202, 16, v74
	v_and_b32_e32 v203, 0xffff0000, v74
	v_lshlrev_b32_e32 v204, 16, v75
	v_and_b32_e32 v205, 0xffff0000, v75
	v_pk_fma_f32 v[2:3], v[104:105], v[206:207], v[174:175]
	v_pk_fma_f32 v[4:5], v[106:107], v[208:209], v[176:177]
	v_pk_fma_f32 v[6:7], v[108:109], v[210:211], v[178:179]
	v_pk_fma_f32 v[8:9], v[110:111], v[212:213], v[180:181]
	v_pk_fma_f32 v[10:11], v[112:113], v[214:215], v[182:183]
	v_pk_fma_f32 v[12:13], v[114:115], v[216:217], v[184:185]
	v_pk_fma_f32 v[14:15], v[116:117], v[218:219], v[186:187]
	v_pk_fma_f32 v[16:17], v[118:119], v[220:221], v[188:189]
	v_pk_fma_f32 v[2:3], v[120:121], v[222:223], v[2:3]
	v_pk_fma_f32 v[4:5], v[122:123], v[224:225], v[4:5]
	v_pk_fma_f32 v[6:7], v[124:125], v[226:227], v[6:7]
	v_pk_fma_f32 v[8:9], v[126:127], v[228:229], v[8:9]
	v_pk_fma_f32 v[10:11], v[128:129], v[230:231], v[10:11]
	v_pk_fma_f32 v[12:13], v[130:131], v[232:233], v[12:13]
	v_pk_fma_f32 v[14:15], v[132:133], v[234:235], v[14:15]
	v_pk_fma_f32 v[16:17], v[134:135], v[236:237], v[16:17]
	v_pk_fma_f32 v[2:3], v[136:137], v[190:191], v[2:3]
	v_pk_fma_f32 v[4:5], v[138:139], v[192:193], v[4:5]
	v_pk_fma_f32 v[6:7], v[140:141], v[194:195], v[6:7]
	v_pk_fma_f32 v[8:9], v[142:143], v[196:197], v[8:9]
	v_pk_fma_f32 v[10:11], v[144:145], v[198:199], v[10:11]
	v_pk_fma_f32 v[12:13], v[146:147], v[200:201], v[12:13]
	v_pk_fma_f32 v[14:15], v[148:149], v[202:203], v[14:15]
	v_pk_fma_f32 v[16:17], v[150:151], v[204:205], v[16:17]
	v_mul_f32_e32 v18, 0xbfb8aa3b, v2
	v_mul_f32_e32 v19, 0xbfb8aa3b, v3
	v_mul_f32_e32 v20, 0xbfb8aa3b, v4
	v_mul_f32_e32 v21, 0xbfb8aa3b, v5
	v_mul_f32_e32 v22, 0xbfb8aa3b, v6
	v_mul_f32_e32 v23, 0xbfb8aa3b, v7
	v_mul_f32_e32 v24, 0xbfb8aa3b, v8
	v_mul_f32_e32 v25, 0xbfb8aa3b, v9
	v_exp_f32_e32 v18, v18
	v_exp_f32_e32 v19, v19
	v_exp_f32_e32 v20, v20
	v_exp_f32_e32 v21, v21
	v_exp_f32_e32 v22, v22
	v_exp_f32_e32 v23, v23
	v_exp_f32_e32 v24, v24
	v_exp_f32_e32 v25, v25
	v_add_f32_e32 v18, 1.0, v18
	v_add_f32_e32 v19, 1.0, v19
	v_add_f32_e32 v20, 1.0, v20
	v_add_f32_e32 v21, 1.0, v21
	v_add_f32_e32 v22, 1.0, v22
	v_add_f32_e32 v23, 1.0, v23
	v_add_f32_e32 v24, 1.0, v24
	v_add_f32_e32 v25, 1.0, v25
	v_rcp_f32_e32 v18, v18
	v_rcp_f32_e32 v19, v19
	v_rcp_f32_e32 v20, v20
	v_rcp_f32_e32 v21, v21
	v_rcp_f32_e32 v22, v22
	v_rcp_f32_e32 v23, v23
	v_rcp_f32_e32 v24, v24
	v_rcp_f32_e32 v25, v25
	v_mul_f32_e32 v18, v2, v18
	v_mul_f32_e32 v19, v3, v19
	v_mul_f32_e32 v20, v4, v20
	v_mul_f32_e32 v21, v5, v21
	v_mul_f32_e32 v22, v6, v22
	v_mul_f32_e32 v23, v7, v23
	v_mul_f32_e32 v24, v8, v24
	v_mul_f32_e32 v25, v9, v25
	v_mul_f32_e32 v18, v10, v18
	v_mul_f32_e32 v19, v11, v19
	v_mul_f32_e32 v20, v12, v20
	v_mul_f32_e32 v21, v13, v21
	v_mul_f32_e32 v22, v14, v22
	v_mul_f32_e32 v23, v15, v23
	v_mul_f32_e32 v24, v16, v24
	v_mul_f32_e32 v25, v17, v25
	v_cvt_pk_bf16_f32 v26, v18, v19
	v_cvt_pk_bf16_f32 v27, v20, v21
	v_cvt_pk_bf16_f32 v28, v22, v23
	v_cvt_pk_bf16_f32 v29, v24, v25
	global_store_dwordx4 v[162:163], v[26:29], off sc1
	v_lshl_add_u64 v[162:163], v[162:163], 0, v[30:31]
	v_lshlrev_b32_e32 v206, 16, v76
	v_and_b32_e32 v207, 0xffff0000, v76
	v_lshlrev_b32_e32 v208, 16, v77
	v_and_b32_e32 v209, 0xffff0000, v77
	v_lshlrev_b32_e32 v210, 16, v78
	v_and_b32_e32 v211, 0xffff0000, v78
	v_lshlrev_b32_e32 v212, 16, v79
	v_and_b32_e32 v213, 0xffff0000, v79
	v_lshlrev_b32_e32 v214, 16, v80
	v_and_b32_e32 v215, 0xffff0000, v80
	v_lshlrev_b32_e32 v216, 16, v81
	v_and_b32_e32 v217, 0xffff0000, v81
	v_lshlrev_b32_e32 v218, 16, v82
	v_and_b32_e32 v219, 0xffff0000, v82
	v_lshlrev_b32_e32 v220, 16, v83
	v_and_b32_e32 v221, 0xffff0000, v83
	v_pk_fma_f32 v[2:3], v[104:105], v[222:223], v[174:175]
	v_pk_fma_f32 v[4:5], v[106:107], v[224:225], v[176:177]
	v_pk_fma_f32 v[6:7], v[108:109], v[226:227], v[178:179]
	v_pk_fma_f32 v[8:9], v[110:111], v[228:229], v[180:181]
	v_pk_fma_f32 v[10:11], v[112:113], v[230:231], v[182:183]
	v_pk_fma_f32 v[12:13], v[114:115], v[232:233], v[184:185]
	v_pk_fma_f32 v[14:15], v[116:117], v[234:235], v[186:187]
	v_pk_fma_f32 v[16:17], v[118:119], v[236:237], v[188:189]
	v_pk_fma_f32 v[2:3], v[120:121], v[190:191], v[2:3]
	v_pk_fma_f32 v[4:5], v[122:123], v[192:193], v[4:5]
	v_pk_fma_f32 v[6:7], v[124:125], v[194:195], v[6:7]
	v_pk_fma_f32 v[8:9], v[126:127], v[196:197], v[8:9]
	v_pk_fma_f32 v[10:11], v[128:129], v[198:199], v[10:11]
	v_pk_fma_f32 v[12:13], v[130:131], v[200:201], v[12:13]
	v_pk_fma_f32 v[14:15], v[132:133], v[202:203], v[14:15]
	v_pk_fma_f32 v[16:17], v[134:135], v[204:205], v[16:17]
	v_pk_fma_f32 v[2:3], v[136:137], v[206:207], v[2:3]
	v_pk_fma_f32 v[4:5], v[138:139], v[208:209], v[4:5]
	v_pk_fma_f32 v[6:7], v[140:141], v[210:211], v[6:7]
	v_pk_fma_f32 v[8:9], v[142:143], v[212:213], v[8:9]
	v_pk_fma_f32 v[10:11], v[144:145], v[214:215], v[10:11]
	v_pk_fma_f32 v[12:13], v[146:147], v[216:217], v[12:13]
	v_pk_fma_f32 v[14:15], v[148:149], v[218:219], v[14:15]
	v_pk_fma_f32 v[16:17], v[150:151], v[220:221], v[16:17]
	v_mul_f32_e32 v18, 0xbfb8aa3b, v2
	v_mul_f32_e32 v19, 0xbfb8aa3b, v3
	v_mul_f32_e32 v20, 0xbfb8aa3b, v4
	v_mul_f32_e32 v21, 0xbfb8aa3b, v5
	v_mul_f32_e32 v22, 0xbfb8aa3b, v6
	v_mul_f32_e32 v23, 0xbfb8aa3b, v7
	v_mul_f32_e32 v24, 0xbfb8aa3b, v8
	v_mul_f32_e32 v25, 0xbfb8aa3b, v9
	v_exp_f32_e32 v18, v18
	v_exp_f32_e32 v19, v19
	v_exp_f32_e32 v20, v20
	v_exp_f32_e32 v21, v21
	v_exp_f32_e32 v22, v22
	v_exp_f32_e32 v23, v23
	v_exp_f32_e32 v24, v24
	v_exp_f32_e32 v25, v25
	v_add_f32_e32 v18, 1.0, v18
	v_add_f32_e32 v19, 1.0, v19
	v_add_f32_e32 v20, 1.0, v20
	v_add_f32_e32 v21, 1.0, v21
	v_add_f32_e32 v22, 1.0, v22
	v_add_f32_e32 v23, 1.0, v23
	v_add_f32_e32 v24, 1.0, v24
	v_add_f32_e32 v25, 1.0, v25
	v_rcp_f32_e32 v18, v18
	v_rcp_f32_e32 v19, v19
	v_rcp_f32_e32 v20, v20
	v_rcp_f32_e32 v21, v21
	v_rcp_f32_e32 v22, v22
	v_rcp_f32_e32 v23, v23
	v_rcp_f32_e32 v24, v24
	v_rcp_f32_e32 v25, v25
	v_mul_f32_e32 v18, v2, v18
	v_mul_f32_e32 v19, v3, v19
	v_mul_f32_e32 v20, v4, v20
	v_mul_f32_e32 v21, v5, v21
	v_mul_f32_e32 v22, v6, v22
	v_mul_f32_e32 v23, v7, v23
	v_mul_f32_e32 v24, v8, v24
	v_mul_f32_e32 v25, v9, v25
	v_mul_f32_e32 v18, v10, v18
	v_mul_f32_e32 v19, v11, v19
	v_mul_f32_e32 v20, v12, v20
	v_mul_f32_e32 v21, v13, v21
	v_mul_f32_e32 v22, v14, v22
	v_mul_f32_e32 v23, v15, v23
	v_mul_f32_e32 v24, v16, v24
	v_mul_f32_e32 v25, v17, v25
	v_cvt_pk_bf16_f32 v26, v18, v19
	v_cvt_pk_bf16_f32 v27, v20, v21
	v_cvt_pk_bf16_f32 v28, v22, v23
	v_cvt_pk_bf16_f32 v29, v24, v25
	global_store_dwordx4 v[162:163], v[26:29], off sc1
	v_lshl_add_u64 v[162:163], v[162:163], 0, v[30:31]
	v_lshlrev_b32_e32 v222, 16, v88
	v_and_b32_e32 v223, 0xffff0000, v88
	v_lshlrev_b32_e32 v224, 16, v89
	v_and_b32_e32 v225, 0xffff0000, v89
	v_lshlrev_b32_e32 v226, 16, v90
	v_and_b32_e32 v227, 0xffff0000, v90
	v_lshlrev_b32_e32 v228, 16, v91
	v_and_b32_e32 v229, 0xffff0000, v91
	v_lshlrev_b32_e32 v230, 16, v92
	v_and_b32_e32 v231, 0xffff0000, v92
	v_lshlrev_b32_e32 v232, 16, v93
	v_and_b32_e32 v233, 0xffff0000, v93
	v_lshlrev_b32_e32 v234, 16, v94
	v_and_b32_e32 v235, 0xffff0000, v94
	v_lshlrev_b32_e32 v236, 16, v95
	v_and_b32_e32 v237, 0xffff0000, v95
	v_pk_fma_f32 v[2:3], v[104:105], v[190:191], v[174:175]
	v_pk_fma_f32 v[4:5], v[106:107], v[192:193], v[176:177]
	v_pk_fma_f32 v[6:7], v[108:109], v[194:195], v[178:179]
	v_pk_fma_f32 v[8:9], v[110:111], v[196:197], v[180:181]
	v_pk_fma_f32 v[10:11], v[112:113], v[198:199], v[182:183]
	v_pk_fma_f32 v[12:13], v[114:115], v[200:201], v[184:185]
	v_pk_fma_f32 v[14:15], v[116:117], v[202:203], v[186:187]
	v_pk_fma_f32 v[16:17], v[118:119], v[204:205], v[188:189]
	v_pk_fma_f32 v[2:3], v[120:121], v[206:207], v[2:3]
	v_pk_fma_f32 v[4:5], v[122:123], v[208:209], v[4:5]
	v_pk_fma_f32 v[6:7], v[124:125], v[210:211], v[6:7]
	v_pk_fma_f32 v[8:9], v[126:127], v[212:213], v[8:9]
	v_pk_fma_f32 v[10:11], v[128:129], v[214:215], v[10:11]
	v_pk_fma_f32 v[12:13], v[130:131], v[216:217], v[12:13]
	v_pk_fma_f32 v[14:15], v[132:133], v[218:219], v[14:15]
	v_pk_fma_f32 v[16:17], v[134:135], v[220:221], v[16:17]
	v_pk_fma_f32 v[2:3], v[136:137], v[222:223], v[2:3]
	v_pk_fma_f32 v[4:5], v[138:139], v[224:225], v[4:5]
	v_pk_fma_f32 v[6:7], v[140:141], v[226:227], v[6:7]
	v_pk_fma_f32 v[8:9], v[142:143], v[228:229], v[8:9]
	v_pk_fma_f32 v[10:11], v[144:145], v[230:231], v[10:11]
	v_pk_fma_f32 v[12:13], v[146:147], v[232:233], v[12:13]
	v_pk_fma_f32 v[14:15], v[148:149], v[234:235], v[14:15]
	v_pk_fma_f32 v[16:17], v[150:151], v[236:237], v[16:17]
	v_mul_f32_e32 v18, 0xbfb8aa3b, v2
	v_mul_f32_e32 v19, 0xbfb8aa3b, v3
	v_mul_f32_e32 v20, 0xbfb8aa3b, v4
	v_mul_f32_e32 v21, 0xbfb8aa3b, v5
	v_mul_f32_e32 v22, 0xbfb8aa3b, v6
	v_mul_f32_e32 v23, 0xbfb8aa3b, v7
	v_mul_f32_e32 v24, 0xbfb8aa3b, v8
	v_mul_f32_e32 v25, 0xbfb8aa3b, v9
	v_exp_f32_e32 v18, v18
	v_exp_f32_e32 v19, v19
	v_exp_f32_e32 v20, v20
	v_exp_f32_e32 v21, v21
	v_exp_f32_e32 v22, v22
	v_exp_f32_e32 v23, v23
	v_exp_f32_e32 v24, v24
	v_exp_f32_e32 v25, v25
	v_add_f32_e32 v18, 1.0, v18
	v_add_f32_e32 v19, 1.0, v19
	v_add_f32_e32 v20, 1.0, v20
	v_add_f32_e32 v21, 1.0, v21
	v_add_f32_e32 v22, 1.0, v22
	v_add_f32_e32 v23, 1.0, v23
	v_add_f32_e32 v24, 1.0, v24
	v_add_f32_e32 v25, 1.0, v25
	v_rcp_f32_e32 v18, v18
	v_rcp_f32_e32 v19, v19
	v_rcp_f32_e32 v20, v20
	v_rcp_f32_e32 v21, v21
	v_rcp_f32_e32 v22, v22
	v_rcp_f32_e32 v23, v23
	v_rcp_f32_e32 v24, v24
	v_rcp_f32_e32 v25, v25
	v_mul_f32_e32 v18, v2, v18
	v_mul_f32_e32 v19, v3, v19
	v_mul_f32_e32 v20, v4, v20
	v_mul_f32_e32 v21, v5, v21
	v_mul_f32_e32 v22, v6, v22
	v_mul_f32_e32 v23, v7, v23
	v_mul_f32_e32 v24, v8, v24
	v_mul_f32_e32 v25, v9, v25
	v_mul_f32_e32 v18, v10, v18
	v_mul_f32_e32 v19, v11, v19
	v_mul_f32_e32 v20, v12, v20
	v_mul_f32_e32 v21, v13, v21
	v_mul_f32_e32 v22, v14, v22
	v_mul_f32_e32 v23, v15, v23
	v_mul_f32_e32 v24, v16, v24
	v_mul_f32_e32 v25, v17, v25
	v_cvt_pk_bf16_f32 v26, v18, v19
	v_cvt_pk_bf16_f32 v27, v20, v21
	v_cvt_pk_bf16_f32 v28, v22, v23
	v_cvt_pk_bf16_f32 v29, v24, v25
	global_store_dwordx4 v[162:163], v[26:29], off sc1
	v_lshl_add_u64 v[162:163], v[162:163], 0, v[30:31]
	v_lshlrev_b32_e32 v190, 16, v96
	v_and_b32_e32 v191, 0xffff0000, v96
	v_lshlrev_b32_e32 v192, 16, v97
	v_and_b32_e32 v193, 0xffff0000, v97
	v_lshlrev_b32_e32 v194, 16, v98
	v_and_b32_e32 v195, 0xffff0000, v98
	v_lshlrev_b32_e32 v196, 16, v99
	v_and_b32_e32 v197, 0xffff0000, v99
	v_lshlrev_b32_e32 v198, 16, v100
	v_and_b32_e32 v199, 0xffff0000, v100
	v_lshlrev_b32_e32 v200, 16, v101
	v_and_b32_e32 v201, 0xffff0000, v101
	v_lshlrev_b32_e32 v202, 16, v102
	v_and_b32_e32 v203, 0xffff0000, v102
	v_lshlrev_b32_e32 v204, 16, v103
	v_and_b32_e32 v205, 0xffff0000, v103
	v_pk_fma_f32 v[2:3], v[104:105], v[206:207], v[174:175]
	v_pk_fma_f32 v[4:5], v[106:107], v[208:209], v[176:177]
	v_pk_fma_f32 v[6:7], v[108:109], v[210:211], v[178:179]
	v_pk_fma_f32 v[8:9], v[110:111], v[212:213], v[180:181]
	v_pk_fma_f32 v[10:11], v[112:113], v[214:215], v[182:183]
	v_pk_fma_f32 v[12:13], v[114:115], v[216:217], v[184:185]
	v_pk_fma_f32 v[14:15], v[116:117], v[218:219], v[186:187]
	v_pk_fma_f32 v[16:17], v[118:119], v[220:221], v[188:189]
	v_pk_fma_f32 v[2:3], v[120:121], v[222:223], v[2:3]
	v_pk_fma_f32 v[4:5], v[122:123], v[224:225], v[4:5]
	v_pk_fma_f32 v[6:7], v[124:125], v[226:227], v[6:7]
	v_pk_fma_f32 v[8:9], v[126:127], v[228:229], v[8:9]
	v_pk_fma_f32 v[10:11], v[128:129], v[230:231], v[10:11]
	v_pk_fma_f32 v[12:13], v[130:131], v[232:233], v[12:13]
	v_pk_fma_f32 v[14:15], v[132:133], v[234:235], v[14:15]
	v_pk_fma_f32 v[16:17], v[134:135], v[236:237], v[16:17]
	v_pk_fma_f32 v[2:3], v[136:137], v[190:191], v[2:3]
	v_pk_fma_f32 v[4:5], v[138:139], v[192:193], v[4:5]
	v_pk_fma_f32 v[6:7], v[140:141], v[194:195], v[6:7]
	v_pk_fma_f32 v[8:9], v[142:143], v[196:197], v[8:9]
	v_pk_fma_f32 v[10:11], v[144:145], v[198:199], v[10:11]
	v_pk_fma_f32 v[12:13], v[146:147], v[200:201], v[12:13]
	v_pk_fma_f32 v[14:15], v[148:149], v[202:203], v[14:15]
	v_pk_fma_f32 v[16:17], v[150:151], v[204:205], v[16:17]
	v_mul_f32_e32 v18, 0xbfb8aa3b, v2
	v_mul_f32_e32 v19, 0xbfb8aa3b, v3
	v_mul_f32_e32 v20, 0xbfb8aa3b, v4
	v_mul_f32_e32 v21, 0xbfb8aa3b, v5
	v_mul_f32_e32 v22, 0xbfb8aa3b, v6
	v_mul_f32_e32 v23, 0xbfb8aa3b, v7
	v_mul_f32_e32 v24, 0xbfb8aa3b, v8
	v_mul_f32_e32 v25, 0xbfb8aa3b, v9
	v_exp_f32_e32 v18, v18
	v_exp_f32_e32 v19, v19
	v_exp_f32_e32 v20, v20
	v_exp_f32_e32 v21, v21
	v_exp_f32_e32 v22, v22
	v_exp_f32_e32 v23, v23
	v_exp_f32_e32 v24, v24
	v_exp_f32_e32 v25, v25
	v_add_f32_e32 v18, 1.0, v18
	v_add_f32_e32 v19, 1.0, v19
	v_add_f32_e32 v20, 1.0, v20
	v_add_f32_e32 v21, 1.0, v21
	v_add_f32_e32 v22, 1.0, v22
	v_add_f32_e32 v23, 1.0, v23
	v_add_f32_e32 v24, 1.0, v24
	v_add_f32_e32 v25, 1.0, v25
	v_rcp_f32_e32 v18, v18
	v_rcp_f32_e32 v19, v19
	v_rcp_f32_e32 v20, v20
	v_rcp_f32_e32 v21, v21
	v_rcp_f32_e32 v22, v22
	v_rcp_f32_e32 v23, v23
	v_rcp_f32_e32 v24, v24
	v_rcp_f32_e32 v25, v25
	v_mul_f32_e32 v18, v2, v18
	v_mul_f32_e32 v19, v3, v19
	v_mul_f32_e32 v20, v4, v20
	v_mul_f32_e32 v21, v5, v21
	v_mul_f32_e32 v22, v6, v22
	v_mul_f32_e32 v23, v7, v23
	v_mul_f32_e32 v24, v8, v24
	v_mul_f32_e32 v25, v9, v25
	v_mul_f32_e32 v18, v10, v18
	v_mul_f32_e32 v19, v11, v19
	v_mul_f32_e32 v20, v12, v20
	v_mul_f32_e32 v21, v13, v21
	v_mul_f32_e32 v22, v14, v22
	v_mul_f32_e32 v23, v15, v23
	v_mul_f32_e32 v24, v16, v24
	v_mul_f32_e32 v25, v17, v25
	v_cvt_pk_bf16_f32 v26, v18, v19
	v_cvt_pk_bf16_f32 v27, v20, v21
	v_cvt_pk_bf16_f32 v28, v22, v23
	v_cvt_pk_bf16_f32 v29, v24, v25
	global_store_dwordx4 v[162:163], v[26:29], off sc1
	v_lshl_add_u64 v[162:163], v[162:163], 0, v[30:31]
	v_add_u32_e32 v32, 0x80, v32
	v_add_u32_e32 v157, 0xba, v157
	v_cmp_lt_u32_e32 vcc, 0x2bf, v32
	v_subrev_u32_e32 v152, 0x2c0, v32
	s_nop 1
	v_cndmask_b32_e32 v32, v32, v152, vcc
	v_addc_co_u32_e32 v157, vcc, 0, v157, vcc
	v_mul_u32_u24_e32 v152, 0x58000, v157
	v_lshl_add_u32 v152, v32, 4, v152
	v_mov_b32_e32 v153, 0
	v_lshl_add_u64 v[158:159], s[36:37], 0, v[152:153]
	v_mul_u32_u24_e32 v152, 0x2c000, v157
	v_lshl_add_u32 v152, v32, 4, v152
	v_lshl_add_u64 v[162:163], s[38:39], 0, v[152:153]
	v_lshlrev_b32_e32 v33, 5, v32
	v_and_b32_e32 v152, 0x7f, v157
	v_cmp_eq_u32_e64 s[40:41], 0, v152
	v_mov_b32_e32 v152, 0x2c00
	v_lshl_add_u64 v[160:161], v[158:159], 0, v[152:153]
	global_load_dwordx4 v[104:107], v33, s[12:13]
	global_load_dwordx4 v[108:111], v33, s[12:13] offset:16
	global_load_dwordx4 v[112:115], v33, s[14:15]
	global_load_dwordx4 v[116:119], v33, s[14:15] offset:16
	global_load_dwordx4 v[120:123], v33, s[16:17]
	global_load_dwordx4 v[124:127], v33, s[16:17] offset:16
	global_load_dwordx4 v[128:131], v33, s[18:19]
	global_load_dwordx4 v[132:135], v33, s[18:19] offset:16
	global_load_dwordx4 v[136:139], v33, s[20:21]
	global_load_dwordx4 v[140:143], v33, s[20:21] offset:16
	global_load_dwordx4 v[144:147], v33, s[22:23]
	global_load_dwordx4 v[148:151], v33, s[22:23] offset:16
	global_load_dwordx4 v[174:177], v33, s[24:25]
	global_load_dwordx4 v[178:181], v33, s[24:25] offset:16
	global_load_dwordx4 v[182:185], v33, s[26:27]
	global_load_dwordx4 v[186:189], v33, s[26:27] offset:16
	v_mov_b32_e32 v152, 0xffffa800
	v_mov_b32_e32 v153, -1
	v_lshl_add_u64 v[154:155], v[158:159], 0, v[152:153]
	global_load_dwordx4 v[238:241], v[154:155], off
	v_lshl_add_u64 v[154:155], v[154:155], 0, v[152:153]
	global_load_dwordx4 v[246:249], v[154:155], off
	v_lshl_add_u64 v[154:155], v[160:161], 0, v[152:153]
	global_load_dwordx4 v[242:245], v[154:155], off
	v_lshl_add_u64 v[154:155], v[154:155], 0, v[152:153]
	global_load_dwordx4 v[250:253], v[154:155], off
	global_load_dwordx4 v[36:39], v[158:159], off
	global_load_dwordx4 v[40:43], v[160:161], off
	v_lshl_add_u64 v[158:159], v[158:159], 0, v[164:165]
	v_lshl_add_u64 v[160:161], v[160:161], 0, v[164:165]
	global_load_dwordx4 v[44:47], v[158:159], off
	global_load_dwordx4 v[48:51], v[160:161], off
	v_lshl_add_u64 v[158:159], v[158:159], 0, v[164:165]
	v_lshl_add_u64 v[160:161], v[160:161], 0, v[164:165]
	global_load_dwordx4 v[52:55], v[158:159], off
	global_load_dwordx4 v[56:59], v[160:161], off
	v_lshl_add_u64 v[158:159], v[158:159], 0, v[164:165]
	v_lshl_add_u64 v[160:161], v[160:161], 0, v[164:165]
	global_load_dwordx4 v[60:63], v[158:159], off
	global_load_dwordx4 v[64:67], v[160:161], off
	v_lshl_add_u64 v[158:159], v[158:159], 0, v[164:165]
	v_lshl_add_u64 v[160:161], v[160:161], 0, v[164:165]
	global_load_dwordx4 v[68:71], v[158:159], off
	global_load_dwordx4 v[72:75], v[160:161], off
	v_lshl_add_u64 v[158:159], v[158:159], 0, v[164:165]
	v_lshl_add_u64 v[160:161], v[160:161], 0, v[164:165]
	global_load_dwordx4 v[76:79], v[158:159], off
	global_load_dwordx4 v[80:83], v[160:161], off
	v_lshl_add_u64 v[158:159], v[158:159], 0, v[164:165]
	v_lshl_add_u64 v[160:161], v[160:161], 0, v[164:165]
	global_load_dwordx4 v[88:91], v[158:159], off
	global_load_dwordx4 v[92:95], v[160:161], off
	v_lshl_add_u64 v[158:159], v[158:159], 0, v[164:165]
	v_lshl_add_u64 v[160:161], v[160:161], 0, v[164:165]
	global_load_dwordx4 v[96:99], v[158:159], off
	global_load_dwordx4 v[100:103], v[160:161], off
	v_lshl_add_u64 v[158:159], v[158:159], 0, v[164:165]
	v_lshl_add_u64 v[160:161], v[160:161], 0, v[164:165]
	s_waitcnt vmcnt(8)
	v_lshlrev_b32_e32 v222, 16, v238
	v_and_b32_e32 v223, 0xffff0000, v238
	v_lshlrev_b32_e32 v224, 16, v239
	v_and_b32_e32 v225, 0xffff0000, v239
	v_lshlrev_b32_e32 v226, 16, v240
	v_and_b32_e32 v227, 0xffff0000, v240
	v_lshlrev_b32_e32 v228, 16, v241
	v_and_b32_e32 v229, 0xffff0000, v241
	v_lshlrev_b32_e32 v206, 16, v246
	v_and_b32_e32 v207, 0xffff0000, v246
	v_lshlrev_b32_e32 v208, 16, v247
	v_and_b32_e32 v209, 0xffff0000, v247
	v_lshlrev_b32_e32 v210, 16, v248
	v_and_b32_e32 v211, 0xffff0000, v248
	v_lshlrev_b32_e32 v212, 16, v249
	v_and_b32_e32 v213, 0xffff0000, v249
	v_lshlrev_b32_e32 v230, 16, v242
	v_and_b32_e32 v231, 0xffff0000, v242
	v_lshlrev_b32_e32 v232, 16, v243
	v_and_b32_e32 v233, 0xffff0000, v243
	v_lshlrev_b32_e32 v234, 16, v244
	v_and_b32_e32 v235, 0xffff0000, v244
	v_lshlrev_b32_e32 v236, 16, v245
	v_and_b32_e32 v237, 0xffff0000, v245
	v_lshlrev_b32_e32 v214, 16, v250
	v_and_b32_e32 v215, 0xffff0000, v250
	v_lshlrev_b32_e32 v216, 16, v251
	v_and_b32_e32 v217, 0xffff0000, v251
	v_lshlrev_b32_e32 v218, 16, v252
	v_and_b32_e32 v219, 0xffff0000, v252
	v_lshlrev_b32_e32 v220, 16, v253
	v_and_b32_e32 v221, 0xffff0000, v253
	v_cndmask_b32_e64 v206, v206, 0, s[40:41]
	v_cndmask_b32_e64 v207, v207, 0, s[40:41]
	v_cndmask_b32_e64 v208, v208, 0, s[40:41]
	v_cndmask_b32_e64 v209, v209, 0, s[40:41]
	v_cndmask_b32_e64 v210, v210, 0, s[40:41]
	v_cndmask_b32_e64 v211, v211, 0, s[40:41]
	v_cndmask_b32_e64 v212, v212, 0, s[40:41]
	v_cndmask_b32_e64 v213, v213, 0, s[40:41]
	v_cndmask_b32_e64 v214, v214, 0, s[40:41]
	v_cndmask_b32_e64 v215, v215, 0, s[40:41]
	v_cndmask_b32_e64 v216, v216, 0, s[40:41]
	v_cndmask_b32_e64 v217, v217, 0, s[40:41]
	v_cndmask_b32_e64 v218, v218, 0, s[40:41]
	v_cndmask_b32_e64 v219, v219, 0, s[40:41]
	v_cndmask_b32_e64 v220, v220, 0, s[40:41]
	v_cndmask_b32_e64 v221, v221, 0, s[40:41]
	v_cndmask_b32_e64 v222, v222, 0, s[40:41]
	v_cndmask_b32_e64 v223, v223, 0, s[40:41]
	v_cndmask_b32_e64 v224, v224, 0, s[40:41]
	v_cndmask_b32_e64 v225, v225, 0, s[40:41]
	v_cndmask_b32_e64 v226, v226, 0, s[40:41]
	v_cndmask_b32_e64 v227, v227, 0, s[40:41]
	v_cndmask_b32_e64 v228, v228, 0, s[40:41]
	v_cndmask_b32_e64 v229, v229, 0, s[40:41]
	v_cndmask_b32_e64 v230, v230, 0, s[40:41]
	v_cndmask_b32_e64 v231, v231, 0, s[40:41]
	v_cndmask_b32_e64 v232, v232, 0, s[40:41]
	v_cndmask_b32_e64 v233, v233, 0, s[40:41]
	v_cndmask_b32_e64 v234, v234, 0, s[40:41]
	v_cndmask_b32_e64 v235, v235, 0, s[40:41]
	v_cndmask_b32_e64 v236, v236, 0, s[40:41]
	v_cndmask_b32_e64 v237, v237, 0, s[40:41]
	v_lshlrev_b32_e32 v190, 16, v36
	v_and_b32_e32 v191, 0xffff0000, v36
	v_lshlrev_b32_e32 v192, 16, v37
	v_and_b32_e32 v193, 0xffff0000, v37
	v_lshlrev_b32_e32 v194, 16, v38
	v_and_b32_e32 v195, 0xffff0000, v38
	v_lshlrev_b32_e32 v196, 16, v39
	v_and_b32_e32 v197, 0xffff0000, v39
	v_lshlrev_b32_e32 v198, 16, v40
	v_and_b32_e32 v199, 0xffff0000, v40
	v_lshlrev_b32_e32 v200, 16, v41
	v_and_b32_e32 v201, 0xffff0000, v41
	v_lshlrev_b32_e32 v202, 16, v42
	v_and_b32_e32 v203, 0xffff0000, v42
	v_lshlrev_b32_e32 v204, 16, v43
	v_and_b32_e32 v205, 0xffff0000, v43
	v_pk_fma_f32 v[2:3], v[104:105], v[206:207], v[174:175]
	v_pk_fma_f32 v[4:5], v[106:107], v[208:209], v[176:177]
	v_pk_fma_f32 v[6:7], v[108:109], v[210:211], v[178:179]
	v_pk_fma_f32 v[8:9], v[110:111], v[212:213], v[180:181]
	v_pk_fma_f32 v[10:11], v[112:113], v[214:215], v[182:183]
	v_pk_fma_f32 v[12:13], v[114:115], v[216:217], v[184:185]
	v_pk_fma_f32 v[14:15], v[116:117], v[218:219], v[186:187]
	v_pk_fma_f32 v[16:17], v[118:119], v[220:221], v[188:189]
	v_pk_fma_f32 v[2:3], v[120:121], v[222:223], v[2:3]
	v_pk_fma_f32 v[4:5], v[122:123], v[224:225], v[4:5]
	v_pk_fma_f32 v[6:7], v[124:125], v[226:227], v[6:7]
	v_pk_fma_f32 v[8:9], v[126:127], v[228:229], v[8:9]
	v_pk_fma_f32 v[10:11], v[128:129], v[230:231], v[10:11]
	v_pk_fma_f32 v[12:13], v[130:131], v[232:233], v[12:13]
	v_pk_fma_f32 v[14:15], v[132:133], v[234:235], v[14:15]
	v_pk_fma_f32 v[16:17], v[134:135], v[236:237], v[16:17]
	v_pk_fma_f32 v[2:3], v[136:137], v[190:191], v[2:3]
	v_pk_fma_f32 v[4:5], v[138:139], v[192:193], v[4:5]
	v_pk_fma_f32 v[6:7], v[140:141], v[194:195], v[6:7]
	v_pk_fma_f32 v[8:9], v[142:143], v[196:197], v[8:9]
	v_pk_fma_f32 v[10:11], v[144:145], v[198:199], v[10:11]
	v_pk_fma_f32 v[12:13], v[146:147], v[200:201], v[12:13]
	v_pk_fma_f32 v[14:15], v[148:149], v[202:203], v[14:15]
	v_pk_fma_f32 v[16:17], v[150:151], v[204:205], v[16:17]
	v_mul_f32_e32 v18, 0xbfb8aa3b, v2
	v_mul_f32_e32 v19, 0xbfb8aa3b, v3
	v_mul_f32_e32 v20, 0xbfb8aa3b, v4
	v_mul_f32_e32 v21, 0xbfb8aa3b, v5
	v_mul_f32_e32 v22, 0xbfb8aa3b, v6
	v_mul_f32_e32 v23, 0xbfb8aa3b, v7
	v_mul_f32_e32 v24, 0xbfb8aa3b, v8
	v_mul_f32_e32 v25, 0xbfb8aa3b, v9
	v_exp_f32_e32 v18, v18
	v_exp_f32_e32 v19, v19
	v_exp_f32_e32 v20, v20
	v_exp_f32_e32 v21, v21
	v_exp_f32_e32 v22, v22
	v_exp_f32_e32 v23, v23
	v_exp_f32_e32 v24, v24
	v_exp_f32_e32 v25, v25
	v_add_f32_e32 v18, 1.0, v18
	v_add_f32_e32 v19, 1.0, v19
	v_add_f32_e32 v20, 1.0, v20
	v_add_f32_e32 v21, 1.0, v21
	v_add_f32_e32 v22, 1.0, v22
	v_add_f32_e32 v23, 1.0, v23
	v_add_f32_e32 v24, 1.0, v24
	v_add_f32_e32 v25, 1.0, v25
	v_rcp_f32_e32 v18, v18
	v_rcp_f32_e32 v19, v19
	v_rcp_f32_e32 v20, v20
	v_rcp_f32_e32 v21, v21
	v_rcp_f32_e32 v22, v22
	v_rcp_f32_e32 v23, v23
	v_rcp_f32_e32 v24, v24
	v_rcp_f32_e32 v25, v25
	v_mul_f32_e32 v18, v2, v18
	v_mul_f32_e32 v19, v3, v19
	v_mul_f32_e32 v20, v4, v20
	v_mul_f32_e32 v21, v5, v21
	v_mul_f32_e32 v22, v6, v22
	v_mul_f32_e32 v23, v7, v23
	v_mul_f32_e32 v24, v8, v24
	v_mul_f32_e32 v25, v9, v25
	v_mul_f32_e32 v18, v10, v18
	v_mul_f32_e32 v19, v11, v19
	v_mul_f32_e32 v20, v12, v20
	v_mul_f32_e32 v21, v13, v21
	v_mul_f32_e32 v22, v14, v22
	v_mul_f32_e32 v23, v15, v23
	v_mul_f32_e32 v24, v16, v24
	v_mul_f32_e32 v25, v17, v25
	v_cvt_pk_bf16_f32 v26, v18, v19
	v_cvt_pk_bf16_f32 v27, v20, v21
	v_cvt_pk_bf16_f32 v28, v22, v23
	v_cvt_pk_bf16_f32 v29, v24, v25
	global_store_dwordx4 v[162:163], v[26:29], off sc1
	v_lshl_add_u64 v[162:163], v[162:163], 0, v[30:31]
	v_lshlrev_b32_e32 v206, 16, v44
	v_and_b32_e32 v207, 0xffff0000, v44
	v_lshlrev_b32_e32 v208, 16, v45
	v_and_b32_e32 v209, 0xffff0000, v45
	v_lshlrev_b32_e32 v210, 16, v46
	v_and_b32_e32 v211, 0xffff0000, v46
	v_lshlrev_b32_e32 v212, 16, v47
	v_and_b32_e32 v213, 0xffff0000, v47
	v_lshlrev_b32_e32 v214, 16, v48
	v_and_b32_e32 v215, 0xffff0000, v48
	v_lshlrev_b32_e32 v216, 16, v49
	v_and_b32_e32 v217, 0xffff0000, v49
	v_lshlrev_b32_e32 v218, 16, v50
	v_and_b32_e32 v219, 0xffff0000, v50
	v_lshlrev_b32_e32 v220, 16, v51
	v_and_b32_e32 v221, 0xffff0000, v51
	v_pk_fma_f32 v[2:3], v[104:105], v[222:223], v[174:175]
	v_pk_fma_f32 v[4:5], v[106:107], v[224:225], v[176:177]
	v_pk_fma_f32 v[6:7], v[108:109], v[226:227], v[178:179]
	v_pk_fma_f32 v[8:9], v[110:111], v[228:229], v[180:181]
	v_pk_fma_f32 v[10:11], v[112:113], v[230:231], v[182:183]
	v_pk_fma_f32 v[12:13], v[114:115], v[232:233], v[184:185]
	v_pk_fma_f32 v[14:15], v[116:117], v[234:235], v[186:187]
	v_pk_fma_f32 v[16:17], v[118:119], v[236:237], v[188:189]
	v_pk_fma_f32 v[2:3], v[120:121], v[190:191], v[2:3]
	v_pk_fma_f32 v[4:5], v[122:123], v[192:193], v[4:5]
	v_pk_fma_f32 v[6:7], v[124:125], v[194:195], v[6:7]
	v_pk_fma_f32 v[8:9], v[126:127], v[196:197], v[8:9]
	v_pk_fma_f32 v[10:11], v[128:129], v[198:199], v[10:11]
	v_pk_fma_f32 v[12:13], v[130:131], v[200:201], v[12:13]
	v_pk_fma_f32 v[14:15], v[132:133], v[202:203], v[14:15]
	v_pk_fma_f32 v[16:17], v[134:135], v[204:205], v[16:17]
	v_pk_fma_f32 v[2:3], v[136:137], v[206:207], v[2:3]
	v_pk_fma_f32 v[4:5], v[138:139], v[208:209], v[4:5]
	v_pk_fma_f32 v[6:7], v[140:141], v[210:211], v[6:7]
	v_pk_fma_f32 v[8:9], v[142:143], v[212:213], v[8:9]
	v_pk_fma_f32 v[10:11], v[144:145], v[214:215], v[10:11]
	v_pk_fma_f32 v[12:13], v[146:147], v[216:217], v[12:13]
	v_pk_fma_f32 v[14:15], v[148:149], v[218:219], v[14:15]
	v_pk_fma_f32 v[16:17], v[150:151], v[220:221], v[16:17]
	v_mul_f32_e32 v18, 0xbfb8aa3b, v2
	v_mul_f32_e32 v19, 0xbfb8aa3b, v3
	v_mul_f32_e32 v20, 0xbfb8aa3b, v4
	v_mul_f32_e32 v21, 0xbfb8aa3b, v5
	v_mul_f32_e32 v22, 0xbfb8aa3b, v6
	v_mul_f32_e32 v23, 0xbfb8aa3b, v7
	v_mul_f32_e32 v24, 0xbfb8aa3b, v8
	v_mul_f32_e32 v25, 0xbfb8aa3b, v9
	v_exp_f32_e32 v18, v18
	v_exp_f32_e32 v19, v19
	v_exp_f32_e32 v20, v20
	v_exp_f32_e32 v21, v21
	v_exp_f32_e32 v22, v22
	v_exp_f32_e32 v23, v23
	v_exp_f32_e32 v24, v24
	v_exp_f32_e32 v25, v25
	v_add_f32_e32 v18, 1.0, v18
	v_add_f32_e32 v19, 1.0, v19
	v_add_f32_e32 v20, 1.0, v20
	v_add_f32_e32 v21, 1.0, v21
	v_add_f32_e32 v22, 1.0, v22
	v_add_f32_e32 v23, 1.0, v23
	v_add_f32_e32 v24, 1.0, v24
	v_add_f32_e32 v25, 1.0, v25
	v_rcp_f32_e32 v18, v18
	v_rcp_f32_e32 v19, v19
	v_rcp_f32_e32 v20, v20
	v_rcp_f32_e32 v21, v21
	v_rcp_f32_e32 v22, v22
	v_rcp_f32_e32 v23, v23
	v_rcp_f32_e32 v24, v24
	v_rcp_f32_e32 v25, v25
	v_mul_f32_e32 v18, v2, v18
	v_mul_f32_e32 v19, v3, v19
	v_mul_f32_e32 v20, v4, v20
	v_mul_f32_e32 v21, v5, v21
	v_mul_f32_e32 v22, v6, v22
	v_mul_f32_e32 v23, v7, v23
	v_mul_f32_e32 v24, v8, v24
	v_mul_f32_e32 v25, v9, v25
	v_mul_f32_e32 v18, v10, v18
	v_mul_f32_e32 v19, v11, v19
	v_mul_f32_e32 v20, v12, v20
	v_mul_f32_e32 v21, v13, v21
	v_mul_f32_e32 v22, v14, v22
	v_mul_f32_e32 v23, v15, v23
	v_mul_f32_e32 v24, v16, v24
	v_mul_f32_e32 v25, v17, v25
	v_cvt_pk_bf16_f32 v26, v18, v19
	v_cvt_pk_bf16_f32 v27, v20, v21
	v_cvt_pk_bf16_f32 v28, v22, v23
	v_cvt_pk_bf16_f32 v29, v24, v25
	global_store_dwordx4 v[162:163], v[26:29], off sc1
	v_lshl_add_u64 v[162:163], v[162:163], 0, v[30:31]
	v_lshlrev_b32_e32 v222, 16, v52
	v_and_b32_e32 v223, 0xffff0000, v52
	v_lshlrev_b32_e32 v224, 16, v53
	v_and_b32_e32 v225, 0xffff0000, v53
	v_lshlrev_b32_e32 v226, 16, v54
	v_and_b32_e32 v227, 0xffff0000, v54
	v_lshlrev_b32_e32 v228, 16, v55
	v_and_b32_e32 v229, 0xffff0000, v55
	v_lshlrev_b32_e32 v230, 16, v56
	v_and_b32_e32 v231, 0xffff0000, v56
	v_lshlrev_b32_e32 v232, 16, v57
	v_and_b32_e32 v233, 0xffff0000, v57
	v_lshlrev_b32_e32 v234, 16, v58
	v_and_b32_e32 v235, 0xffff0000, v58
	v_lshlrev_b32_e32 v236, 16, v59
	v_and_b32_e32 v237, 0xffff0000, v59
	v_pk_fma_f32 v[2:3], v[104:105], v[190:191], v[174:175]
	v_pk_fma_f32 v[4:5], v[106:107], v[192:193], v[176:177]
	v_pk_fma_f32 v[6:7], v[108:109], v[194:195], v[178:179]
	v_pk_fma_f32 v[8:9], v[110:111], v[196:197], v[180:181]
	v_pk_fma_f32 v[10:11], v[112:113], v[198:199], v[182:183]
	v_pk_fma_f32 v[12:13], v[114:115], v[200:201], v[184:185]
	v_pk_fma_f32 v[14:15], v[116:117], v[202:203], v[186:187]
	v_pk_fma_f32 v[16:17], v[118:119], v[204:205], v[188:189]
	v_pk_fma_f32 v[2:3], v[120:121], v[206:207], v[2:3]
	v_pk_fma_f32 v[4:5], v[122:123], v[208:209], v[4:5]
	v_pk_fma_f32 v[6:7], v[124:125], v[210:211], v[6:7]
	v_pk_fma_f32 v[8:9], v[126:127], v[212:213], v[8:9]
	v_pk_fma_f32 v[10:11], v[128:129], v[214:215], v[10:11]
	v_pk_fma_f32 v[12:13], v[130:131], v[216:217], v[12:13]
	v_pk_fma_f32 v[14:15], v[132:133], v[218:219], v[14:15]
	v_pk_fma_f32 v[16:17], v[134:135], v[220:221], v[16:17]
	v_pk_fma_f32 v[2:3], v[136:137], v[222:223], v[2:3]
	v_pk_fma_f32 v[4:5], v[138:139], v[224:225], v[4:5]
	v_pk_fma_f32 v[6:7], v[140:141], v[226:227], v[6:7]
	v_pk_fma_f32 v[8:9], v[142:143], v[228:229], v[8:9]
	v_pk_fma_f32 v[10:11], v[144:145], v[230:231], v[10:11]
	v_pk_fma_f32 v[12:13], v[146:147], v[232:233], v[12:13]
	v_pk_fma_f32 v[14:15], v[148:149], v[234:235], v[14:15]
	v_pk_fma_f32 v[16:17], v[150:151], v[236:237], v[16:17]
	v_mul_f32_e32 v18, 0xbfb8aa3b, v2
	v_mul_f32_e32 v19, 0xbfb8aa3b, v3
	v_mul_f32_e32 v20, 0xbfb8aa3b, v4
	v_mul_f32_e32 v21, 0xbfb8aa3b, v5
	v_mul_f32_e32 v22, 0xbfb8aa3b, v6
	v_mul_f32_e32 v23, 0xbfb8aa3b, v7
	v_mul_f32_e32 v24, 0xbfb8aa3b, v8
	v_mul_f32_e32 v25, 0xbfb8aa3b, v9
	v_exp_f32_e32 v18, v18
	v_exp_f32_e32 v19, v19
	v_exp_f32_e32 v20, v20
	v_exp_f32_e32 v21, v21
	v_exp_f32_e32 v22, v22
	v_exp_f32_e32 v23, v23
	v_exp_f32_e32 v24, v24
	v_exp_f32_e32 v25, v25
	v_add_f32_e32 v18, 1.0, v18
	v_add_f32_e32 v19, 1.0, v19
	v_add_f32_e32 v20, 1.0, v20
	v_add_f32_e32 v21, 1.0, v21
	v_add_f32_e32 v22, 1.0, v22
	v_add_f32_e32 v23, 1.0, v23
	v_add_f32_e32 v24, 1.0, v24
	v_add_f32_e32 v25, 1.0, v25
	v_rcp_f32_e32 v18, v18
	v_rcp_f32_e32 v19, v19
	v_rcp_f32_e32 v20, v20
	v_rcp_f32_e32 v21, v21
	v_rcp_f32_e32 v22, v22
	v_rcp_f32_e32 v23, v23
	v_rcp_f32_e32 v24, v24
	v_rcp_f32_e32 v25, v25
	v_mul_f32_e32 v18, v2, v18
	v_mul_f32_e32 v19, v3, v19
	v_mul_f32_e32 v20, v4, v20
	v_mul_f32_e32 v21, v5, v21
	v_mul_f32_e32 v22, v6, v22
	v_mul_f32_e32 v23, v7, v23
	v_mul_f32_e32 v24, v8, v24
	v_mul_f32_e32 v25, v9, v25
	v_mul_f32_e32 v18, v10, v18
	v_mul_f32_e32 v19, v11, v19
	v_mul_f32_e32 v20, v12, v20
	v_mul_f32_e32 v21, v13, v21
	v_mul_f32_e32 v22, v14, v22
	v_mul_f32_e32 v23, v15, v23
	v_mul_f32_e32 v24, v16, v24
	v_mul_f32_e32 v25, v17, v25
	v_cvt_pk_bf16_f32 v26, v18, v19
	v_cvt_pk_bf16_f32 v27, v20, v21
	v_cvt_pk_bf16_f32 v28, v22, v23
	v_cvt_pk_bf16_f32 v29, v24, v25
	global_store_dwordx4 v[162:163], v[26:29], off sc1
	v_lshl_add_u64 v[162:163], v[162:163], 0, v[30:31]
	v_lshlrev_b32_e32 v190, 16, v60
	v_and_b32_e32 v191, 0xffff0000, v60
	v_lshlrev_b32_e32 v192, 16, v61
	v_and_b32_e32 v193, 0xffff0000, v61
	v_lshlrev_b32_e32 v194, 16, v62
	v_and_b32_e32 v195, 0xffff0000, v62
	v_lshlrev_b32_e32 v196, 16, v63
	v_and_b32_e32 v197, 0xffff0000, v63
	v_lshlrev_b32_e32 v198, 16, v64
	v_and_b32_e32 v199, 0xffff0000, v64
	v_lshlrev_b32_e32 v200, 16, v65
	v_and_b32_e32 v201, 0xffff0000, v65
	v_lshlrev_b32_e32 v202, 16, v66
	v_and_b32_e32 v203, 0xffff0000, v66
	v_lshlrev_b32_e32 v204, 16, v67
	v_and_b32_e32 v205, 0xffff0000, v67
	v_pk_fma_f32 v[2:3], v[104:105], v[206:207], v[174:175]
	v_pk_fma_f32 v[4:5], v[106:107], v[208:209], v[176:177]
	v_pk_fma_f32 v[6:7], v[108:109], v[210:211], v[178:179]
	v_pk_fma_f32 v[8:9], v[110:111], v[212:213], v[180:181]
	v_pk_fma_f32 v[10:11], v[112:113], v[214:215], v[182:183]
	v_pk_fma_f32 v[12:13], v[114:115], v[216:217], v[184:185]
	v_pk_fma_f32 v[14:15], v[116:117], v[218:219], v[186:187]
	v_pk_fma_f32 v[16:17], v[118:119], v[220:221], v[188:189]
	v_pk_fma_f32 v[2:3], v[120:121], v[222:223], v[2:3]
	v_pk_fma_f32 v[4:5], v[122:123], v[224:225], v[4:5]
	v_pk_fma_f32 v[6:7], v[124:125], v[226:227], v[6:7]
	v_pk_fma_f32 v[8:9], v[126:127], v[228:229], v[8:9]
	v_pk_fma_f32 v[10:11], v[128:129], v[230:231], v[10:11]
	v_pk_fma_f32 v[12:13], v[130:131], v[232:233], v[12:13]
	v_pk_fma_f32 v[14:15], v[132:133], v[234:235], v[14:15]
	v_pk_fma_f32 v[16:17], v[134:135], v[236:237], v[16:17]
	v_pk_fma_f32 v[2:3], v[136:137], v[190:191], v[2:3]
	v_pk_fma_f32 v[4:5], v[138:139], v[192:193], v[4:5]
	v_pk_fma_f32 v[6:7], v[140:141], v[194:195], v[6:7]
	v_pk_fma_f32 v[8:9], v[142:143], v[196:197], v[8:9]
	v_pk_fma_f32 v[10:11], v[144:145], v[198:199], v[10:11]
	v_pk_fma_f32 v[12:13], v[146:147], v[200:201], v[12:13]
	v_pk_fma_f32 v[14:15], v[148:149], v[202:203], v[14:15]
	v_pk_fma_f32 v[16:17], v[150:151], v[204:205], v[16:17]
	v_mul_f32_e32 v18, 0xbfb8aa3b, v2
	v_mul_f32_e32 v19, 0xbfb8aa3b, v3
	v_mul_f32_e32 v20, 0xbfb8aa3b, v4
	v_mul_f32_e32 v21, 0xbfb8aa3b, v5
	v_mul_f32_e32 v22, 0xbfb8aa3b, v6
	v_mul_f32_e32 v23, 0xbfb8aa3b, v7
	v_mul_f32_e32 v24, 0xbfb8aa3b, v8
	v_mul_f32_e32 v25, 0xbfb8aa3b, v9
	v_exp_f32_e32 v18, v18
	v_exp_f32_e32 v19, v19
	v_exp_f32_e32 v20, v20
	v_exp_f32_e32 v21, v21
	v_exp_f32_e32 v22, v22
	v_exp_f32_e32 v23, v23
	v_exp_f32_e32 v24, v24
	v_exp_f32_e32 v25, v25
	v_add_f32_e32 v18, 1.0, v18
	v_add_f32_e32 v19, 1.0, v19
	v_add_f32_e32 v20, 1.0, v20
	v_add_f32_e32 v21, 1.0, v21
	v_add_f32_e32 v22, 1.0, v22
	v_add_f32_e32 v23, 1.0, v23
	v_add_f32_e32 v24, 1.0, v24
	v_add_f32_e32 v25, 1.0, v25
	v_rcp_f32_e32 v18, v18
	v_rcp_f32_e32 v19, v19
	v_rcp_f32_e32 v20, v20
	v_rcp_f32_e32 v21, v21
	v_rcp_f32_e32 v22, v22
	v_rcp_f32_e32 v23, v23
	v_rcp_f32_e32 v24, v24
	v_rcp_f32_e32 v25, v25
	v_mul_f32_e32 v18, v2, v18
	v_mul_f32_e32 v19, v3, v19
	v_mul_f32_e32 v20, v4, v20
	v_mul_f32_e32 v21, v5, v21
	v_mul_f32_e32 v22, v6, v22
	v_mul_f32_e32 v23, v7, v23
	v_mul_f32_e32 v24, v8, v24
	v_mul_f32_e32 v25, v9, v25
	v_mul_f32_e32 v18, v10, v18
	v_mul_f32_e32 v19, v11, v19
	v_mul_f32_e32 v20, v12, v20
	v_mul_f32_e32 v21, v13, v21
	v_mul_f32_e32 v22, v14, v22
	v_mul_f32_e32 v23, v15, v23
	v_mul_f32_e32 v24, v16, v24
	v_mul_f32_e32 v25, v17, v25
	v_cvt_pk_bf16_f32 v26, v18, v19
	v_cvt_pk_bf16_f32 v27, v20, v21
	v_cvt_pk_bf16_f32 v28, v22, v23
	v_cvt_pk_bf16_f32 v29, v24, v25
	global_store_dwordx4 v[162:163], v[26:29], off sc1
	v_lshl_add_u64 v[162:163], v[162:163], 0, v[30:31]
	global_load_dwordx4 v[36:39], v[158:159], off
	global_load_dwordx4 v[40:43], v[160:161], off
	v_lshl_add_u64 v[158:159], v[158:159], 0, v[164:165]
	v_lshl_add_u64 v[160:161], v[160:161], 0, v[164:165]
	global_load_dwordx4 v[44:47], v[158:159], off
	global_load_dwordx4 v[48:51], v[160:161], off
	v_lshl_add_u64 v[158:159], v[158:159], 0, v[164:165]
	v_lshl_add_u64 v[160:161], v[160:161], 0, v[164:165]
	global_load_dwordx4 v[52:55], v[158:159], off
	global_load_dwordx4 v[56:59], v[160:161], off
	v_lshl_add_u64 v[158:159], v[158:159], 0, v[164:165]
	v_lshl_add_u64 v[160:161], v[160:161], 0, v[164:165]
	global_load_dwordx4 v[60:63], v[158:159], off
	global_load_dwordx4 v[64:67], v[160:161], off
	v_lshl_add_u64 v[158:159], v[158:159], 0, v[164:165]
	v_lshl_add_u64 v[160:161], v[160:161], 0, v[164:165]
	s_waitcnt vmcnt(12)
	v_lshlrev_b32_e32 v206, 16, v68
	v_and_b32_e32 v207, 0xffff0000, v68
	v_lshlrev_b32_e32 v208, 16, v69
	v_and_b32_e32 v209, 0xffff0000, v69
	v_lshlrev_b32_e32 v210, 16, v70
	v_and_b32_e32 v211, 0xffff0000, v70
	v_lshlrev_b32_e32 v212, 16, v71
	v_and_b32_e32 v213, 0xffff0000, v71
	v_lshlrev_b32_e32 v214, 16, v72
	v_and_b32_e32 v215, 0xffff0000, v72
	v_lshlrev_b32_e32 v216, 16, v73
	v_and_b32_e32 v217, 0xffff0000, v73
	v_lshlrev_b32_e32 v218, 16, v74
	v_and_b32_e32 v219, 0xffff0000, v74
	v_lshlrev_b32_e32 v220, 16, v75
	v_and_b32_e32 v221, 0xffff0000, v75
	v_pk_fma_f32 v[2:3], v[104:105], v[222:223], v[174:175]
	v_pk_fma_f32 v[4:5], v[106:107], v[224:225], v[176:177]
	v_pk_fma_f32 v[6:7], v[108:109], v[226:227], v[178:179]
	v_pk_fma_f32 v[8:9], v[110:111], v[228:229], v[180:181]
	v_pk_fma_f32 v[10:11], v[112:113], v[230:231], v[182:183]
	v_pk_fma_f32 v[12:13], v[114:115], v[232:233], v[184:185]
	v_pk_fma_f32 v[14:15], v[116:117], v[234:235], v[186:187]
	v_pk_fma_f32 v[16:17], v[118:119], v[236:237], v[188:189]
	v_pk_fma_f32 v[2:3], v[120:121], v[190:191], v[2:3]
	v_pk_fma_f32 v[4:5], v[122:123], v[192:193], v[4:5]
	v_pk_fma_f32 v[6:7], v[124:125], v[194:195], v[6:7]
	v_pk_fma_f32 v[8:9], v[126:127], v[196:197], v[8:9]
	v_pk_fma_f32 v[10:11], v[128:129], v[198:199], v[10:11]
	v_pk_fma_f32 v[12:13], v[130:131], v[200:201], v[12:13]
	v_pk_fma_f32 v[14:15], v[132:133], v[202:203], v[14:15]
	v_pk_fma_f32 v[16:17], v[134:135], v[204:205], v[16:17]
	v_pk_fma_f32 v[2:3], v[136:137], v[206:207], v[2:3]
	v_pk_fma_f32 v[4:5], v[138:139], v[208:209], v[4:5]
	v_pk_fma_f32 v[6:7], v[140:141], v[210:211], v[6:7]
	v_pk_fma_f32 v[8:9], v[142:143], v[212:213], v[8:9]
	v_pk_fma_f32 v[10:11], v[144:145], v[214:215], v[10:11]
	v_pk_fma_f32 v[12:13], v[146:147], v[216:217], v[12:13]
	v_pk_fma_f32 v[14:15], v[148:149], v[218:219], v[14:15]
	v_pk_fma_f32 v[16:17], v[150:151], v[220:221], v[16:17]
	v_mul_f32_e32 v18, 0xbfb8aa3b, v2
	v_mul_f32_e32 v19, 0xbfb8aa3b, v3
	v_mul_f32_e32 v20, 0xbfb8aa3b, v4
	v_mul_f32_e32 v21, 0xbfb8aa3b, v5
	v_mul_f32_e32 v22, 0xbfb8aa3b, v6
	v_mul_f32_e32 v23, 0xbfb8aa3b, v7
	v_mul_f32_e32 v24, 0xbfb8aa3b, v8
	v_mul_f32_e32 v25, 0xbfb8aa3b, v9
	v_exp_f32_e32 v18, v18
	v_exp_f32_e32 v19, v19
	v_exp_f32_e32 v20, v20
	v_exp_f32_e32 v21, v21
	v_exp_f32_e32 v22, v22
	v_exp_f32_e32 v23, v23
	v_exp_f32_e32 v24, v24
	v_exp_f32_e32 v25, v25
	v_add_f32_e32 v18, 1.0, v18
	v_add_f32_e32 v19, 1.0, v19
	v_add_f32_e32 v20, 1.0, v20
	v_add_f32_e32 v21, 1.0, v21
	v_add_f32_e32 v22, 1.0, v22
	v_add_f32_e32 v23, 1.0, v23
	v_add_f32_e32 v24, 1.0, v24
	v_add_f32_e32 v25, 1.0, v25
	v_rcp_f32_e32 v18, v18
	v_rcp_f32_e32 v19, v19
	v_rcp_f32_e32 v20, v20
	v_rcp_f32_e32 v21, v21
	v_rcp_f32_e32 v22, v22
	v_rcp_f32_e32 v23, v23
	v_rcp_f32_e32 v24, v24
	v_rcp_f32_e32 v25, v25
	v_mul_f32_e32 v18, v2, v18
	v_mul_f32_e32 v19, v3, v19
	v_mul_f32_e32 v20, v4, v20
	v_mul_f32_e32 v21, v5, v21
	v_mul_f32_e32 v22, v6, v22
	v_mul_f32_e32 v23, v7, v23
	v_mul_f32_e32 v24, v8, v24
	v_mul_f32_e32 v25, v9, v25
	v_mul_f32_e32 v18, v10, v18
	v_mul_f32_e32 v19, v11, v19
	v_mul_f32_e32 v20, v12, v20
	v_mul_f32_e32 v21, v13, v21
	v_mul_f32_e32 v22, v14, v22
	v_mul_f32_e32 v23, v15, v23
	v_mul_f32_e32 v24, v16, v24
	v_mul_f32_e32 v25, v17, v25
	v_cvt_pk_bf16_f32 v26, v18, v19
	v_cvt_pk_bf16_f32 v27, v20, v21
	v_cvt_pk_bf16_f32 v28, v22, v23
	v_cvt_pk_bf16_f32 v29, v24, v25
	global_store_dwordx4 v[162:163], v[26:29], off sc1
	v_lshl_add_u64 v[162:163], v[162:163], 0, v[30:31]
	v_lshlrev_b32_e32 v222, 16, v76
	v_and_b32_e32 v223, 0xffff0000, v76
	v_lshlrev_b32_e32 v224, 16, v77
	v_and_b32_e32 v225, 0xffff0000, v77
	v_lshlrev_b32_e32 v226, 16, v78
	v_and_b32_e32 v227, 0xffff0000, v78
	v_lshlrev_b32_e32 v228, 16, v79
	v_and_b32_e32 v229, 0xffff0000, v79
	v_lshlrev_b32_e32 v230, 16, v80
	v_and_b32_e32 v231, 0xffff0000, v80
	v_lshlrev_b32_e32 v232, 16, v81
	v_and_b32_e32 v233, 0xffff0000, v81
	v_lshlrev_b32_e32 v234, 16, v82
	v_and_b32_e32 v235, 0xffff0000, v82
	v_lshlrev_b32_e32 v236, 16, v83
	v_and_b32_e32 v237, 0xffff0000, v83
	v_pk_fma_f32 v[2:3], v[104:105], v[190:191], v[174:175]
	v_pk_fma_f32 v[4:5], v[106:107], v[192:193], v[176:177]
	v_pk_fma_f32 v[6:7], v[108:109], v[194:195], v[178:179]
	v_pk_fma_f32 v[8:9], v[110:111], v[196:197], v[180:181]
	v_pk_fma_f32 v[10:11], v[112:113], v[198:199], v[182:183]
	v_pk_fma_f32 v[12:13], v[114:115], v[200:201], v[184:185]
	v_pk_fma_f32 v[14:15], v[116:117], v[202:203], v[186:187]
	v_pk_fma_f32 v[16:17], v[118:119], v[204:205], v[188:189]
	v_pk_fma_f32 v[2:3], v[120:121], v[206:207], v[2:3]
	v_pk_fma_f32 v[4:5], v[122:123], v[208:209], v[4:5]
	v_pk_fma_f32 v[6:7], v[124:125], v[210:211], v[6:7]
	v_pk_fma_f32 v[8:9], v[126:127], v[212:213], v[8:9]
	v_pk_fma_f32 v[10:11], v[128:129], v[214:215], v[10:11]
	v_pk_fma_f32 v[12:13], v[130:131], v[216:217], v[12:13]
	v_pk_fma_f32 v[14:15], v[132:133], v[218:219], v[14:15]
	v_pk_fma_f32 v[16:17], v[134:135], v[220:221], v[16:17]
	v_pk_fma_f32 v[2:3], v[136:137], v[222:223], v[2:3]
	v_pk_fma_f32 v[4:5], v[138:139], v[224:225], v[4:5]
	v_pk_fma_f32 v[6:7], v[140:141], v[226:227], v[6:7]
	v_pk_fma_f32 v[8:9], v[142:143], v[228:229], v[8:9]
	v_pk_fma_f32 v[10:11], v[144:145], v[230:231], v[10:11]
	v_pk_fma_f32 v[12:13], v[146:147], v[232:233], v[12:13]
	v_pk_fma_f32 v[14:15], v[148:149], v[234:235], v[14:15]
	v_pk_fma_f32 v[16:17], v[150:151], v[236:237], v[16:17]
	v_mul_f32_e32 v18, 0xbfb8aa3b, v2
	v_mul_f32_e32 v19, 0xbfb8aa3b, v3
	v_mul_f32_e32 v20, 0xbfb8aa3b, v4
	v_mul_f32_e32 v21, 0xbfb8aa3b, v5
	v_mul_f32_e32 v22, 0xbfb8aa3b, v6
	v_mul_f32_e32 v23, 0xbfb8aa3b, v7
	v_mul_f32_e32 v24, 0xbfb8aa3b, v8
	v_mul_f32_e32 v25, 0xbfb8aa3b, v9
	v_exp_f32_e32 v18, v18
	v_exp_f32_e32 v19, v19
	v_exp_f32_e32 v20, v20
	v_exp_f32_e32 v21, v21
	v_exp_f32_e32 v22, v22
	v_exp_f32_e32 v23, v23
	v_exp_f32_e32 v24, v24
	v_exp_f32_e32 v25, v25
	v_add_f32_e32 v18, 1.0, v18
	v_add_f32_e32 v19, 1.0, v19
	v_add_f32_e32 v20, 1.0, v20
	v_add_f32_e32 v21, 1.0, v21
	v_add_f32_e32 v22, 1.0, v22
	v_add_f32_e32 v23, 1.0, v23
	v_add_f32_e32 v24, 1.0, v24
	v_add_f32_e32 v25, 1.0, v25
	v_rcp_f32_e32 v18, v18
	v_rcp_f32_e32 v19, v19
	v_rcp_f32_e32 v20, v20
	v_rcp_f32_e32 v21, v21
	v_rcp_f32_e32 v22, v22
	v_rcp_f32_e32 v23, v23
	v_rcp_f32_e32 v24, v24
	v_rcp_f32_e32 v25, v25
	v_mul_f32_e32 v18, v2, v18
	v_mul_f32_e32 v19, v3, v19
	v_mul_f32_e32 v20, v4, v20
	v_mul_f32_e32 v21, v5, v21
	v_mul_f32_e32 v22, v6, v22
	v_mul_f32_e32 v23, v7, v23
	v_mul_f32_e32 v24, v8, v24
	v_mul_f32_e32 v25, v9, v25
	v_mul_f32_e32 v18, v10, v18
	v_mul_f32_e32 v19, v11, v19
	v_mul_f32_e32 v20, v12, v20
	v_mul_f32_e32 v21, v13, v21
	v_mul_f32_e32 v22, v14, v22
	v_mul_f32_e32 v23, v15, v23
	v_mul_f32_e32 v24, v16, v24
	v_mul_f32_e32 v25, v17, v25
	v_cvt_pk_bf16_f32 v26, v18, v19
	v_cvt_pk_bf16_f32 v27, v20, v21
	v_cvt_pk_bf16_f32 v28, v22, v23
	v_cvt_pk_bf16_f32 v29, v24, v25
	global_store_dwordx4 v[162:163], v[26:29], off sc1
	v_lshl_add_u64 v[162:163], v[162:163], 0, v[30:31]
	v_lshlrev_b32_e32 v190, 16, v88
	v_and_b32_e32 v191, 0xffff0000, v88
	v_lshlrev_b32_e32 v192, 16, v89
	v_and_b32_e32 v193, 0xffff0000, v89
	v_lshlrev_b32_e32 v194, 16, v90
	v_and_b32_e32 v195, 0xffff0000, v90
	v_lshlrev_b32_e32 v196, 16, v91
	v_and_b32_e32 v197, 0xffff0000, v91
	v_lshlrev_b32_e32 v198, 16, v92
	v_and_b32_e32 v199, 0xffff0000, v92
	v_lshlrev_b32_e32 v200, 16, v93
	v_and_b32_e32 v201, 0xffff0000, v93
	v_lshlrev_b32_e32 v202, 16, v94
	v_and_b32_e32 v203, 0xffff0000, v94
	v_lshlrev_b32_e32 v204, 16, v95
	v_and_b32_e32 v205, 0xffff0000, v95
	v_pk_fma_f32 v[2:3], v[104:105], v[206:207], v[174:175]
	v_pk_fma_f32 v[4:5], v[106:107], v[208:209], v[176:177]
	v_pk_fma_f32 v[6:7], v[108:109], v[210:211], v[178:179]
	v_pk_fma_f32 v[8:9], v[110:111], v[212:213], v[180:181]
	v_pk_fma_f32 v[10:11], v[112:113], v[214:215], v[182:183]
	v_pk_fma_f32 v[12:13], v[114:115], v[216:217], v[184:185]
	v_pk_fma_f32 v[14:15], v[116:117], v[218:219], v[186:187]
	v_pk_fma_f32 v[16:17], v[118:119], v[220:221], v[188:189]
	v_pk_fma_f32 v[2:3], v[120:121], v[222:223], v[2:3]
	v_pk_fma_f32 v[4:5], v[122:123], v[224:225], v[4:5]
	v_pk_fma_f32 v[6:7], v[124:125], v[226:227], v[6:7]
	v_pk_fma_f32 v[8:9], v[126:127], v[228:229], v[8:9]
	v_pk_fma_f32 v[10:11], v[128:129], v[230:231], v[10:11]
	v_pk_fma_f32 v[12:13], v[130:131], v[232:233], v[12:13]
	v_pk_fma_f32 v[14:15], v[132:133], v[234:235], v[14:15]
	v_pk_fma_f32 v[16:17], v[134:135], v[236:237], v[16:17]
	v_pk_fma_f32 v[2:3], v[136:137], v[190:191], v[2:3]
	v_pk_fma_f32 v[4:5], v[138:139], v[192:193], v[4:5]
	v_pk_fma_f32 v[6:7], v[140:141], v[194:195], v[6:7]
	v_pk_fma_f32 v[8:9], v[142:143], v[196:197], v[8:9]
	v_pk_fma_f32 v[10:11], v[144:145], v[198:199], v[10:11]
	v_pk_fma_f32 v[12:13], v[146:147], v[200:201], v[12:13]
	v_pk_fma_f32 v[14:15], v[148:149], v[202:203], v[14:15]
	v_pk_fma_f32 v[16:17], v[150:151], v[204:205], v[16:17]
	v_mul_f32_e32 v18, 0xbfb8aa3b, v2
	v_mul_f32_e32 v19, 0xbfb8aa3b, v3
	v_mul_f32_e32 v20, 0xbfb8aa3b, v4
	v_mul_f32_e32 v21, 0xbfb8aa3b, v5
	v_mul_f32_e32 v22, 0xbfb8aa3b, v6
	v_mul_f32_e32 v23, 0xbfb8aa3b, v7
	v_mul_f32_e32 v24, 0xbfb8aa3b, v8
	v_mul_f32_e32 v25, 0xbfb8aa3b, v9
	v_exp_f32_e32 v18, v18
	v_exp_f32_e32 v19, v19
	v_exp_f32_e32 v20, v20
	v_exp_f32_e32 v21, v21
	v_exp_f32_e32 v22, v22
	v_exp_f32_e32 v23, v23
	v_exp_f32_e32 v24, v24
	v_exp_f32_e32 v25, v25
	v_add_f32_e32 v18, 1.0, v18
	v_add_f32_e32 v19, 1.0, v19
	v_add_f32_e32 v20, 1.0, v20
	v_add_f32_e32 v21, 1.0, v21
	v_add_f32_e32 v22, 1.0, v22
	v_add_f32_e32 v23, 1.0, v23
	v_add_f32_e32 v24, 1.0, v24
	v_add_f32_e32 v25, 1.0, v25
	v_rcp_f32_e32 v18, v18
	v_rcp_f32_e32 v19, v19
	v_rcp_f32_e32 v20, v20
	v_rcp_f32_e32 v21, v21
	v_rcp_f32_e32 v22, v22
	v_rcp_f32_e32 v23, v23
	v_rcp_f32_e32 v24, v24
	v_rcp_f32_e32 v25, v25
	v_mul_f32_e32 v18, v2, v18
	v_mul_f32_e32 v19, v3, v19
	v_mul_f32_e32 v20, v4, v20
	v_mul_f32_e32 v21, v5, v21
	v_mul_f32_e32 v22, v6, v22
	v_mul_f32_e32 v23, v7, v23
	v_mul_f32_e32 v24, v8, v24
	v_mul_f32_e32 v25, v9, v25
	v_mul_f32_e32 v18, v10, v18
	v_mul_f32_e32 v19, v11, v19
	v_mul_f32_e32 v20, v12, v20
	v_mul_f32_e32 v21, v13, v21
	v_mul_f32_e32 v22, v14, v22
	v_mul_f32_e32 v23, v15, v23
	v_mul_f32_e32 v24, v16, v24
	v_mul_f32_e32 v25, v17, v25
	v_cvt_pk_bf16_f32 v26, v18, v19
	v_cvt_pk_bf16_f32 v27, v20, v21
	v_cvt_pk_bf16_f32 v28, v22, v23
	v_cvt_pk_bf16_f32 v29, v24, v25
	global_store_dwordx4 v[162:163], v[26:29], off sc1
	v_lshl_add_u64 v[162:163], v[162:163], 0, v[30:31]
	v_lshlrev_b32_e32 v206, 16, v96
	v_and_b32_e32 v207, 0xffff0000, v96
	v_lshlrev_b32_e32 v208, 16, v97
	v_and_b32_e32 v209, 0xffff0000, v97
	v_lshlrev_b32_e32 v210, 16, v98
	v_and_b32_e32 v211, 0xffff0000, v98
	v_lshlrev_b32_e32 v212, 16, v99
	v_and_b32_e32 v213, 0xffff0000, v99
	v_lshlrev_b32_e32 v214, 16, v100
	v_and_b32_e32 v215, 0xffff0000, v100
	v_lshlrev_b32_e32 v216, 16, v101
	v_and_b32_e32 v217, 0xffff0000, v101
	v_lshlrev_b32_e32 v218, 16, v102
	v_and_b32_e32 v219, 0xffff0000, v102
	v_lshlrev_b32_e32 v220, 16, v103
	v_and_b32_e32 v221, 0xffff0000, v103
	v_pk_fma_f32 v[2:3], v[104:105], v[222:223], v[174:175]
	v_pk_fma_f32 v[4:5], v[106:107], v[224:225], v[176:177]
	v_pk_fma_f32 v[6:7], v[108:109], v[226:227], v[178:179]
	v_pk_fma_f32 v[8:9], v[110:111], v[228:229], v[180:181]
	v_pk_fma_f32 v[10:11], v[112:113], v[230:231], v[182:183]
	v_pk_fma_f32 v[12:13], v[114:115], v[232:233], v[184:185]
	v_pk_fma_f32 v[14:15], v[116:117], v[234:235], v[186:187]
	v_pk_fma_f32 v[16:17], v[118:119], v[236:237], v[188:189]
	v_pk_fma_f32 v[2:3], v[120:121], v[190:191], v[2:3]
	v_pk_fma_f32 v[4:5], v[122:123], v[192:193], v[4:5]
	v_pk_fma_f32 v[6:7], v[124:125], v[194:195], v[6:7]
	v_pk_fma_f32 v[8:9], v[126:127], v[196:197], v[8:9]
	v_pk_fma_f32 v[10:11], v[128:129], v[198:199], v[10:11]
	v_pk_fma_f32 v[12:13], v[130:131], v[200:201], v[12:13]
	v_pk_fma_f32 v[14:15], v[132:133], v[202:203], v[14:15]
	v_pk_fma_f32 v[16:17], v[134:135], v[204:205], v[16:17]
	v_pk_fma_f32 v[2:3], v[136:137], v[206:207], v[2:3]
	v_pk_fma_f32 v[4:5], v[138:139], v[208:209], v[4:5]
	v_pk_fma_f32 v[6:7], v[140:141], v[210:211], v[6:7]
	v_pk_fma_f32 v[8:9], v[142:143], v[212:213], v[8:9]
	v_pk_fma_f32 v[10:11], v[144:145], v[214:215], v[10:11]
	v_pk_fma_f32 v[12:13], v[146:147], v[216:217], v[12:13]
	v_pk_fma_f32 v[14:15], v[148:149], v[218:219], v[14:15]
	v_pk_fma_f32 v[16:17], v[150:151], v[220:221], v[16:17]
	v_mul_f32_e32 v18, 0xbfb8aa3b, v2
	v_mul_f32_e32 v19, 0xbfb8aa3b, v3
	v_mul_f32_e32 v20, 0xbfb8aa3b, v4
	v_mul_f32_e32 v21, 0xbfb8aa3b, v5
	v_mul_f32_e32 v22, 0xbfb8aa3b, v6
	v_mul_f32_e32 v23, 0xbfb8aa3b, v7
	v_mul_f32_e32 v24, 0xbfb8aa3b, v8
	v_mul_f32_e32 v25, 0xbfb8aa3b, v9
	v_exp_f32_e32 v18, v18
	v_exp_f32_e32 v19, v19
	v_exp_f32_e32 v20, v20
	v_exp_f32_e32 v21, v21
	v_exp_f32_e32 v22, v22
	v_exp_f32_e32 v23, v23
	v_exp_f32_e32 v24, v24
	v_exp_f32_e32 v25, v25
	v_add_f32_e32 v18, 1.0, v18
	v_add_f32_e32 v19, 1.0, v19
	v_add_f32_e32 v20, 1.0, v20
	v_add_f32_e32 v21, 1.0, v21
	v_add_f32_e32 v22, 1.0, v22
	v_add_f32_e32 v23, 1.0, v23
	v_add_f32_e32 v24, 1.0, v24
	v_add_f32_e32 v25, 1.0, v25
	v_rcp_f32_e32 v18, v18
	v_rcp_f32_e32 v19, v19
	v_rcp_f32_e32 v20, v20
	v_rcp_f32_e32 v21, v21
	v_rcp_f32_e32 v22, v22
	v_rcp_f32_e32 v23, v23
	v_rcp_f32_e32 v24, v24
	v_rcp_f32_e32 v25, v25
	v_mul_f32_e32 v18, v2, v18
	v_mul_f32_e32 v19, v3, v19
	v_mul_f32_e32 v20, v4, v20
	v_mul_f32_e32 v21, v5, v21
	v_mul_f32_e32 v22, v6, v22
	v_mul_f32_e32 v23, v7, v23
	v_mul_f32_e32 v24, v8, v24
	v_mul_f32_e32 v25, v9, v25
	v_mul_f32_e32 v18, v10, v18
	v_mul_f32_e32 v19, v11, v19
	v_mul_f32_e32 v20, v12, v20
	v_mul_f32_e32 v21, v13, v21
	v_mul_f32_e32 v22, v14, v22
	v_mul_f32_e32 v23, v15, v23
	v_mul_f32_e32 v24, v16, v24
	v_mul_f32_e32 v25, v17, v25
	v_cvt_pk_bf16_f32 v26, v18, v19
	v_cvt_pk_bf16_f32 v27, v20, v21
	v_cvt_pk_bf16_f32 v28, v22, v23
	v_cvt_pk_bf16_f32 v29, v24, v25
	global_store_dwordx4 v[162:163], v[26:29], off sc1
	v_lshl_add_u64 v[162:163], v[162:163], 0, v[30:31]
	global_load_dwordx4 v[68:71], v[158:159], off
	global_load_dwordx4 v[72:75], v[160:161], off
	v_lshl_add_u64 v[158:159], v[158:159], 0, v[164:165]
	v_lshl_add_u64 v[160:161], v[160:161], 0, v[164:165]
	global_load_dwordx4 v[76:79], v[158:159], off
	global_load_dwordx4 v[80:83], v[160:161], off
	v_lshl_add_u64 v[158:159], v[158:159], 0, v[164:165]
	v_lshl_add_u64 v[160:161], v[160:161], 0, v[164:165]
	global_load_dwordx4 v[88:91], v[158:159], off
	global_load_dwordx4 v[92:95], v[160:161], off
	v_lshl_add_u64 v[158:159], v[158:159], 0, v[164:165]
	v_lshl_add_u64 v[160:161], v[160:161], 0, v[164:165]
	global_load_dwordx4 v[96:99], v[158:159], off
	global_load_dwordx4 v[100:103], v[160:161], off
	v_lshl_add_u64 v[158:159], v[158:159], 0, v[164:165]
	v_lshl_add_u64 v[160:161], v[160:161], 0, v[164:165]
	s_waitcnt vmcnt(12)
	v_lshlrev_b32_e32 v222, 16, v36
	v_and_b32_e32 v223, 0xffff0000, v36
	v_lshlrev_b32_e32 v224, 16, v37
	v_and_b32_e32 v225, 0xffff0000, v37
	v_lshlrev_b32_e32 v226, 16, v38
	v_and_b32_e32 v227, 0xffff0000, v38
	v_lshlrev_b32_e32 v228, 16, v39
	v_and_b32_e32 v229, 0xffff0000, v39
	v_lshlrev_b32_e32 v230, 16, v40
	v_and_b32_e32 v231, 0xffff0000, v40
	v_lshlrev_b32_e32 v232, 16, v41
	v_and_b32_e32 v233, 0xffff0000, v41
	v_lshlrev_b32_e32 v234, 16, v42
	v_and_b32_e32 v235, 0xffff0000, v42
	v_lshlrev_b32_e32 v236, 16, v43
	v_and_b32_e32 v237, 0xffff0000, v43
	v_pk_fma_f32 v[2:3], v[104:105], v[190:191], v[174:175]
	v_pk_fma_f32 v[4:5], v[106:107], v[192:193], v[176:177]
	v_pk_fma_f32 v[6:7], v[108:109], v[194:195], v[178:179]
	v_pk_fma_f32 v[8:9], v[110:111], v[196:197], v[180:181]
	v_pk_fma_f32 v[10:11], v[112:113], v[198:199], v[182:183]
	v_pk_fma_f32 v[12:13], v[114:115], v[200:201], v[184:185]
	v_pk_fma_f32 v[14:15], v[116:117], v[202:203], v[186:187]
	v_pk_fma_f32 v[16:17], v[118:119], v[204:205], v[188:189]
	v_pk_fma_f32 v[2:3], v[120:121], v[206:207], v[2:3]
	v_pk_fma_f32 v[4:5], v[122:123], v[208:209], v[4:5]
	v_pk_fma_f32 v[6:7], v[124:125], v[210:211], v[6:7]
	v_pk_fma_f32 v[8:9], v[126:127], v[212:213], v[8:9]
	v_pk_fma_f32 v[10:11], v[128:129], v[214:215], v[10:11]
	v_pk_fma_f32 v[12:13], v[130:131], v[216:217], v[12:13]
	v_pk_fma_f32 v[14:15], v[132:133], v[218:219], v[14:15]
	v_pk_fma_f32 v[16:17], v[134:135], v[220:221], v[16:17]
	v_pk_fma_f32 v[2:3], v[136:137], v[222:223], v[2:3]
	v_pk_fma_f32 v[4:5], v[138:139], v[224:225], v[4:5]
	v_pk_fma_f32 v[6:7], v[140:141], v[226:227], v[6:7]
	v_pk_fma_f32 v[8:9], v[142:143], v[228:229], v[8:9]
	v_pk_fma_f32 v[10:11], v[144:145], v[230:231], v[10:11]
	v_pk_fma_f32 v[12:13], v[146:147], v[232:233], v[12:13]
	v_pk_fma_f32 v[14:15], v[148:149], v[234:235], v[14:15]
	v_pk_fma_f32 v[16:17], v[150:151], v[236:237], v[16:17]
	v_mul_f32_e32 v18, 0xbfb8aa3b, v2
	v_mul_f32_e32 v19, 0xbfb8aa3b, v3
	v_mul_f32_e32 v20, 0xbfb8aa3b, v4
	v_mul_f32_e32 v21, 0xbfb8aa3b, v5
	v_mul_f32_e32 v22, 0xbfb8aa3b, v6
	v_mul_f32_e32 v23, 0xbfb8aa3b, v7
	v_mul_f32_e32 v24, 0xbfb8aa3b, v8
	v_mul_f32_e32 v25, 0xbfb8aa3b, v9
	v_exp_f32_e32 v18, v18
	v_exp_f32_e32 v19, v19
	v_exp_f32_e32 v20, v20
	v_exp_f32_e32 v21, v21
	v_exp_f32_e32 v22, v22
	v_exp_f32_e32 v23, v23
	v_exp_f32_e32 v24, v24
	v_exp_f32_e32 v25, v25
	v_add_f32_e32 v18, 1.0, v18
	v_add_f32_e32 v19, 1.0, v19
	v_add_f32_e32 v20, 1.0, v20
	v_add_f32_e32 v21, 1.0, v21
	v_add_f32_e32 v22, 1.0, v22
	v_add_f32_e32 v23, 1.0, v23
	v_add_f32_e32 v24, 1.0, v24
	v_add_f32_e32 v25, 1.0, v25
	v_rcp_f32_e32 v18, v18
	v_rcp_f32_e32 v19, v19
	v_rcp_f32_e32 v20, v20
	v_rcp_f32_e32 v21, v21
	v_rcp_f32_e32 v22, v22
	v_rcp_f32_e32 v23, v23
	v_rcp_f32_e32 v24, v24
	v_rcp_f32_e32 v25, v25
	v_mul_f32_e32 v18, v2, v18
	v_mul_f32_e32 v19, v3, v19
	v_mul_f32_e32 v20, v4, v20
	v_mul_f32_e32 v21, v5, v21
	v_mul_f32_e32 v22, v6, v22
	v_mul_f32_e32 v23, v7, v23
	v_mul_f32_e32 v24, v8, v24
	v_mul_f32_e32 v25, v9, v25
	v_mul_f32_e32 v18, v10, v18
	v_mul_f32_e32 v19, v11, v19
	v_mul_f32_e32 v20, v12, v20
	v_mul_f32_e32 v21, v13, v21
	v_mul_f32_e32 v22, v14, v22
	v_mul_f32_e32 v23, v15, v23
	v_mul_f32_e32 v24, v16, v24
	v_mul_f32_e32 v25, v17, v25
	v_cvt_pk_bf16_f32 v26, v18, v19
	v_cvt_pk_bf16_f32 v27, v20, v21
	v_cvt_pk_bf16_f32 v28, v22, v23
	v_cvt_pk_bf16_f32 v29, v24, v25
	global_store_dwordx4 v[162:163], v[26:29], off sc1
	v_lshl_add_u64 v[162:163], v[162:163], 0, v[30:31]
	v_lshlrev_b32_e32 v190, 16, v44
	v_and_b32_e32 v191, 0xffff0000, v44
	v_lshlrev_b32_e32 v192, 16, v45
	v_and_b32_e32 v193, 0xffff0000, v45
	v_lshlrev_b32_e32 v194, 16, v46
	v_and_b32_e32 v195, 0xffff0000, v46
	v_lshlrev_b32_e32 v196, 16, v47
	v_and_b32_e32 v197, 0xffff0000, v47
	v_lshlrev_b32_e32 v198, 16, v48
	v_and_b32_e32 v199, 0xffff0000, v48
	v_lshlrev_b32_e32 v200, 16, v49
	v_and_b32_e32 v201, 0xffff0000, v49
	v_lshlrev_b32_e32 v202, 16, v50
	v_and_b32_e32 v203, 0xffff0000, v50
	v_lshlrev_b32_e32 v204, 16, v51
	v_and_b32_e32 v205, 0xffff0000, v51
	v_pk_fma_f32 v[2:3], v[104:105], v[206:207], v[174:175]
	v_pk_fma_f32 v[4:5], v[106:107], v[208:209], v[176:177]
	v_pk_fma_f32 v[6:7], v[108:109], v[210:211], v[178:179]
	v_pk_fma_f32 v[8:9], v[110:111], v[212:213], v[180:181]
	v_pk_fma_f32 v[10:11], v[112:113], v[214:215], v[182:183]
	v_pk_fma_f32 v[12:13], v[114:115], v[216:217], v[184:185]
	v_pk_fma_f32 v[14:15], v[116:117], v[218:219], v[186:187]
	v_pk_fma_f32 v[16:17], v[118:119], v[220:221], v[188:189]
	v_pk_fma_f32 v[2:3], v[120:121], v[222:223], v[2:3]
	v_pk_fma_f32 v[4:5], v[122:123], v[224:225], v[4:5]
	v_pk_fma_f32 v[6:7], v[124:125], v[226:227], v[6:7]
	v_pk_fma_f32 v[8:9], v[126:127], v[228:229], v[8:9]
	v_pk_fma_f32 v[10:11], v[128:129], v[230:231], v[10:11]
	v_pk_fma_f32 v[12:13], v[130:131], v[232:233], v[12:13]
	v_pk_fma_f32 v[14:15], v[132:133], v[234:235], v[14:15]
	v_pk_fma_f32 v[16:17], v[134:135], v[236:237], v[16:17]
	v_pk_fma_f32 v[2:3], v[136:137], v[190:191], v[2:3]
	v_pk_fma_f32 v[4:5], v[138:139], v[192:193], v[4:5]
	v_pk_fma_f32 v[6:7], v[140:141], v[194:195], v[6:7]
	v_pk_fma_f32 v[8:9], v[142:143], v[196:197], v[8:9]
	v_pk_fma_f32 v[10:11], v[144:145], v[198:199], v[10:11]
	v_pk_fma_f32 v[12:13], v[146:147], v[200:201], v[12:13]
	v_pk_fma_f32 v[14:15], v[148:149], v[202:203], v[14:15]
	v_pk_fma_f32 v[16:17], v[150:151], v[204:205], v[16:17]
	v_mul_f32_e32 v18, 0xbfb8aa3b, v2
	v_mul_f32_e32 v19, 0xbfb8aa3b, v3
	v_mul_f32_e32 v20, 0xbfb8aa3b, v4
	v_mul_f32_e32 v21, 0xbfb8aa3b, v5
	v_mul_f32_e32 v22, 0xbfb8aa3b, v6
	v_mul_f32_e32 v23, 0xbfb8aa3b, v7
	v_mul_f32_e32 v24, 0xbfb8aa3b, v8
	v_mul_f32_e32 v25, 0xbfb8aa3b, v9
	v_exp_f32_e32 v18, v18
	v_exp_f32_e32 v19, v19
	v_exp_f32_e32 v20, v20
	v_exp_f32_e32 v21, v21
	v_exp_f32_e32 v22, v22
	v_exp_f32_e32 v23, v23
	v_exp_f32_e32 v24, v24
	v_exp_f32_e32 v25, v25
	v_add_f32_e32 v18, 1.0, v18
	v_add_f32_e32 v19, 1.0, v19
	v_add_f32_e32 v20, 1.0, v20
	v_add_f32_e32 v21, 1.0, v21
	v_add_f32_e32 v22, 1.0, v22
	v_add_f32_e32 v23, 1.0, v23
	v_add_f32_e32 v24, 1.0, v24
	v_add_f32_e32 v25, 1.0, v25
	v_rcp_f32_e32 v18, v18
	v_rcp_f32_e32 v19, v19
	v_rcp_f32_e32 v20, v20
	v_rcp_f32_e32 v21, v21
	v_rcp_f32_e32 v22, v22
	v_rcp_f32_e32 v23, v23
	v_rcp_f32_e32 v24, v24
	v_rcp_f32_e32 v25, v25
	v_mul_f32_e32 v18, v2, v18
	v_mul_f32_e32 v19, v3, v19
	v_mul_f32_e32 v20, v4, v20
	v_mul_f32_e32 v21, v5, v21
	v_mul_f32_e32 v22, v6, v22
	v_mul_f32_e32 v23, v7, v23
	v_mul_f32_e32 v24, v8, v24
	v_mul_f32_e32 v25, v9, v25
	v_mul_f32_e32 v18, v10, v18
	v_mul_f32_e32 v19, v11, v19
	v_mul_f32_e32 v20, v12, v20
	v_mul_f32_e32 v21, v13, v21
	v_mul_f32_e32 v22, v14, v22
	v_mul_f32_e32 v23, v15, v23
	v_mul_f32_e32 v24, v16, v24
	v_mul_f32_e32 v25, v17, v25
	v_cvt_pk_bf16_f32 v26, v18, v19
	v_cvt_pk_bf16_f32 v27, v20, v21
	v_cvt_pk_bf16_f32 v28, v22, v23
	v_cvt_pk_bf16_f32 v29, v24, v25
	global_store_dwordx4 v[162:163], v[26:29], off sc1
	v_lshl_add_u64 v[162:163], v[162:163], 0, v[30:31]
	v_lshlrev_b32_e32 v206, 16, v52
	v_and_b32_e32 v207, 0xffff0000, v52
	v_lshlrev_b32_e32 v208, 16, v53
	v_and_b32_e32 v209, 0xffff0000, v53
	v_lshlrev_b32_e32 v210, 16, v54
	v_and_b32_e32 v211, 0xffff0000, v54
	v_lshlrev_b32_e32 v212, 16, v55
	v_and_b32_e32 v213, 0xffff0000, v55
	v_lshlrev_b32_e32 v214, 16, v56
	v_and_b32_e32 v215, 0xffff0000, v56
	v_lshlrev_b32_e32 v216, 16, v57
	v_and_b32_e32 v217, 0xffff0000, v57
	v_lshlrev_b32_e32 v218, 16, v58
	v_and_b32_e32 v219, 0xffff0000, v58
	v_lshlrev_b32_e32 v220, 16, v59
	v_and_b32_e32 v221, 0xffff0000, v59
	v_pk_fma_f32 v[2:3], v[104:105], v[222:223], v[174:175]
	v_pk_fma_f32 v[4:5], v[106:107], v[224:225], v[176:177]
	v_pk_fma_f32 v[6:7], v[108:109], v[226:227], v[178:179]
	v_pk_fma_f32 v[8:9], v[110:111], v[228:229], v[180:181]
	v_pk_fma_f32 v[10:11], v[112:113], v[230:231], v[182:183]
	v_pk_fma_f32 v[12:13], v[114:115], v[232:233], v[184:185]
	v_pk_fma_f32 v[14:15], v[116:117], v[234:235], v[186:187]
	v_pk_fma_f32 v[16:17], v[118:119], v[236:237], v[188:189]
	v_pk_fma_f32 v[2:3], v[120:121], v[190:191], v[2:3]
	v_pk_fma_f32 v[4:5], v[122:123], v[192:193], v[4:5]
	v_pk_fma_f32 v[6:7], v[124:125], v[194:195], v[6:7]
	v_pk_fma_f32 v[8:9], v[126:127], v[196:197], v[8:9]
	v_pk_fma_f32 v[10:11], v[128:129], v[198:199], v[10:11]
	v_pk_fma_f32 v[12:13], v[130:131], v[200:201], v[12:13]
	v_pk_fma_f32 v[14:15], v[132:133], v[202:203], v[14:15]
	v_pk_fma_f32 v[16:17], v[134:135], v[204:205], v[16:17]
	v_pk_fma_f32 v[2:3], v[136:137], v[206:207], v[2:3]
	v_pk_fma_f32 v[4:5], v[138:139], v[208:209], v[4:5]
	v_pk_fma_f32 v[6:7], v[140:141], v[210:211], v[6:7]
	v_pk_fma_f32 v[8:9], v[142:143], v[212:213], v[8:9]
	v_pk_fma_f32 v[10:11], v[144:145], v[214:215], v[10:11]
	v_pk_fma_f32 v[12:13], v[146:147], v[216:217], v[12:13]
	v_pk_fma_f32 v[14:15], v[148:149], v[218:219], v[14:15]
	v_pk_fma_f32 v[16:17], v[150:151], v[220:221], v[16:17]
	v_mul_f32_e32 v18, 0xbfb8aa3b, v2
	v_mul_f32_e32 v19, 0xbfb8aa3b, v3
	v_mul_f32_e32 v20, 0xbfb8aa3b, v4
	v_mul_f32_e32 v21, 0xbfb8aa3b, v5
	v_mul_f32_e32 v22, 0xbfb8aa3b, v6
	v_mul_f32_e32 v23, 0xbfb8aa3b, v7
	v_mul_f32_e32 v24, 0xbfb8aa3b, v8
	v_mul_f32_e32 v25, 0xbfb8aa3b, v9
	v_exp_f32_e32 v18, v18
	v_exp_f32_e32 v19, v19
	v_exp_f32_e32 v20, v20
	v_exp_f32_e32 v21, v21
	v_exp_f32_e32 v22, v22
	v_exp_f32_e32 v23, v23
	v_exp_f32_e32 v24, v24
	v_exp_f32_e32 v25, v25
	v_add_f32_e32 v18, 1.0, v18
	v_add_f32_e32 v19, 1.0, v19
	v_add_f32_e32 v20, 1.0, v20
	v_add_f32_e32 v21, 1.0, v21
	v_add_f32_e32 v22, 1.0, v22
	v_add_f32_e32 v23, 1.0, v23
	v_add_f32_e32 v24, 1.0, v24
	v_add_f32_e32 v25, 1.0, v25
	v_rcp_f32_e32 v18, v18
	v_rcp_f32_e32 v19, v19
	v_rcp_f32_e32 v20, v20
	v_rcp_f32_e32 v21, v21
	v_rcp_f32_e32 v22, v22
	v_rcp_f32_e32 v23, v23
	v_rcp_f32_e32 v24, v24
	v_rcp_f32_e32 v25, v25
	v_mul_f32_e32 v18, v2, v18
	v_mul_f32_e32 v19, v3, v19
	v_mul_f32_e32 v20, v4, v20
	v_mul_f32_e32 v21, v5, v21
	v_mul_f32_e32 v22, v6, v22
	v_mul_f32_e32 v23, v7, v23
	v_mul_f32_e32 v24, v8, v24
	v_mul_f32_e32 v25, v9, v25
	v_mul_f32_e32 v18, v10, v18
	v_mul_f32_e32 v19, v11, v19
	v_mul_f32_e32 v20, v12, v20
	v_mul_f32_e32 v21, v13, v21
	v_mul_f32_e32 v22, v14, v22
	v_mul_f32_e32 v23, v15, v23
	v_mul_f32_e32 v24, v16, v24
	v_mul_f32_e32 v25, v17, v25
	v_cvt_pk_bf16_f32 v26, v18, v19
	v_cvt_pk_bf16_f32 v27, v20, v21
	v_cvt_pk_bf16_f32 v28, v22, v23
	v_cvt_pk_bf16_f32 v29, v24, v25
	global_store_dwordx4 v[162:163], v[26:29], off sc1
	v_lshl_add_u64 v[162:163], v[162:163], 0, v[30:31]
	v_lshlrev_b32_e32 v222, 16, v60
	v_and_b32_e32 v223, 0xffff0000, v60
	v_lshlrev_b32_e32 v224, 16, v61
	v_and_b32_e32 v225, 0xffff0000, v61
	v_lshlrev_b32_e32 v226, 16, v62
	v_and_b32_e32 v227, 0xffff0000, v62
	v_lshlrev_b32_e32 v228, 16, v63
	v_and_b32_e32 v229, 0xffff0000, v63
	v_lshlrev_b32_e32 v230, 16, v64
	v_and_b32_e32 v231, 0xffff0000, v64
	v_lshlrev_b32_e32 v232, 16, v65
	v_and_b32_e32 v233, 0xffff0000, v65
	v_lshlrev_b32_e32 v234, 16, v66
	v_and_b32_e32 v235, 0xffff0000, v66
	v_lshlrev_b32_e32 v236, 16, v67
	v_and_b32_e32 v237, 0xffff0000, v67
	v_pk_fma_f32 v[2:3], v[104:105], v[190:191], v[174:175]
	v_pk_fma_f32 v[4:5], v[106:107], v[192:193], v[176:177]
	v_pk_fma_f32 v[6:7], v[108:109], v[194:195], v[178:179]
	v_pk_fma_f32 v[8:9], v[110:111], v[196:197], v[180:181]
	v_pk_fma_f32 v[10:11], v[112:113], v[198:199], v[182:183]
	v_pk_fma_f32 v[12:13], v[114:115], v[200:201], v[184:185]
	v_pk_fma_f32 v[14:15], v[116:117], v[202:203], v[186:187]
	v_pk_fma_f32 v[16:17], v[118:119], v[204:205], v[188:189]
	v_pk_fma_f32 v[2:3], v[120:121], v[206:207], v[2:3]
	v_pk_fma_f32 v[4:5], v[122:123], v[208:209], v[4:5]
	v_pk_fma_f32 v[6:7], v[124:125], v[210:211], v[6:7]
	v_pk_fma_f32 v[8:9], v[126:127], v[212:213], v[8:9]
	v_pk_fma_f32 v[10:11], v[128:129], v[214:215], v[10:11]
	v_pk_fma_f32 v[12:13], v[130:131], v[216:217], v[12:13]
	v_pk_fma_f32 v[14:15], v[132:133], v[218:219], v[14:15]
	v_pk_fma_f32 v[16:17], v[134:135], v[220:221], v[16:17]
	v_pk_fma_f32 v[2:3], v[136:137], v[222:223], v[2:3]
	v_pk_fma_f32 v[4:5], v[138:139], v[224:225], v[4:5]
	v_pk_fma_f32 v[6:7], v[140:141], v[226:227], v[6:7]
	v_pk_fma_f32 v[8:9], v[142:143], v[228:229], v[8:9]
	v_pk_fma_f32 v[10:11], v[144:145], v[230:231], v[10:11]
	v_pk_fma_f32 v[12:13], v[146:147], v[232:233], v[12:13]
	v_pk_fma_f32 v[14:15], v[148:149], v[234:235], v[14:15]
	v_pk_fma_f32 v[16:17], v[150:151], v[236:237], v[16:17]
	v_mul_f32_e32 v18, 0xbfb8aa3b, v2
	v_mul_f32_e32 v19, 0xbfb8aa3b, v3
	v_mul_f32_e32 v20, 0xbfb8aa3b, v4
	v_mul_f32_e32 v21, 0xbfb8aa3b, v5
	v_mul_f32_e32 v22, 0xbfb8aa3b, v6
	v_mul_f32_e32 v23, 0xbfb8aa3b, v7
	v_mul_f32_e32 v24, 0xbfb8aa3b, v8
	v_mul_f32_e32 v25, 0xbfb8aa3b, v9
	v_exp_f32_e32 v18, v18
	v_exp_f32_e32 v19, v19
	v_exp_f32_e32 v20, v20
	v_exp_f32_e32 v21, v21
	v_exp_f32_e32 v22, v22
	v_exp_f32_e32 v23, v23
	v_exp_f32_e32 v24, v24
	v_exp_f32_e32 v25, v25
	v_add_f32_e32 v18, 1.0, v18
	v_add_f32_e32 v19, 1.0, v19
	v_add_f32_e32 v20, 1.0, v20
	v_add_f32_e32 v21, 1.0, v21
	v_add_f32_e32 v22, 1.0, v22
	v_add_f32_e32 v23, 1.0, v23
	v_add_f32_e32 v24, 1.0, v24
	v_add_f32_e32 v25, 1.0, v25
	v_rcp_f32_e32 v18, v18
	v_rcp_f32_e32 v19, v19
	v_rcp_f32_e32 v20, v20
	v_rcp_f32_e32 v21, v21
	v_rcp_f32_e32 v22, v22
	v_rcp_f32_e32 v23, v23
	v_rcp_f32_e32 v24, v24
	v_rcp_f32_e32 v25, v25
	v_mul_f32_e32 v18, v2, v18
	v_mul_f32_e32 v19, v3, v19
	v_mul_f32_e32 v20, v4, v20
	v_mul_f32_e32 v21, v5, v21
	v_mul_f32_e32 v22, v6, v22
	v_mul_f32_e32 v23, v7, v23
	v_mul_f32_e32 v24, v8, v24
	v_mul_f32_e32 v25, v9, v25
	v_mul_f32_e32 v18, v10, v18
	v_mul_f32_e32 v19, v11, v19
	v_mul_f32_e32 v20, v12, v20
	v_mul_f32_e32 v21, v13, v21
	v_mul_f32_e32 v22, v14, v22
	v_mul_f32_e32 v23, v15, v23
	v_mul_f32_e32 v24, v16, v24
	v_mul_f32_e32 v25, v17, v25
	v_cvt_pk_bf16_f32 v26, v18, v19
	v_cvt_pk_bf16_f32 v27, v20, v21
	v_cvt_pk_bf16_f32 v28, v22, v23
	v_cvt_pk_bf16_f32 v29, v24, v25
	global_store_dwordx4 v[162:163], v[26:29], off sc1
	v_lshl_add_u64 v[162:163], v[162:163], 0, v[30:31]
	s_waitcnt vmcnt(4)
	v_lshlrev_b32_e32 v190, 16, v68
	v_and_b32_e32 v191, 0xffff0000, v68
	v_lshlrev_b32_e32 v192, 16, v69
	v_and_b32_e32 v193, 0xffff0000, v69
	v_lshlrev_b32_e32 v194, 16, v70
	v_and_b32_e32 v195, 0xffff0000, v70
	v_lshlrev_b32_e32 v196, 16, v71
	v_and_b32_e32 v197, 0xffff0000, v71
	v_lshlrev_b32_e32 v198, 16, v72
	v_and_b32_e32 v199, 0xffff0000, v72
	v_lshlrev_b32_e32 v200, 16, v73
	v_and_b32_e32 v201, 0xffff0000, v73
	v_lshlrev_b32_e32 v202, 16, v74
	v_and_b32_e32 v203, 0xffff0000, v74
	v_lshlrev_b32_e32 v204, 16, v75
	v_and_b32_e32 v205, 0xffff0000, v75
	v_pk_fma_f32 v[2:3], v[104:105], v[206:207], v[174:175]
	v_pk_fma_f32 v[4:5], v[106:107], v[208:209], v[176:177]
	v_pk_fma_f32 v[6:7], v[108:109], v[210:211], v[178:179]
	v_pk_fma_f32 v[8:9], v[110:111], v[212:213], v[180:181]
	v_pk_fma_f32 v[10:11], v[112:113], v[214:215], v[182:183]
	v_pk_fma_f32 v[12:13], v[114:115], v[216:217], v[184:185]
	v_pk_fma_f32 v[14:15], v[116:117], v[218:219], v[186:187]
	v_pk_fma_f32 v[16:17], v[118:119], v[220:221], v[188:189]
	v_pk_fma_f32 v[2:3], v[120:121], v[222:223], v[2:3]
	v_pk_fma_f32 v[4:5], v[122:123], v[224:225], v[4:5]
	v_pk_fma_f32 v[6:7], v[124:125], v[226:227], v[6:7]
	v_pk_fma_f32 v[8:9], v[126:127], v[228:229], v[8:9]
	v_pk_fma_f32 v[10:11], v[128:129], v[230:231], v[10:11]
	v_pk_fma_f32 v[12:13], v[130:131], v[232:233], v[12:13]
	v_pk_fma_f32 v[14:15], v[132:133], v[234:235], v[14:15]
	v_pk_fma_f32 v[16:17], v[134:135], v[236:237], v[16:17]
	v_pk_fma_f32 v[2:3], v[136:137], v[190:191], v[2:3]
	v_pk_fma_f32 v[4:5], v[138:139], v[192:193], v[4:5]
	v_pk_fma_f32 v[6:7], v[140:141], v[194:195], v[6:7]
	v_pk_fma_f32 v[8:9], v[142:143], v[196:197], v[8:9]
	v_pk_fma_f32 v[10:11], v[144:145], v[198:199], v[10:11]
	v_pk_fma_f32 v[12:13], v[146:147], v[200:201], v[12:13]
	v_pk_fma_f32 v[14:15], v[148:149], v[202:203], v[14:15]
	v_pk_fma_f32 v[16:17], v[150:151], v[204:205], v[16:17]
	v_mul_f32_e32 v18, 0xbfb8aa3b, v2
	v_mul_f32_e32 v19, 0xbfb8aa3b, v3
	v_mul_f32_e32 v20, 0xbfb8aa3b, v4
	v_mul_f32_e32 v21, 0xbfb8aa3b, v5
	v_mul_f32_e32 v22, 0xbfb8aa3b, v6
	v_mul_f32_e32 v23, 0xbfb8aa3b, v7
	v_mul_f32_e32 v24, 0xbfb8aa3b, v8
	v_mul_f32_e32 v25, 0xbfb8aa3b, v9
	v_exp_f32_e32 v18, v18
	v_exp_f32_e32 v19, v19
	v_exp_f32_e32 v20, v20
	v_exp_f32_e32 v21, v21
	v_exp_f32_e32 v22, v22
	v_exp_f32_e32 v23, v23
	v_exp_f32_e32 v24, v24
	v_exp_f32_e32 v25, v25
	v_add_f32_e32 v18, 1.0, v18
	v_add_f32_e32 v19, 1.0, v19
	v_add_f32_e32 v20, 1.0, v20
	v_add_f32_e32 v21, 1.0, v21
	v_add_f32_e32 v22, 1.0, v22
	v_add_f32_e32 v23, 1.0, v23
	v_add_f32_e32 v24, 1.0, v24
	v_add_f32_e32 v25, 1.0, v25
	v_rcp_f32_e32 v18, v18
	v_rcp_f32_e32 v19, v19
	v_rcp_f32_e32 v20, v20
	v_rcp_f32_e32 v21, v21
	v_rcp_f32_e32 v22, v22
	v_rcp_f32_e32 v23, v23
	v_rcp_f32_e32 v24, v24
	v_rcp_f32_e32 v25, v25
	v_mul_f32_e32 v18, v2, v18
	v_mul_f32_e32 v19, v3, v19
	v_mul_f32_e32 v20, v4, v20
	v_mul_f32_e32 v21, v5, v21
	v_mul_f32_e32 v22, v6, v22
	v_mul_f32_e32 v23, v7, v23
	v_mul_f32_e32 v24, v8, v24
	v_mul_f32_e32 v25, v9, v25
	v_mul_f32_e32 v18, v10, v18
	v_mul_f32_e32 v19, v11, v19
	v_mul_f32_e32 v20, v12, v20
	v_mul_f32_e32 v21, v13, v21
	v_mul_f32_e32 v22, v14, v22
	v_mul_f32_e32 v23, v15, v23
	v_mul_f32_e32 v24, v16, v24
	v_mul_f32_e32 v25, v17, v25
	v_cvt_pk_bf16_f32 v26, v18, v19
	v_cvt_pk_bf16_f32 v27, v20, v21
	v_cvt_pk_bf16_f32 v28, v22, v23
	v_cvt_pk_bf16_f32 v29, v24, v25
	global_store_dwordx4 v[162:163], v[26:29], off sc1
	v_lshl_add_u64 v[162:163], v[162:163], 0, v[30:31]
	v_lshlrev_b32_e32 v206, 16, v76
	v_and_b32_e32 v207, 0xffff0000, v76
	v_lshlrev_b32_e32 v208, 16, v77
	v_and_b32_e32 v209, 0xffff0000, v77
	v_lshlrev_b32_e32 v210, 16, v78
	v_and_b32_e32 v211, 0xffff0000, v78
	v_lshlrev_b32_e32 v212, 16, v79
	v_and_b32_e32 v213, 0xffff0000, v79
	v_lshlrev_b32_e32 v214, 16, v80
	v_and_b32_e32 v215, 0xffff0000, v80
	v_lshlrev_b32_e32 v216, 16, v81
	v_and_b32_e32 v217, 0xffff0000, v81
	v_lshlrev_b32_e32 v218, 16, v82
	v_and_b32_e32 v219, 0xffff0000, v82
	v_lshlrev_b32_e32 v220, 16, v83
	v_and_b32_e32 v221, 0xffff0000, v83
	v_pk_fma_f32 v[2:3], v[104:105], v[222:223], v[174:175]
	v_pk_fma_f32 v[4:5], v[106:107], v[224:225], v[176:177]
	v_pk_fma_f32 v[6:7], v[108:109], v[226:227], v[178:179]
	v_pk_fma_f32 v[8:9], v[110:111], v[228:229], v[180:181]
	v_pk_fma_f32 v[10:11], v[112:113], v[230:231], v[182:183]
	v_pk_fma_f32 v[12:13], v[114:115], v[232:233], v[184:185]
	v_pk_fma_f32 v[14:15], v[116:117], v[234:235], v[186:187]
	v_pk_fma_f32 v[16:17], v[118:119], v[236:237], v[188:189]
	v_pk_fma_f32 v[2:3], v[120:121], v[190:191], v[2:3]
	v_pk_fma_f32 v[4:5], v[122:123], v[192:193], v[4:5]
	v_pk_fma_f32 v[6:7], v[124:125], v[194:195], v[6:7]
	v_pk_fma_f32 v[8:9], v[126:127], v[196:197], v[8:9]
	v_pk_fma_f32 v[10:11], v[128:129], v[198:199], v[10:11]
	v_pk_fma_f32 v[12:13], v[130:131], v[200:201], v[12:13]
	v_pk_fma_f32 v[14:15], v[132:133], v[202:203], v[14:15]
	v_pk_fma_f32 v[16:17], v[134:135], v[204:205], v[16:17]
	v_pk_fma_f32 v[2:3], v[136:137], v[206:207], v[2:3]
	v_pk_fma_f32 v[4:5], v[138:139], v[208:209], v[4:5]
	v_pk_fma_f32 v[6:7], v[140:141], v[210:211], v[6:7]
	v_pk_fma_f32 v[8:9], v[142:143], v[212:213], v[8:9]
	v_pk_fma_f32 v[10:11], v[144:145], v[214:215], v[10:11]
	v_pk_fma_f32 v[12:13], v[146:147], v[216:217], v[12:13]
	v_pk_fma_f32 v[14:15], v[148:149], v[218:219], v[14:15]
	v_pk_fma_f32 v[16:17], v[150:151], v[220:221], v[16:17]
	v_mul_f32_e32 v18, 0xbfb8aa3b, v2
	v_mul_f32_e32 v19, 0xbfb8aa3b, v3
	v_mul_f32_e32 v20, 0xbfb8aa3b, v4
	v_mul_f32_e32 v21, 0xbfb8aa3b, v5
	v_mul_f32_e32 v22, 0xbfb8aa3b, v6
	v_mul_f32_e32 v23, 0xbfb8aa3b, v7
	v_mul_f32_e32 v24, 0xbfb8aa3b, v8
	v_mul_f32_e32 v25, 0xbfb8aa3b, v9
	v_exp_f32_e32 v18, v18
	v_exp_f32_e32 v19, v19
	v_exp_f32_e32 v20, v20
	v_exp_f32_e32 v21, v21
	v_exp_f32_e32 v22, v22
	v_exp_f32_e32 v23, v23
	v_exp_f32_e32 v24, v24
	v_exp_f32_e32 v25, v25
	v_add_f32_e32 v18, 1.0, v18
	v_add_f32_e32 v19, 1.0, v19
	v_add_f32_e32 v20, 1.0, v20
	v_add_f32_e32 v21, 1.0, v21
	v_add_f32_e32 v22, 1.0, v22
	v_add_f32_e32 v23, 1.0, v23
	v_add_f32_e32 v24, 1.0, v24
	v_add_f32_e32 v25, 1.0, v25
	v_rcp_f32_e32 v18, v18
	v_rcp_f32_e32 v19, v19
	v_rcp_f32_e32 v20, v20
	v_rcp_f32_e32 v21, v21
	v_rcp_f32_e32 v22, v22
	v_rcp_f32_e32 v23, v23
	v_rcp_f32_e32 v24, v24
	v_rcp_f32_e32 v25, v25
	v_mul_f32_e32 v18, v2, v18
	v_mul_f32_e32 v19, v3, v19
	v_mul_f32_e32 v20, v4, v20
	v_mul_f32_e32 v21, v5, v21
	v_mul_f32_e32 v22, v6, v22
	v_mul_f32_e32 v23, v7, v23
	v_mul_f32_e32 v24, v8, v24
	v_mul_f32_e32 v25, v9, v25
	v_mul_f32_e32 v18, v10, v18
	v_mul_f32_e32 v19, v11, v19
	v_mul_f32_e32 v20, v12, v20
	v_mul_f32_e32 v21, v13, v21
	v_mul_f32_e32 v22, v14, v22
	v_mul_f32_e32 v23, v15, v23
	v_mul_f32_e32 v24, v16, v24
	v_mul_f32_e32 v25, v17, v25
	v_cvt_pk_bf16_f32 v26, v18, v19
	v_cvt_pk_bf16_f32 v27, v20, v21
	v_cvt_pk_bf16_f32 v28, v22, v23
	v_cvt_pk_bf16_f32 v29, v24, v25
	global_store_dwordx4 v[162:163], v[26:29], off sc1
	v_lshl_add_u64 v[162:163], v[162:163], 0, v[30:31]
	v_lshlrev_b32_e32 v222, 16, v88
	v_and_b32_e32 v223, 0xffff0000, v88
	v_lshlrev_b32_e32 v224, 16, v89
	v_and_b32_e32 v225, 0xffff0000, v89
	v_lshlrev_b32_e32 v226, 16, v90
	v_and_b32_e32 v227, 0xffff0000, v90
	v_lshlrev_b32_e32 v228, 16, v91
	v_and_b32_e32 v229, 0xffff0000, v91
	v_lshlrev_b32_e32 v230, 16, v92
	v_and_b32_e32 v231, 0xffff0000, v92
	v_lshlrev_b32_e32 v232, 16, v93
	v_and_b32_e32 v233, 0xffff0000, v93
	v_lshlrev_b32_e32 v234, 16, v94
	v_and_b32_e32 v235, 0xffff0000, v94
	v_lshlrev_b32_e32 v236, 16, v95
	v_and_b32_e32 v237, 0xffff0000, v95
	v_pk_fma_f32 v[2:3], v[104:105], v[190:191], v[174:175]
	v_pk_fma_f32 v[4:5], v[106:107], v[192:193], v[176:177]
	v_pk_fma_f32 v[6:7], v[108:109], v[194:195], v[178:179]
	v_pk_fma_f32 v[8:9], v[110:111], v[196:197], v[180:181]
	v_pk_fma_f32 v[10:11], v[112:113], v[198:199], v[182:183]
	v_pk_fma_f32 v[12:13], v[114:115], v[200:201], v[184:185]
	v_pk_fma_f32 v[14:15], v[116:117], v[202:203], v[186:187]
	v_pk_fma_f32 v[16:17], v[118:119], v[204:205], v[188:189]
	v_pk_fma_f32 v[2:3], v[120:121], v[206:207], v[2:3]
	v_pk_fma_f32 v[4:5], v[122:123], v[208:209], v[4:5]
	v_pk_fma_f32 v[6:7], v[124:125], v[210:211], v[6:7]
	v_pk_fma_f32 v[8:9], v[126:127], v[212:213], v[8:9]
	v_pk_fma_f32 v[10:11], v[128:129], v[214:215], v[10:11]
	v_pk_fma_f32 v[12:13], v[130:131], v[216:217], v[12:13]
	v_pk_fma_f32 v[14:15], v[132:133], v[218:219], v[14:15]
	v_pk_fma_f32 v[16:17], v[134:135], v[220:221], v[16:17]
	v_pk_fma_f32 v[2:3], v[136:137], v[222:223], v[2:3]
	v_pk_fma_f32 v[4:5], v[138:139], v[224:225], v[4:5]
	v_pk_fma_f32 v[6:7], v[140:141], v[226:227], v[6:7]
	v_pk_fma_f32 v[8:9], v[142:143], v[228:229], v[8:9]
	v_pk_fma_f32 v[10:11], v[144:145], v[230:231], v[10:11]
	v_pk_fma_f32 v[12:13], v[146:147], v[232:233], v[12:13]
	v_pk_fma_f32 v[14:15], v[148:149], v[234:235], v[14:15]
	v_pk_fma_f32 v[16:17], v[150:151], v[236:237], v[16:17]
	v_mul_f32_e32 v18, 0xbfb8aa3b, v2
	v_mul_f32_e32 v19, 0xbfb8aa3b, v3
	v_mul_f32_e32 v20, 0xbfb8aa3b, v4
	v_mul_f32_e32 v21, 0xbfb8aa3b, v5
	v_mul_f32_e32 v22, 0xbfb8aa3b, v6
	v_mul_f32_e32 v23, 0xbfb8aa3b, v7
	v_mul_f32_e32 v24, 0xbfb8aa3b, v8
	v_mul_f32_e32 v25, 0xbfb8aa3b, v9
	v_exp_f32_e32 v18, v18
	v_exp_f32_e32 v19, v19
	v_exp_f32_e32 v20, v20
	v_exp_f32_e32 v21, v21
	v_exp_f32_e32 v22, v22
	v_exp_f32_e32 v23, v23
	v_exp_f32_e32 v24, v24
	v_exp_f32_e32 v25, v25
	v_add_f32_e32 v18, 1.0, v18
	v_add_f32_e32 v19, 1.0, v19
	v_add_f32_e32 v20, 1.0, v20
	v_add_f32_e32 v21, 1.0, v21
	v_add_f32_e32 v22, 1.0, v22
	v_add_f32_e32 v23, 1.0, v23
	v_add_f32_e32 v24, 1.0, v24
	v_add_f32_e32 v25, 1.0, v25
	v_rcp_f32_e32 v18, v18
	v_rcp_f32_e32 v19, v19
	v_rcp_f32_e32 v20, v20
	v_rcp_f32_e32 v21, v21
	v_rcp_f32_e32 v22, v22
	v_rcp_f32_e32 v23, v23
	v_rcp_f32_e32 v24, v24
	v_rcp_f32_e32 v25, v25
	v_mul_f32_e32 v18, v2, v18
	v_mul_f32_e32 v19, v3, v19
	v_mul_f32_e32 v20, v4, v20
	v_mul_f32_e32 v21, v5, v21
	v_mul_f32_e32 v22, v6, v22
	v_mul_f32_e32 v23, v7, v23
	v_mul_f32_e32 v24, v8, v24
	v_mul_f32_e32 v25, v9, v25
	v_mul_f32_e32 v18, v10, v18
	v_mul_f32_e32 v19, v11, v19
	v_mul_f32_e32 v20, v12, v20
	v_mul_f32_e32 v21, v13, v21
	v_mul_f32_e32 v22, v14, v22
	v_mul_f32_e32 v23, v15, v23
	v_mul_f32_e32 v24, v16, v24
	v_mul_f32_e32 v25, v17, v25
	v_cvt_pk_bf16_f32 v26, v18, v19
	v_cvt_pk_bf16_f32 v27, v20, v21
	v_cvt_pk_bf16_f32 v28, v22, v23
	v_cvt_pk_bf16_f32 v29, v24, v25
	global_store_dwordx4 v[162:163], v[26:29], off sc1
	v_lshl_add_u64 v[162:163], v[162:163], 0, v[30:31]
	v_lshlrev_b32_e32 v190, 16, v96
	v_and_b32_e32 v191, 0xffff0000, v96
	v_lshlrev_b32_e32 v192, 16, v97
	v_and_b32_e32 v193, 0xffff0000, v97
	v_lshlrev_b32_e32 v194, 16, v98
	v_and_b32_e32 v195, 0xffff0000, v98
	v_lshlrev_b32_e32 v196, 16, v99
	v_and_b32_e32 v197, 0xffff0000, v99
	v_lshlrev_b32_e32 v198, 16, v100
	v_and_b32_e32 v199, 0xffff0000, v100
	v_lshlrev_b32_e32 v200, 16, v101
	v_and_b32_e32 v201, 0xffff0000, v101
	v_lshlrev_b32_e32 v202, 16, v102
	v_and_b32_e32 v203, 0xffff0000, v102
	v_lshlrev_b32_e32 v204, 16, v103
	v_and_b32_e32 v205, 0xffff0000, v103
	v_pk_fma_f32 v[2:3], v[104:105], v[206:207], v[174:175]
	v_pk_fma_f32 v[4:5], v[106:107], v[208:209], v[176:177]
	v_pk_fma_f32 v[6:7], v[108:109], v[210:211], v[178:179]
	v_pk_fma_f32 v[8:9], v[110:111], v[212:213], v[180:181]
	v_pk_fma_f32 v[10:11], v[112:113], v[214:215], v[182:183]
	v_pk_fma_f32 v[12:13], v[114:115], v[216:217], v[184:185]
	v_pk_fma_f32 v[14:15], v[116:117], v[218:219], v[186:187]
	v_pk_fma_f32 v[16:17], v[118:119], v[220:221], v[188:189]
	v_pk_fma_f32 v[2:3], v[120:121], v[222:223], v[2:3]
	v_pk_fma_f32 v[4:5], v[122:123], v[224:225], v[4:5]
	v_pk_fma_f32 v[6:7], v[124:125], v[226:227], v[6:7]
	v_pk_fma_f32 v[8:9], v[126:127], v[228:229], v[8:9]
	v_pk_fma_f32 v[10:11], v[128:129], v[230:231], v[10:11]
	v_pk_fma_f32 v[12:13], v[130:131], v[232:233], v[12:13]
	v_pk_fma_f32 v[14:15], v[132:133], v[234:235], v[14:15]
	v_pk_fma_f32 v[16:17], v[134:135], v[236:237], v[16:17]
	v_pk_fma_f32 v[2:3], v[136:137], v[190:191], v[2:3]
	v_pk_fma_f32 v[4:5], v[138:139], v[192:193], v[4:5]
	v_pk_fma_f32 v[6:7], v[140:141], v[194:195], v[6:7]
	v_pk_fma_f32 v[8:9], v[142:143], v[196:197], v[8:9]
	v_pk_fma_f32 v[10:11], v[144:145], v[198:199], v[10:11]
	v_pk_fma_f32 v[12:13], v[146:147], v[200:201], v[12:13]
	v_pk_fma_f32 v[14:15], v[148:149], v[202:203], v[14:15]
	v_pk_fma_f32 v[16:17], v[150:151], v[204:205], v[16:17]
	v_mul_f32_e32 v18, 0xbfb8aa3b, v2
	v_mul_f32_e32 v19, 0xbfb8aa3b, v3
	v_mul_f32_e32 v20, 0xbfb8aa3b, v4
	v_mul_f32_e32 v21, 0xbfb8aa3b, v5
	v_mul_f32_e32 v22, 0xbfb8aa3b, v6
	v_mul_f32_e32 v23, 0xbfb8aa3b, v7
	v_mul_f32_e32 v24, 0xbfb8aa3b, v8
	v_mul_f32_e32 v25, 0xbfb8aa3b, v9
	v_exp_f32_e32 v18, v18
	v_exp_f32_e32 v19, v19
	v_exp_f32_e32 v20, v20
	v_exp_f32_e32 v21, v21
	v_exp_f32_e32 v22, v22
	v_exp_f32_e32 v23, v23
	v_exp_f32_e32 v24, v24
	v_exp_f32_e32 v25, v25
	v_add_f32_e32 v18, 1.0, v18
	v_add_f32_e32 v19, 1.0, v19
	v_add_f32_e32 v20, 1.0, v20
	v_add_f32_e32 v21, 1.0, v21
	v_add_f32_e32 v22, 1.0, v22
	v_add_f32_e32 v23, 1.0, v23
	v_add_f32_e32 v24, 1.0, v24
	v_add_f32_e32 v25, 1.0, v25
	v_rcp_f32_e32 v18, v18
	v_rcp_f32_e32 v19, v19
	v_rcp_f32_e32 v20, v20
	v_rcp_f32_e32 v21, v21
	v_rcp_f32_e32 v22, v22
	v_rcp_f32_e32 v23, v23
	v_rcp_f32_e32 v24, v24
	v_rcp_f32_e32 v25, v25
	v_mul_f32_e32 v18, v2, v18
	v_mul_f32_e32 v19, v3, v19
	v_mul_f32_e32 v20, v4, v20
	v_mul_f32_e32 v21, v5, v21
	v_mul_f32_e32 v22, v6, v22
	v_mul_f32_e32 v23, v7, v23
	v_mul_f32_e32 v24, v8, v24
	v_mul_f32_e32 v25, v9, v25
	v_mul_f32_e32 v18, v10, v18
	v_mul_f32_e32 v19, v11, v19
	v_mul_f32_e32 v20, v12, v20
	v_mul_f32_e32 v21, v13, v21
	v_mul_f32_e32 v22, v14, v22
	v_mul_f32_e32 v23, v15, v23
	v_mul_f32_e32 v24, v16, v24
	v_mul_f32_e32 v25, v17, v25
	v_cvt_pk_bf16_f32 v26, v18, v19
	v_cvt_pk_bf16_f32 v27, v20, v21
	v_cvt_pk_bf16_f32 v28, v22, v23
	v_cvt_pk_bf16_f32 v29, v24, v25
	global_store_dwordx4 v[162:163], v[26:29], off sc1
	v_lshl_add_u64 v[162:163], v[162:163], 0, v[30:31]
	s_cmpk_gt_u32 s28, 0xbf
	s_cbranch_scc1 .LBB0_2504
	v_add_u32_e32 v32, 0x80, v32
	v_add_u32_e32 v157, 0xba, v157
	v_cmp_lt_u32_e32 vcc, 0x2bf, v32
	v_subrev_u32_e32 v152, 0x2c0, v32
	s_nop 1
	v_cndmask_b32_e32 v32, v32, v152, vcc
	v_addc_co_u32_e32 v157, vcc, 0, v157, vcc
	v_mul_u32_u24_e32 v152, 0x58000, v157
	v_lshl_add_u32 v152, v32, 4, v152
	v_mov_b32_e32 v153, 0
	v_lshl_add_u64 v[158:159], s[36:37], 0, v[152:153]
	v_mul_u32_u24_e32 v152, 0x2c000, v157
	v_lshl_add_u32 v152, v32, 4, v152
	v_lshl_add_u64 v[162:163], s[38:39], 0, v[152:153]
	v_lshlrev_b32_e32 v33, 5, v32
	v_and_b32_e32 v152, 0x7f, v157
	v_cmp_eq_u32_e64 s[40:41], 0, v152
	v_mov_b32_e32 v152, 0x2c00
	v_lshl_add_u64 v[160:161], v[158:159], 0, v[152:153]
	global_load_dwordx4 v[104:107], v33, s[12:13]
	global_load_dwordx4 v[108:111], v33, s[12:13] offset:16
	global_load_dwordx4 v[112:115], v33, s[14:15]
	global_load_dwordx4 v[116:119], v33, s[14:15] offset:16
	global_load_dwordx4 v[120:123], v33, s[16:17]
	global_load_dwordx4 v[124:127], v33, s[16:17] offset:16
	global_load_dwordx4 v[128:131], v33, s[18:19]
	global_load_dwordx4 v[132:135], v33, s[18:19] offset:16
	global_load_dwordx4 v[136:139], v33, s[20:21]
	global_load_dwordx4 v[140:143], v33, s[20:21] offset:16
	global_load_dwordx4 v[144:147], v33, s[22:23]
	global_load_dwordx4 v[148:151], v33, s[22:23] offset:16
	global_load_dwordx4 v[174:177], v33, s[24:25]
	global_load_dwordx4 v[178:181], v33, s[24:25] offset:16
	global_load_dwordx4 v[182:185], v33, s[26:27]
	global_load_dwordx4 v[186:189], v33, s[26:27] offset:16
	v_mov_b32_e32 v152, 0xffffa800
	v_mov_b32_e32 v153, -1
	v_lshl_add_u64 v[154:155], v[158:159], 0, v[152:153]
	global_load_dwordx4 v[238:241], v[154:155], off
	v_lshl_add_u64 v[154:155], v[154:155], 0, v[152:153]
	global_load_dwordx4 v[246:249], v[154:155], off
	v_lshl_add_u64 v[154:155], v[160:161], 0, v[152:153]
	global_load_dwordx4 v[242:245], v[154:155], off
	v_lshl_add_u64 v[154:155], v[154:155], 0, v[152:153]
	global_load_dwordx4 v[250:253], v[154:155], off
	global_load_dwordx4 v[36:39], v[158:159], off
	global_load_dwordx4 v[40:43], v[160:161], off
	v_lshl_add_u64 v[158:159], v[158:159], 0, v[164:165]
	v_lshl_add_u64 v[160:161], v[160:161], 0, v[164:165]
	global_load_dwordx4 v[44:47], v[158:159], off
	global_load_dwordx4 v[48:51], v[160:161], off
	v_lshl_add_u64 v[158:159], v[158:159], 0, v[164:165]
	v_lshl_add_u64 v[160:161], v[160:161], 0, v[164:165]
	global_load_dwordx4 v[52:55], v[158:159], off
	global_load_dwordx4 v[56:59], v[160:161], off
	v_lshl_add_u64 v[158:159], v[158:159], 0, v[164:165]
	v_lshl_add_u64 v[160:161], v[160:161], 0, v[164:165]
	global_load_dwordx4 v[60:63], v[158:159], off
	global_load_dwordx4 v[64:67], v[160:161], off
	v_lshl_add_u64 v[158:159], v[158:159], 0, v[164:165]
	v_lshl_add_u64 v[160:161], v[160:161], 0, v[164:165]
	global_load_dwordx4 v[68:71], v[158:159], off
	global_load_dwordx4 v[72:75], v[160:161], off
	v_lshl_add_u64 v[158:159], v[158:159], 0, v[164:165]
	v_lshl_add_u64 v[160:161], v[160:161], 0, v[164:165]
	global_load_dwordx4 v[76:79], v[158:159], off
	global_load_dwordx4 v[80:83], v[160:161], off
	v_lshl_add_u64 v[158:159], v[158:159], 0, v[164:165]
	v_lshl_add_u64 v[160:161], v[160:161], 0, v[164:165]
	global_load_dwordx4 v[88:91], v[158:159], off
	global_load_dwordx4 v[92:95], v[160:161], off
	v_lshl_add_u64 v[158:159], v[158:159], 0, v[164:165]
	v_lshl_add_u64 v[160:161], v[160:161], 0, v[164:165]
	global_load_dwordx4 v[96:99], v[158:159], off
	global_load_dwordx4 v[100:103], v[160:161], off
	v_lshl_add_u64 v[158:159], v[158:159], 0, v[164:165]
	v_lshl_add_u64 v[160:161], v[160:161], 0, v[164:165]
	s_waitcnt vmcnt(8)
	v_lshlrev_b32_e32 v222, 16, v238
	v_and_b32_e32 v223, 0xffff0000, v238
	v_lshlrev_b32_e32 v224, 16, v239
	v_and_b32_e32 v225, 0xffff0000, v239
	v_lshlrev_b32_e32 v226, 16, v240
	v_and_b32_e32 v227, 0xffff0000, v240
	v_lshlrev_b32_e32 v228, 16, v241
	v_and_b32_e32 v229, 0xffff0000, v241
	v_lshlrev_b32_e32 v206, 16, v246
	v_and_b32_e32 v207, 0xffff0000, v246
	v_lshlrev_b32_e32 v208, 16, v247
	v_and_b32_e32 v209, 0xffff0000, v247
	v_lshlrev_b32_e32 v210, 16, v248
	v_and_b32_e32 v211, 0xffff0000, v248
	v_lshlrev_b32_e32 v212, 16, v249
	v_and_b32_e32 v213, 0xffff0000, v249
	v_lshlrev_b32_e32 v230, 16, v242
	v_and_b32_e32 v231, 0xffff0000, v242
	v_lshlrev_b32_e32 v232, 16, v243
	v_and_b32_e32 v233, 0xffff0000, v243
	v_lshlrev_b32_e32 v234, 16, v244
	v_and_b32_e32 v235, 0xffff0000, v244
	v_lshlrev_b32_e32 v236, 16, v245
	v_and_b32_e32 v237, 0xffff0000, v245
	v_lshlrev_b32_e32 v214, 16, v250
	v_and_b32_e32 v215, 0xffff0000, v250
	v_lshlrev_b32_e32 v216, 16, v251
	v_and_b32_e32 v217, 0xffff0000, v251
	v_lshlrev_b32_e32 v218, 16, v252
	v_and_b32_e32 v219, 0xffff0000, v252
	v_lshlrev_b32_e32 v220, 16, v253
	v_and_b32_e32 v221, 0xffff0000, v253
	v_cndmask_b32_e64 v206, v206, 0, s[40:41]
	v_cndmask_b32_e64 v207, v207, 0, s[40:41]
	v_cndmask_b32_e64 v208, v208, 0, s[40:41]
	v_cndmask_b32_e64 v209, v209, 0, s[40:41]
	v_cndmask_b32_e64 v210, v210, 0, s[40:41]
	v_cndmask_b32_e64 v211, v211, 0, s[40:41]
	v_cndmask_b32_e64 v212, v212, 0, s[40:41]
	v_cndmask_b32_e64 v213, v213, 0, s[40:41]
	v_cndmask_b32_e64 v214, v214, 0, s[40:41]
	v_cndmask_b32_e64 v215, v215, 0, s[40:41]
	v_cndmask_b32_e64 v216, v216, 0, s[40:41]
	v_cndmask_b32_e64 v217, v217, 0, s[40:41]
	v_cndmask_b32_e64 v218, v218, 0, s[40:41]
	v_cndmask_b32_e64 v219, v219, 0, s[40:41]
	v_cndmask_b32_e64 v220, v220, 0, s[40:41]
	v_cndmask_b32_e64 v221, v221, 0, s[40:41]
	v_cndmask_b32_e64 v222, v222, 0, s[40:41]
	v_cndmask_b32_e64 v223, v223, 0, s[40:41]
	v_cndmask_b32_e64 v224, v224, 0, s[40:41]
	v_cndmask_b32_e64 v225, v225, 0, s[40:41]
	v_cndmask_b32_e64 v226, v226, 0, s[40:41]
	v_cndmask_b32_e64 v227, v227, 0, s[40:41]
	v_cndmask_b32_e64 v228, v228, 0, s[40:41]
	v_cndmask_b32_e64 v229, v229, 0, s[40:41]
	v_cndmask_b32_e64 v230, v230, 0, s[40:41]
	v_cndmask_b32_e64 v231, v231, 0, s[40:41]
	v_cndmask_b32_e64 v232, v232, 0, s[40:41]
	v_cndmask_b32_e64 v233, v233, 0, s[40:41]
	v_cndmask_b32_e64 v234, v234, 0, s[40:41]
	v_cndmask_b32_e64 v235, v235, 0, s[40:41]
	v_cndmask_b32_e64 v236, v236, 0, s[40:41]
	v_cndmask_b32_e64 v237, v237, 0, s[40:41]
	v_lshlrev_b32_e32 v190, 16, v36
	v_and_b32_e32 v191, 0xffff0000, v36
	v_lshlrev_b32_e32 v192, 16, v37
	v_and_b32_e32 v193, 0xffff0000, v37
	v_lshlrev_b32_e32 v194, 16, v38
	v_and_b32_e32 v195, 0xffff0000, v38
	v_lshlrev_b32_e32 v196, 16, v39
	v_and_b32_e32 v197, 0xffff0000, v39
	v_lshlrev_b32_e32 v198, 16, v40
	v_and_b32_e32 v199, 0xffff0000, v40
	v_lshlrev_b32_e32 v200, 16, v41
	v_and_b32_e32 v201, 0xffff0000, v41
	v_lshlrev_b32_e32 v202, 16, v42
	v_and_b32_e32 v203, 0xffff0000, v42
	v_lshlrev_b32_e32 v204, 16, v43
	v_and_b32_e32 v205, 0xffff0000, v43
	v_pk_fma_f32 v[2:3], v[104:105], v[206:207], v[174:175]
	v_pk_fma_f32 v[4:5], v[106:107], v[208:209], v[176:177]
	v_pk_fma_f32 v[6:7], v[108:109], v[210:211], v[178:179]
	v_pk_fma_f32 v[8:9], v[110:111], v[212:213], v[180:181]
	v_pk_fma_f32 v[10:11], v[112:113], v[214:215], v[182:183]
	v_pk_fma_f32 v[12:13], v[114:115], v[216:217], v[184:185]
	v_pk_fma_f32 v[14:15], v[116:117], v[218:219], v[186:187]
	v_pk_fma_f32 v[16:17], v[118:119], v[220:221], v[188:189]
	v_pk_fma_f32 v[2:3], v[120:121], v[222:223], v[2:3]
	v_pk_fma_f32 v[4:5], v[122:123], v[224:225], v[4:5]
	v_pk_fma_f32 v[6:7], v[124:125], v[226:227], v[6:7]
	v_pk_fma_f32 v[8:9], v[126:127], v[228:229], v[8:9]
	v_pk_fma_f32 v[10:11], v[128:129], v[230:231], v[10:11]
	v_pk_fma_f32 v[12:13], v[130:131], v[232:233], v[12:13]
	v_pk_fma_f32 v[14:15], v[132:133], v[234:235], v[14:15]
	v_pk_fma_f32 v[16:17], v[134:135], v[236:237], v[16:17]
	v_pk_fma_f32 v[2:3], v[136:137], v[190:191], v[2:3]
	v_pk_fma_f32 v[4:5], v[138:139], v[192:193], v[4:5]
	v_pk_fma_f32 v[6:7], v[140:141], v[194:195], v[6:7]
	v_pk_fma_f32 v[8:9], v[142:143], v[196:197], v[8:9]
	v_pk_fma_f32 v[10:11], v[144:145], v[198:199], v[10:11]
	v_pk_fma_f32 v[12:13], v[146:147], v[200:201], v[12:13]
	v_pk_fma_f32 v[14:15], v[148:149], v[202:203], v[14:15]
	v_pk_fma_f32 v[16:17], v[150:151], v[204:205], v[16:17]
	v_mul_f32_e32 v18, 0xbfb8aa3b, v2
	v_mul_f32_e32 v19, 0xbfb8aa3b, v3
	v_mul_f32_e32 v20, 0xbfb8aa3b, v4
	v_mul_f32_e32 v21, 0xbfb8aa3b, v5
	v_mul_f32_e32 v22, 0xbfb8aa3b, v6
	v_mul_f32_e32 v23, 0xbfb8aa3b, v7
	v_mul_f32_e32 v24, 0xbfb8aa3b, v8
	v_mul_f32_e32 v25, 0xbfb8aa3b, v9
	v_exp_f32_e32 v18, v18
	v_exp_f32_e32 v19, v19
	v_exp_f32_e32 v20, v20
	v_exp_f32_e32 v21, v21
	v_exp_f32_e32 v22, v22
	v_exp_f32_e32 v23, v23
	v_exp_f32_e32 v24, v24
	v_exp_f32_e32 v25, v25
	v_add_f32_e32 v18, 1.0, v18
	v_add_f32_e32 v19, 1.0, v19
	v_add_f32_e32 v20, 1.0, v20
	v_add_f32_e32 v21, 1.0, v21
	v_add_f32_e32 v22, 1.0, v22
	v_add_f32_e32 v23, 1.0, v23
	v_add_f32_e32 v24, 1.0, v24
	v_add_f32_e32 v25, 1.0, v25
	v_rcp_f32_e32 v18, v18
	v_rcp_f32_e32 v19, v19
	v_rcp_f32_e32 v20, v20
	v_rcp_f32_e32 v21, v21
	v_rcp_f32_e32 v22, v22
	v_rcp_f32_e32 v23, v23
	v_rcp_f32_e32 v24, v24
	v_rcp_f32_e32 v25, v25
	v_mul_f32_e32 v18, v2, v18
	v_mul_f32_e32 v19, v3, v19
	v_mul_f32_e32 v20, v4, v20
	v_mul_f32_e32 v21, v5, v21
	v_mul_f32_e32 v22, v6, v22
	v_mul_f32_e32 v23, v7, v23
	v_mul_f32_e32 v24, v8, v24
	v_mul_f32_e32 v25, v9, v25
	v_mul_f32_e32 v18, v10, v18
	v_mul_f32_e32 v19, v11, v19
	v_mul_f32_e32 v20, v12, v20
	v_mul_f32_e32 v21, v13, v21
	v_mul_f32_e32 v22, v14, v22
	v_mul_f32_e32 v23, v15, v23
	v_mul_f32_e32 v24, v16, v24
	v_mul_f32_e32 v25, v17, v25
	v_cvt_pk_bf16_f32 v26, v18, v19
	v_cvt_pk_bf16_f32 v27, v20, v21
	v_cvt_pk_bf16_f32 v28, v22, v23
	v_cvt_pk_bf16_f32 v29, v24, v25
	global_store_dwordx4 v[162:163], v[26:29], off sc1
	v_lshl_add_u64 v[162:163], v[162:163], 0, v[30:31]
	v_lshlrev_b32_e32 v206, 16, v44
	v_and_b32_e32 v207, 0xffff0000, v44
	v_lshlrev_b32_e32 v208, 16, v45
	v_and_b32_e32 v209, 0xffff0000, v45
	v_lshlrev_b32_e32 v210, 16, v46
	v_and_b32_e32 v211, 0xffff0000, v46
	v_lshlrev_b32_e32 v212, 16, v47
	v_and_b32_e32 v213, 0xffff0000, v47
	v_lshlrev_b32_e32 v214, 16, v48
	v_and_b32_e32 v215, 0xffff0000, v48
	v_lshlrev_b32_e32 v216, 16, v49
	v_and_b32_e32 v217, 0xffff0000, v49
	v_lshlrev_b32_e32 v218, 16, v50
	v_and_b32_e32 v219, 0xffff0000, v50
	v_lshlrev_b32_e32 v220, 16, v51
	v_and_b32_e32 v221, 0xffff0000, v51
	v_pk_fma_f32 v[2:3], v[104:105], v[222:223], v[174:175]
	v_pk_fma_f32 v[4:5], v[106:107], v[224:225], v[176:177]
	v_pk_fma_f32 v[6:7], v[108:109], v[226:227], v[178:179]
	v_pk_fma_f32 v[8:9], v[110:111], v[228:229], v[180:181]
	v_pk_fma_f32 v[10:11], v[112:113], v[230:231], v[182:183]
	v_pk_fma_f32 v[12:13], v[114:115], v[232:233], v[184:185]
	v_pk_fma_f32 v[14:15], v[116:117], v[234:235], v[186:187]
	v_pk_fma_f32 v[16:17], v[118:119], v[236:237], v[188:189]
	v_pk_fma_f32 v[2:3], v[120:121], v[190:191], v[2:3]
	v_pk_fma_f32 v[4:5], v[122:123], v[192:193], v[4:5]
	v_pk_fma_f32 v[6:7], v[124:125], v[194:195], v[6:7]
	v_pk_fma_f32 v[8:9], v[126:127], v[196:197], v[8:9]
	v_pk_fma_f32 v[10:11], v[128:129], v[198:199], v[10:11]
	v_pk_fma_f32 v[12:13], v[130:131], v[200:201], v[12:13]
	v_pk_fma_f32 v[14:15], v[132:133], v[202:203], v[14:15]
	v_pk_fma_f32 v[16:17], v[134:135], v[204:205], v[16:17]
	v_pk_fma_f32 v[2:3], v[136:137], v[206:207], v[2:3]
	v_pk_fma_f32 v[4:5], v[138:139], v[208:209], v[4:5]
	v_pk_fma_f32 v[6:7], v[140:141], v[210:211], v[6:7]
	v_pk_fma_f32 v[8:9], v[142:143], v[212:213], v[8:9]
	v_pk_fma_f32 v[10:11], v[144:145], v[214:215], v[10:11]
	v_pk_fma_f32 v[12:13], v[146:147], v[216:217], v[12:13]
	v_pk_fma_f32 v[14:15], v[148:149], v[218:219], v[14:15]
	v_pk_fma_f32 v[16:17], v[150:151], v[220:221], v[16:17]
	v_mul_f32_e32 v18, 0xbfb8aa3b, v2
	v_mul_f32_e32 v19, 0xbfb8aa3b, v3
	v_mul_f32_e32 v20, 0xbfb8aa3b, v4
	v_mul_f32_e32 v21, 0xbfb8aa3b, v5
	v_mul_f32_e32 v22, 0xbfb8aa3b, v6
	v_mul_f32_e32 v23, 0xbfb8aa3b, v7
	v_mul_f32_e32 v24, 0xbfb8aa3b, v8
	v_mul_f32_e32 v25, 0xbfb8aa3b, v9
	v_exp_f32_e32 v18, v18
	v_exp_f32_e32 v19, v19
	v_exp_f32_e32 v20, v20
	v_exp_f32_e32 v21, v21
	v_exp_f32_e32 v22, v22
	v_exp_f32_e32 v23, v23
	v_exp_f32_e32 v24, v24
	v_exp_f32_e32 v25, v25
	v_add_f32_e32 v18, 1.0, v18
	v_add_f32_e32 v19, 1.0, v19
	v_add_f32_e32 v20, 1.0, v20
	v_add_f32_e32 v21, 1.0, v21
	v_add_f32_e32 v22, 1.0, v22
	v_add_f32_e32 v23, 1.0, v23
	v_add_f32_e32 v24, 1.0, v24
	v_add_f32_e32 v25, 1.0, v25
	v_rcp_f32_e32 v18, v18
	v_rcp_f32_e32 v19, v19
	v_rcp_f32_e32 v20, v20
	v_rcp_f32_e32 v21, v21
	v_rcp_f32_e32 v22, v22
	v_rcp_f32_e32 v23, v23
	v_rcp_f32_e32 v24, v24
	v_rcp_f32_e32 v25, v25
	v_mul_f32_e32 v18, v2, v18
	v_mul_f32_e32 v19, v3, v19
	v_mul_f32_e32 v20, v4, v20
	v_mul_f32_e32 v21, v5, v21
	v_mul_f32_e32 v22, v6, v22
	v_mul_f32_e32 v23, v7, v23
	v_mul_f32_e32 v24, v8, v24
	v_mul_f32_e32 v25, v9, v25
	v_mul_f32_e32 v18, v10, v18
	v_mul_f32_e32 v19, v11, v19
	v_mul_f32_e32 v20, v12, v20
	v_mul_f32_e32 v21, v13, v21
	v_mul_f32_e32 v22, v14, v22
	v_mul_f32_e32 v23, v15, v23
	v_mul_f32_e32 v24, v16, v24
	v_mul_f32_e32 v25, v17, v25
	v_cvt_pk_bf16_f32 v26, v18, v19
	v_cvt_pk_bf16_f32 v27, v20, v21
	v_cvt_pk_bf16_f32 v28, v22, v23
	v_cvt_pk_bf16_f32 v29, v24, v25
	global_store_dwordx4 v[162:163], v[26:29], off sc1
	v_lshl_add_u64 v[162:163], v[162:163], 0, v[30:31]
	v_lshlrev_b32_e32 v222, 16, v52
	v_and_b32_e32 v223, 0xffff0000, v52
	v_lshlrev_b32_e32 v224, 16, v53
	v_and_b32_e32 v225, 0xffff0000, v53
	v_lshlrev_b32_e32 v226, 16, v54
	v_and_b32_e32 v227, 0xffff0000, v54
	v_lshlrev_b32_e32 v228, 16, v55
	v_and_b32_e32 v229, 0xffff0000, v55
	v_lshlrev_b32_e32 v230, 16, v56
	v_and_b32_e32 v231, 0xffff0000, v56
	v_lshlrev_b32_e32 v232, 16, v57
	v_and_b32_e32 v233, 0xffff0000, v57
	v_lshlrev_b32_e32 v234, 16, v58
	v_and_b32_e32 v235, 0xffff0000, v58
	v_lshlrev_b32_e32 v236, 16, v59
	v_and_b32_e32 v237, 0xffff0000, v59
	v_pk_fma_f32 v[2:3], v[104:105], v[190:191], v[174:175]
	v_pk_fma_f32 v[4:5], v[106:107], v[192:193], v[176:177]
	v_pk_fma_f32 v[6:7], v[108:109], v[194:195], v[178:179]
	v_pk_fma_f32 v[8:9], v[110:111], v[196:197], v[180:181]
	v_pk_fma_f32 v[10:11], v[112:113], v[198:199], v[182:183]
	v_pk_fma_f32 v[12:13], v[114:115], v[200:201], v[184:185]
	v_pk_fma_f32 v[14:15], v[116:117], v[202:203], v[186:187]
	v_pk_fma_f32 v[16:17], v[118:119], v[204:205], v[188:189]
	v_pk_fma_f32 v[2:3], v[120:121], v[206:207], v[2:3]
	v_pk_fma_f32 v[4:5], v[122:123], v[208:209], v[4:5]
	v_pk_fma_f32 v[6:7], v[124:125], v[210:211], v[6:7]
	v_pk_fma_f32 v[8:9], v[126:127], v[212:213], v[8:9]
	v_pk_fma_f32 v[10:11], v[128:129], v[214:215], v[10:11]
	v_pk_fma_f32 v[12:13], v[130:131], v[216:217], v[12:13]
	v_pk_fma_f32 v[14:15], v[132:133], v[218:219], v[14:15]
	v_pk_fma_f32 v[16:17], v[134:135], v[220:221], v[16:17]
	v_pk_fma_f32 v[2:3], v[136:137], v[222:223], v[2:3]
	v_pk_fma_f32 v[4:5], v[138:139], v[224:225], v[4:5]
	v_pk_fma_f32 v[6:7], v[140:141], v[226:227], v[6:7]
	v_pk_fma_f32 v[8:9], v[142:143], v[228:229], v[8:9]
	v_pk_fma_f32 v[10:11], v[144:145], v[230:231], v[10:11]
	v_pk_fma_f32 v[12:13], v[146:147], v[232:233], v[12:13]
	v_pk_fma_f32 v[14:15], v[148:149], v[234:235], v[14:15]
	v_pk_fma_f32 v[16:17], v[150:151], v[236:237], v[16:17]
	v_mul_f32_e32 v18, 0xbfb8aa3b, v2
	v_mul_f32_e32 v19, 0xbfb8aa3b, v3
	v_mul_f32_e32 v20, 0xbfb8aa3b, v4
	v_mul_f32_e32 v21, 0xbfb8aa3b, v5
	v_mul_f32_e32 v22, 0xbfb8aa3b, v6
	v_mul_f32_e32 v23, 0xbfb8aa3b, v7
	v_mul_f32_e32 v24, 0xbfb8aa3b, v8
	v_mul_f32_e32 v25, 0xbfb8aa3b, v9
	v_exp_f32_e32 v18, v18
	v_exp_f32_e32 v19, v19
	v_exp_f32_e32 v20, v20
	v_exp_f32_e32 v21, v21
	v_exp_f32_e32 v22, v22
	v_exp_f32_e32 v23, v23
	v_exp_f32_e32 v24, v24
	v_exp_f32_e32 v25, v25
	v_add_f32_e32 v18, 1.0, v18
	v_add_f32_e32 v19, 1.0, v19
	v_add_f32_e32 v20, 1.0, v20
	v_add_f32_e32 v21, 1.0, v21
	v_add_f32_e32 v22, 1.0, v22
	v_add_f32_e32 v23, 1.0, v23
	v_add_f32_e32 v24, 1.0, v24
	v_add_f32_e32 v25, 1.0, v25
	v_rcp_f32_e32 v18, v18
	v_rcp_f32_e32 v19, v19
	v_rcp_f32_e32 v20, v20
	v_rcp_f32_e32 v21, v21
	v_rcp_f32_e32 v22, v22
	v_rcp_f32_e32 v23, v23
	v_rcp_f32_e32 v24, v24
	v_rcp_f32_e32 v25, v25
	v_mul_f32_e32 v18, v2, v18
	v_mul_f32_e32 v19, v3, v19
	v_mul_f32_e32 v20, v4, v20
	v_mul_f32_e32 v21, v5, v21
	v_mul_f32_e32 v22, v6, v22
	v_mul_f32_e32 v23, v7, v23
	v_mul_f32_e32 v24, v8, v24
	v_mul_f32_e32 v25, v9, v25
	v_mul_f32_e32 v18, v10, v18
	v_mul_f32_e32 v19, v11, v19
	v_mul_f32_e32 v20, v12, v20
	v_mul_f32_e32 v21, v13, v21
	v_mul_f32_e32 v22, v14, v22
	v_mul_f32_e32 v23, v15, v23
	v_mul_f32_e32 v24, v16, v24
	v_mul_f32_e32 v25, v17, v25
	v_cvt_pk_bf16_f32 v26, v18, v19
	v_cvt_pk_bf16_f32 v27, v20, v21
	v_cvt_pk_bf16_f32 v28, v22, v23
	v_cvt_pk_bf16_f32 v29, v24, v25
	global_store_dwordx4 v[162:163], v[26:29], off sc1
	v_lshl_add_u64 v[162:163], v[162:163], 0, v[30:31]
	v_lshlrev_b32_e32 v190, 16, v60
	v_and_b32_e32 v191, 0xffff0000, v60
	v_lshlrev_b32_e32 v192, 16, v61
	v_and_b32_e32 v193, 0xffff0000, v61
	v_lshlrev_b32_e32 v194, 16, v62
	v_and_b32_e32 v195, 0xffff0000, v62
	v_lshlrev_b32_e32 v196, 16, v63
	v_and_b32_e32 v197, 0xffff0000, v63
	v_lshlrev_b32_e32 v198, 16, v64
	v_and_b32_e32 v199, 0xffff0000, v64
	v_lshlrev_b32_e32 v200, 16, v65
	v_and_b32_e32 v201, 0xffff0000, v65
	v_lshlrev_b32_e32 v202, 16, v66
	v_and_b32_e32 v203, 0xffff0000, v66
	v_lshlrev_b32_e32 v204, 16, v67
	v_and_b32_e32 v205, 0xffff0000, v67
	v_pk_fma_f32 v[2:3], v[104:105], v[206:207], v[174:175]
	v_pk_fma_f32 v[4:5], v[106:107], v[208:209], v[176:177]
	v_pk_fma_f32 v[6:7], v[108:109], v[210:211], v[178:179]
	v_pk_fma_f32 v[8:9], v[110:111], v[212:213], v[180:181]
	v_pk_fma_f32 v[10:11], v[112:113], v[214:215], v[182:183]
	v_pk_fma_f32 v[12:13], v[114:115], v[216:217], v[184:185]
	v_pk_fma_f32 v[14:15], v[116:117], v[218:219], v[186:187]
	v_pk_fma_f32 v[16:17], v[118:119], v[220:221], v[188:189]
	v_pk_fma_f32 v[2:3], v[120:121], v[222:223], v[2:3]
	v_pk_fma_f32 v[4:5], v[122:123], v[224:225], v[4:5]
	v_pk_fma_f32 v[6:7], v[124:125], v[226:227], v[6:7]
	v_pk_fma_f32 v[8:9], v[126:127], v[228:229], v[8:9]
	v_pk_fma_f32 v[10:11], v[128:129], v[230:231], v[10:11]
	v_pk_fma_f32 v[12:13], v[130:131], v[232:233], v[12:13]
	v_pk_fma_f32 v[14:15], v[132:133], v[234:235], v[14:15]
	v_pk_fma_f32 v[16:17], v[134:135], v[236:237], v[16:17]
	v_pk_fma_f32 v[2:3], v[136:137], v[190:191], v[2:3]
	v_pk_fma_f32 v[4:5], v[138:139], v[192:193], v[4:5]
	v_pk_fma_f32 v[6:7], v[140:141], v[194:195], v[6:7]
	v_pk_fma_f32 v[8:9], v[142:143], v[196:197], v[8:9]
	v_pk_fma_f32 v[10:11], v[144:145], v[198:199], v[10:11]
	v_pk_fma_f32 v[12:13], v[146:147], v[200:201], v[12:13]
	v_pk_fma_f32 v[14:15], v[148:149], v[202:203], v[14:15]
	v_pk_fma_f32 v[16:17], v[150:151], v[204:205], v[16:17]
	v_mul_f32_e32 v18, 0xbfb8aa3b, v2
	v_mul_f32_e32 v19, 0xbfb8aa3b, v3
	v_mul_f32_e32 v20, 0xbfb8aa3b, v4
	v_mul_f32_e32 v21, 0xbfb8aa3b, v5
	v_mul_f32_e32 v22, 0xbfb8aa3b, v6
	v_mul_f32_e32 v23, 0xbfb8aa3b, v7
	v_mul_f32_e32 v24, 0xbfb8aa3b, v8
	v_mul_f32_e32 v25, 0xbfb8aa3b, v9
	v_exp_f32_e32 v18, v18
	v_exp_f32_e32 v19, v19
	v_exp_f32_e32 v20, v20
	v_exp_f32_e32 v21, v21
	v_exp_f32_e32 v22, v22
	v_exp_f32_e32 v23, v23
	v_exp_f32_e32 v24, v24
	v_exp_f32_e32 v25, v25
	v_add_f32_e32 v18, 1.0, v18
	v_add_f32_e32 v19, 1.0, v19
	v_add_f32_e32 v20, 1.0, v20
	v_add_f32_e32 v21, 1.0, v21
	v_add_f32_e32 v22, 1.0, v22
	v_add_f32_e32 v23, 1.0, v23
	v_add_f32_e32 v24, 1.0, v24
	v_add_f32_e32 v25, 1.0, v25
	v_rcp_f32_e32 v18, v18
	v_rcp_f32_e32 v19, v19
	v_rcp_f32_e32 v20, v20
	v_rcp_f32_e32 v21, v21
	v_rcp_f32_e32 v22, v22
	v_rcp_f32_e32 v23, v23
	v_rcp_f32_e32 v24, v24
	v_rcp_f32_e32 v25, v25
	v_mul_f32_e32 v18, v2, v18
	v_mul_f32_e32 v19, v3, v19
	v_mul_f32_e32 v20, v4, v20
	v_mul_f32_e32 v21, v5, v21
	v_mul_f32_e32 v22, v6, v22
	v_mul_f32_e32 v23, v7, v23
	v_mul_f32_e32 v24, v8, v24
	v_mul_f32_e32 v25, v9, v25
	v_mul_f32_e32 v18, v10, v18
	v_mul_f32_e32 v19, v11, v19
	v_mul_f32_e32 v20, v12, v20
	v_mul_f32_e32 v21, v13, v21
	v_mul_f32_e32 v22, v14, v22
	v_mul_f32_e32 v23, v15, v23
	v_mul_f32_e32 v24, v16, v24
	v_mul_f32_e32 v25, v17, v25
	v_cvt_pk_bf16_f32 v26, v18, v19
	v_cvt_pk_bf16_f32 v27, v20, v21
	v_cvt_pk_bf16_f32 v28, v22, v23
	v_cvt_pk_bf16_f32 v29, v24, v25
	global_store_dwordx4 v[162:163], v[26:29], off sc1
	v_lshl_add_u64 v[162:163], v[162:163], 0, v[30:31]
	global_load_dwordx4 v[36:39], v[158:159], off
	global_load_dwordx4 v[40:43], v[160:161], off
	v_lshl_add_u64 v[158:159], v[158:159], 0, v[164:165]
	v_lshl_add_u64 v[160:161], v[160:161], 0, v[164:165]
	global_load_dwordx4 v[44:47], v[158:159], off
	global_load_dwordx4 v[48:51], v[160:161], off
	v_lshl_add_u64 v[158:159], v[158:159], 0, v[164:165]
	v_lshl_add_u64 v[160:161], v[160:161], 0, v[164:165]
	global_load_dwordx4 v[52:55], v[158:159], off
	global_load_dwordx4 v[56:59], v[160:161], off
	v_lshl_add_u64 v[158:159], v[158:159], 0, v[164:165]
	v_lshl_add_u64 v[160:161], v[160:161], 0, v[164:165]
	global_load_dwordx4 v[60:63], v[158:159], off
	global_load_dwordx4 v[64:67], v[160:161], off
	v_lshl_add_u64 v[158:159], v[158:159], 0, v[164:165]
	v_lshl_add_u64 v[160:161], v[160:161], 0, v[164:165]
	s_waitcnt vmcnt(12)
	v_lshlrev_b32_e32 v206, 16, v68
	v_and_b32_e32 v207, 0xffff0000, v68
	v_lshlrev_b32_e32 v208, 16, v69
	v_and_b32_e32 v209, 0xffff0000, v69
	v_lshlrev_b32_e32 v210, 16, v70
	v_and_b32_e32 v211, 0xffff0000, v70
	v_lshlrev_b32_e32 v212, 16, v71
	v_and_b32_e32 v213, 0xffff0000, v71
	v_lshlrev_b32_e32 v214, 16, v72
	v_and_b32_e32 v215, 0xffff0000, v72
	v_lshlrev_b32_e32 v216, 16, v73
	v_and_b32_e32 v217, 0xffff0000, v73
	v_lshlrev_b32_e32 v218, 16, v74
	v_and_b32_e32 v219, 0xffff0000, v74
	v_lshlrev_b32_e32 v220, 16, v75
	v_and_b32_e32 v221, 0xffff0000, v75
	v_pk_fma_f32 v[2:3], v[104:105], v[222:223], v[174:175]
	v_pk_fma_f32 v[4:5], v[106:107], v[224:225], v[176:177]
	v_pk_fma_f32 v[6:7], v[108:109], v[226:227], v[178:179]
	v_pk_fma_f32 v[8:9], v[110:111], v[228:229], v[180:181]
	v_pk_fma_f32 v[10:11], v[112:113], v[230:231], v[182:183]
	v_pk_fma_f32 v[12:13], v[114:115], v[232:233], v[184:185]
	v_pk_fma_f32 v[14:15], v[116:117], v[234:235], v[186:187]
	v_pk_fma_f32 v[16:17], v[118:119], v[236:237], v[188:189]
	v_pk_fma_f32 v[2:3], v[120:121], v[190:191], v[2:3]
	v_pk_fma_f32 v[4:5], v[122:123], v[192:193], v[4:5]
	v_pk_fma_f32 v[6:7], v[124:125], v[194:195], v[6:7]
	v_pk_fma_f32 v[8:9], v[126:127], v[196:197], v[8:9]
	v_pk_fma_f32 v[10:11], v[128:129], v[198:199], v[10:11]
	v_pk_fma_f32 v[12:13], v[130:131], v[200:201], v[12:13]
	v_pk_fma_f32 v[14:15], v[132:133], v[202:203], v[14:15]
	v_pk_fma_f32 v[16:17], v[134:135], v[204:205], v[16:17]
	v_pk_fma_f32 v[2:3], v[136:137], v[206:207], v[2:3]
	v_pk_fma_f32 v[4:5], v[138:139], v[208:209], v[4:5]
	v_pk_fma_f32 v[6:7], v[140:141], v[210:211], v[6:7]
	v_pk_fma_f32 v[8:9], v[142:143], v[212:213], v[8:9]
	v_pk_fma_f32 v[10:11], v[144:145], v[214:215], v[10:11]
	v_pk_fma_f32 v[12:13], v[146:147], v[216:217], v[12:13]
	v_pk_fma_f32 v[14:15], v[148:149], v[218:219], v[14:15]
	v_pk_fma_f32 v[16:17], v[150:151], v[220:221], v[16:17]
	v_mul_f32_e32 v18, 0xbfb8aa3b, v2
	v_mul_f32_e32 v19, 0xbfb8aa3b, v3
	v_mul_f32_e32 v20, 0xbfb8aa3b, v4
	v_mul_f32_e32 v21, 0xbfb8aa3b, v5
	v_mul_f32_e32 v22, 0xbfb8aa3b, v6
	v_mul_f32_e32 v23, 0xbfb8aa3b, v7
	v_mul_f32_e32 v24, 0xbfb8aa3b, v8
	v_mul_f32_e32 v25, 0xbfb8aa3b, v9
	v_exp_f32_e32 v18, v18
	v_exp_f32_e32 v19, v19
	v_exp_f32_e32 v20, v20
	v_exp_f32_e32 v21, v21
	v_exp_f32_e32 v22, v22
	v_exp_f32_e32 v23, v23
	v_exp_f32_e32 v24, v24
	v_exp_f32_e32 v25, v25
	v_add_f32_e32 v18, 1.0, v18
	v_add_f32_e32 v19, 1.0, v19
	v_add_f32_e32 v20, 1.0, v20
	v_add_f32_e32 v21, 1.0, v21
	v_add_f32_e32 v22, 1.0, v22
	v_add_f32_e32 v23, 1.0, v23
	v_add_f32_e32 v24, 1.0, v24
	v_add_f32_e32 v25, 1.0, v25
	v_rcp_f32_e32 v18, v18
	v_rcp_f32_e32 v19, v19
	v_rcp_f32_e32 v20, v20
	v_rcp_f32_e32 v21, v21
	v_rcp_f32_e32 v22, v22
	v_rcp_f32_e32 v23, v23
	v_rcp_f32_e32 v24, v24
	v_rcp_f32_e32 v25, v25
	v_mul_f32_e32 v18, v2, v18
	v_mul_f32_e32 v19, v3, v19
	v_mul_f32_e32 v20, v4, v20
	v_mul_f32_e32 v21, v5, v21
	v_mul_f32_e32 v22, v6, v22
	v_mul_f32_e32 v23, v7, v23
	v_mul_f32_e32 v24, v8, v24
	v_mul_f32_e32 v25, v9, v25
	v_mul_f32_e32 v18, v10, v18
	v_mul_f32_e32 v19, v11, v19
	v_mul_f32_e32 v20, v12, v20
	v_mul_f32_e32 v21, v13, v21
	v_mul_f32_e32 v22, v14, v22
	v_mul_f32_e32 v23, v15, v23
	v_mul_f32_e32 v24, v16, v24
	v_mul_f32_e32 v25, v17, v25
	v_cvt_pk_bf16_f32 v26, v18, v19
	v_cvt_pk_bf16_f32 v27, v20, v21
	v_cvt_pk_bf16_f32 v28, v22, v23
	v_cvt_pk_bf16_f32 v29, v24, v25
	global_store_dwordx4 v[162:163], v[26:29], off sc1
	v_lshl_add_u64 v[162:163], v[162:163], 0, v[30:31]
	v_lshlrev_b32_e32 v222, 16, v76
	v_and_b32_e32 v223, 0xffff0000, v76
	v_lshlrev_b32_e32 v224, 16, v77
	v_and_b32_e32 v225, 0xffff0000, v77
	v_lshlrev_b32_e32 v226, 16, v78
	v_and_b32_e32 v227, 0xffff0000, v78
	v_lshlrev_b32_e32 v228, 16, v79
	v_and_b32_e32 v229, 0xffff0000, v79
	v_lshlrev_b32_e32 v230, 16, v80
	v_and_b32_e32 v231, 0xffff0000, v80
	v_lshlrev_b32_e32 v232, 16, v81
	v_and_b32_e32 v233, 0xffff0000, v81
	v_lshlrev_b32_e32 v234, 16, v82
	v_and_b32_e32 v235, 0xffff0000, v82
	v_lshlrev_b32_e32 v236, 16, v83
	v_and_b32_e32 v237, 0xffff0000, v83
	v_pk_fma_f32 v[2:3], v[104:105], v[190:191], v[174:175]
	v_pk_fma_f32 v[4:5], v[106:107], v[192:193], v[176:177]
	v_pk_fma_f32 v[6:7], v[108:109], v[194:195], v[178:179]
	v_pk_fma_f32 v[8:9], v[110:111], v[196:197], v[180:181]
	v_pk_fma_f32 v[10:11], v[112:113], v[198:199], v[182:183]
	v_pk_fma_f32 v[12:13], v[114:115], v[200:201], v[184:185]
	v_pk_fma_f32 v[14:15], v[116:117], v[202:203], v[186:187]
	v_pk_fma_f32 v[16:17], v[118:119], v[204:205], v[188:189]
	v_pk_fma_f32 v[2:3], v[120:121], v[206:207], v[2:3]
	v_pk_fma_f32 v[4:5], v[122:123], v[208:209], v[4:5]
	v_pk_fma_f32 v[6:7], v[124:125], v[210:211], v[6:7]
	v_pk_fma_f32 v[8:9], v[126:127], v[212:213], v[8:9]
	v_pk_fma_f32 v[10:11], v[128:129], v[214:215], v[10:11]
	v_pk_fma_f32 v[12:13], v[130:131], v[216:217], v[12:13]
	v_pk_fma_f32 v[14:15], v[132:133], v[218:219], v[14:15]
	v_pk_fma_f32 v[16:17], v[134:135], v[220:221], v[16:17]
	v_pk_fma_f32 v[2:3], v[136:137], v[222:223], v[2:3]
	v_pk_fma_f32 v[4:5], v[138:139], v[224:225], v[4:5]
	v_pk_fma_f32 v[6:7], v[140:141], v[226:227], v[6:7]
	v_pk_fma_f32 v[8:9], v[142:143], v[228:229], v[8:9]
	v_pk_fma_f32 v[10:11], v[144:145], v[230:231], v[10:11]
	v_pk_fma_f32 v[12:13], v[146:147], v[232:233], v[12:13]
	v_pk_fma_f32 v[14:15], v[148:149], v[234:235], v[14:15]
	v_pk_fma_f32 v[16:17], v[150:151], v[236:237], v[16:17]
	v_mul_f32_e32 v18, 0xbfb8aa3b, v2
	v_mul_f32_e32 v19, 0xbfb8aa3b, v3
	v_mul_f32_e32 v20, 0xbfb8aa3b, v4
	v_mul_f32_e32 v21, 0xbfb8aa3b, v5
	v_mul_f32_e32 v22, 0xbfb8aa3b, v6
	v_mul_f32_e32 v23, 0xbfb8aa3b, v7
	v_mul_f32_e32 v24, 0xbfb8aa3b, v8
	v_mul_f32_e32 v25, 0xbfb8aa3b, v9
	v_exp_f32_e32 v18, v18
	v_exp_f32_e32 v19, v19
	v_exp_f32_e32 v20, v20
	v_exp_f32_e32 v21, v21
	v_exp_f32_e32 v22, v22
	v_exp_f32_e32 v23, v23
	v_exp_f32_e32 v24, v24
	v_exp_f32_e32 v25, v25
	v_add_f32_e32 v18, 1.0, v18
	v_add_f32_e32 v19, 1.0, v19
	v_add_f32_e32 v20, 1.0, v20
	v_add_f32_e32 v21, 1.0, v21
	v_add_f32_e32 v22, 1.0, v22
	v_add_f32_e32 v23, 1.0, v23
	v_add_f32_e32 v24, 1.0, v24
	v_add_f32_e32 v25, 1.0, v25
	v_rcp_f32_e32 v18, v18
	v_rcp_f32_e32 v19, v19
	v_rcp_f32_e32 v20, v20
	v_rcp_f32_e32 v21, v21
	v_rcp_f32_e32 v22, v22
	v_rcp_f32_e32 v23, v23
	v_rcp_f32_e32 v24, v24
	v_rcp_f32_e32 v25, v25
	v_mul_f32_e32 v18, v2, v18
	v_mul_f32_e32 v19, v3, v19
	v_mul_f32_e32 v20, v4, v20
	v_mul_f32_e32 v21, v5, v21
	v_mul_f32_e32 v22, v6, v22
	v_mul_f32_e32 v23, v7, v23
	v_mul_f32_e32 v24, v8, v24
	v_mul_f32_e32 v25, v9, v25
	v_mul_f32_e32 v18, v10, v18
	v_mul_f32_e32 v19, v11, v19
	v_mul_f32_e32 v20, v12, v20
	v_mul_f32_e32 v21, v13, v21
	v_mul_f32_e32 v22, v14, v22
	v_mul_f32_e32 v23, v15, v23
	v_mul_f32_e32 v24, v16, v24
	v_mul_f32_e32 v25, v17, v25
	v_cvt_pk_bf16_f32 v26, v18, v19
	v_cvt_pk_bf16_f32 v27, v20, v21
	v_cvt_pk_bf16_f32 v28, v22, v23
	v_cvt_pk_bf16_f32 v29, v24, v25
	global_store_dwordx4 v[162:163], v[26:29], off sc1
	v_lshl_add_u64 v[162:163], v[162:163], 0, v[30:31]
	v_lshlrev_b32_e32 v190, 16, v88
	v_and_b32_e32 v191, 0xffff0000, v88
	v_lshlrev_b32_e32 v192, 16, v89
	v_and_b32_e32 v193, 0xffff0000, v89
	v_lshlrev_b32_e32 v194, 16, v90
	v_and_b32_e32 v195, 0xffff0000, v90
	v_lshlrev_b32_e32 v196, 16, v91
	v_and_b32_e32 v197, 0xffff0000, v91
	v_lshlrev_b32_e32 v198, 16, v92
	v_and_b32_e32 v199, 0xffff0000, v92
	v_lshlrev_b32_e32 v200, 16, v93
	v_and_b32_e32 v201, 0xffff0000, v93
	v_lshlrev_b32_e32 v202, 16, v94
	v_and_b32_e32 v203, 0xffff0000, v94
	v_lshlrev_b32_e32 v204, 16, v95
	v_and_b32_e32 v205, 0xffff0000, v95
	v_pk_fma_f32 v[2:3], v[104:105], v[206:207], v[174:175]
	v_pk_fma_f32 v[4:5], v[106:107], v[208:209], v[176:177]
	v_pk_fma_f32 v[6:7], v[108:109], v[210:211], v[178:179]
	v_pk_fma_f32 v[8:9], v[110:111], v[212:213], v[180:181]
	v_pk_fma_f32 v[10:11], v[112:113], v[214:215], v[182:183]
	v_pk_fma_f32 v[12:13], v[114:115], v[216:217], v[184:185]
	v_pk_fma_f32 v[14:15], v[116:117], v[218:219], v[186:187]
	v_pk_fma_f32 v[16:17], v[118:119], v[220:221], v[188:189]
	v_pk_fma_f32 v[2:3], v[120:121], v[222:223], v[2:3]
	v_pk_fma_f32 v[4:5], v[122:123], v[224:225], v[4:5]
	v_pk_fma_f32 v[6:7], v[124:125], v[226:227], v[6:7]
	v_pk_fma_f32 v[8:9], v[126:127], v[228:229], v[8:9]
	v_pk_fma_f32 v[10:11], v[128:129], v[230:231], v[10:11]
	v_pk_fma_f32 v[12:13], v[130:131], v[232:233], v[12:13]
	v_pk_fma_f32 v[14:15], v[132:133], v[234:235], v[14:15]
	v_pk_fma_f32 v[16:17], v[134:135], v[236:237], v[16:17]
	v_pk_fma_f32 v[2:3], v[136:137], v[190:191], v[2:3]
	v_pk_fma_f32 v[4:5], v[138:139], v[192:193], v[4:5]
	v_pk_fma_f32 v[6:7], v[140:141], v[194:195], v[6:7]
	v_pk_fma_f32 v[8:9], v[142:143], v[196:197], v[8:9]
	v_pk_fma_f32 v[10:11], v[144:145], v[198:199], v[10:11]
	v_pk_fma_f32 v[12:13], v[146:147], v[200:201], v[12:13]
	v_pk_fma_f32 v[14:15], v[148:149], v[202:203], v[14:15]
	v_pk_fma_f32 v[16:17], v[150:151], v[204:205], v[16:17]
	v_mul_f32_e32 v18, 0xbfb8aa3b, v2
	v_mul_f32_e32 v19, 0xbfb8aa3b, v3
	v_mul_f32_e32 v20, 0xbfb8aa3b, v4
	v_mul_f32_e32 v21, 0xbfb8aa3b, v5
	v_mul_f32_e32 v22, 0xbfb8aa3b, v6
	v_mul_f32_e32 v23, 0xbfb8aa3b, v7
	v_mul_f32_e32 v24, 0xbfb8aa3b, v8
	v_mul_f32_e32 v25, 0xbfb8aa3b, v9
	v_exp_f32_e32 v18, v18
	v_exp_f32_e32 v19, v19
	v_exp_f32_e32 v20, v20
	v_exp_f32_e32 v21, v21
	v_exp_f32_e32 v22, v22
	v_exp_f32_e32 v23, v23
	v_exp_f32_e32 v24, v24
	v_exp_f32_e32 v25, v25
	v_add_f32_e32 v18, 1.0, v18
	v_add_f32_e32 v19, 1.0, v19
	v_add_f32_e32 v20, 1.0, v20
	v_add_f32_e32 v21, 1.0, v21
	v_add_f32_e32 v22, 1.0, v22
	v_add_f32_e32 v23, 1.0, v23
	v_add_f32_e32 v24, 1.0, v24
	v_add_f32_e32 v25, 1.0, v25
	v_rcp_f32_e32 v18, v18
	v_rcp_f32_e32 v19, v19
	v_rcp_f32_e32 v20, v20
	v_rcp_f32_e32 v21, v21
	v_rcp_f32_e32 v22, v22
	v_rcp_f32_e32 v23, v23
	v_rcp_f32_e32 v24, v24
	v_rcp_f32_e32 v25, v25
	v_mul_f32_e32 v18, v2, v18
	v_mul_f32_e32 v19, v3, v19
	v_mul_f32_e32 v20, v4, v20
	v_mul_f32_e32 v21, v5, v21
	v_mul_f32_e32 v22, v6, v22
	v_mul_f32_e32 v23, v7, v23
	v_mul_f32_e32 v24, v8, v24
	v_mul_f32_e32 v25, v9, v25
	v_mul_f32_e32 v18, v10, v18
	v_mul_f32_e32 v19, v11, v19
	v_mul_f32_e32 v20, v12, v20
	v_mul_f32_e32 v21, v13, v21
	v_mul_f32_e32 v22, v14, v22
	v_mul_f32_e32 v23, v15, v23
	v_mul_f32_e32 v24, v16, v24
	v_mul_f32_e32 v25, v17, v25
	v_cvt_pk_bf16_f32 v26, v18, v19
	v_cvt_pk_bf16_f32 v27, v20, v21
	v_cvt_pk_bf16_f32 v28, v22, v23
	v_cvt_pk_bf16_f32 v29, v24, v25
	global_store_dwordx4 v[162:163], v[26:29], off sc1
	v_lshl_add_u64 v[162:163], v[162:163], 0, v[30:31]
	v_lshlrev_b32_e32 v206, 16, v96
	v_and_b32_e32 v207, 0xffff0000, v96
	v_lshlrev_b32_e32 v208, 16, v97
	v_and_b32_e32 v209, 0xffff0000, v97
	v_lshlrev_b32_e32 v210, 16, v98
	v_and_b32_e32 v211, 0xffff0000, v98
	v_lshlrev_b32_e32 v212, 16, v99
	v_and_b32_e32 v213, 0xffff0000, v99
	v_lshlrev_b32_e32 v214, 16, v100
	v_and_b32_e32 v215, 0xffff0000, v100
	v_lshlrev_b32_e32 v216, 16, v101
	v_and_b32_e32 v217, 0xffff0000, v101
	v_lshlrev_b32_e32 v218, 16, v102
	v_and_b32_e32 v219, 0xffff0000, v102
	v_lshlrev_b32_e32 v220, 16, v103
	v_and_b32_e32 v221, 0xffff0000, v103
	v_pk_fma_f32 v[2:3], v[104:105], v[222:223], v[174:175]
	v_pk_fma_f32 v[4:5], v[106:107], v[224:225], v[176:177]
	v_pk_fma_f32 v[6:7], v[108:109], v[226:227], v[178:179]
	v_pk_fma_f32 v[8:9], v[110:111], v[228:229], v[180:181]
	v_pk_fma_f32 v[10:11], v[112:113], v[230:231], v[182:183]
	v_pk_fma_f32 v[12:13], v[114:115], v[232:233], v[184:185]
	v_pk_fma_f32 v[14:15], v[116:117], v[234:235], v[186:187]
	v_pk_fma_f32 v[16:17], v[118:119], v[236:237], v[188:189]
	v_pk_fma_f32 v[2:3], v[120:121], v[190:191], v[2:3]
	v_pk_fma_f32 v[4:5], v[122:123], v[192:193], v[4:5]
	v_pk_fma_f32 v[6:7], v[124:125], v[194:195], v[6:7]
	v_pk_fma_f32 v[8:9], v[126:127], v[196:197], v[8:9]
	v_pk_fma_f32 v[10:11], v[128:129], v[198:199], v[10:11]
	v_pk_fma_f32 v[12:13], v[130:131], v[200:201], v[12:13]
	v_pk_fma_f32 v[14:15], v[132:133], v[202:203], v[14:15]
	v_pk_fma_f32 v[16:17], v[134:135], v[204:205], v[16:17]
	v_pk_fma_f32 v[2:3], v[136:137], v[206:207], v[2:3]
	v_pk_fma_f32 v[4:5], v[138:139], v[208:209], v[4:5]
	v_pk_fma_f32 v[6:7], v[140:141], v[210:211], v[6:7]
	v_pk_fma_f32 v[8:9], v[142:143], v[212:213], v[8:9]
	v_pk_fma_f32 v[10:11], v[144:145], v[214:215], v[10:11]
	v_pk_fma_f32 v[12:13], v[146:147], v[216:217], v[12:13]
	v_pk_fma_f32 v[14:15], v[148:149], v[218:219], v[14:15]
	v_pk_fma_f32 v[16:17], v[150:151], v[220:221], v[16:17]
	v_mul_f32_e32 v18, 0xbfb8aa3b, v2
	v_mul_f32_e32 v19, 0xbfb8aa3b, v3
	v_mul_f32_e32 v20, 0xbfb8aa3b, v4
	v_mul_f32_e32 v21, 0xbfb8aa3b, v5
	v_mul_f32_e32 v22, 0xbfb8aa3b, v6
	v_mul_f32_e32 v23, 0xbfb8aa3b, v7
	v_mul_f32_e32 v24, 0xbfb8aa3b, v8
	v_mul_f32_e32 v25, 0xbfb8aa3b, v9
	v_exp_f32_e32 v18, v18
	v_exp_f32_e32 v19, v19
	v_exp_f32_e32 v20, v20
	v_exp_f32_e32 v21, v21
	v_exp_f32_e32 v22, v22
	v_exp_f32_e32 v23, v23
	v_exp_f32_e32 v24, v24
	v_exp_f32_e32 v25, v25
	v_add_f32_e32 v18, 1.0, v18
	v_add_f32_e32 v19, 1.0, v19
	v_add_f32_e32 v20, 1.0, v20
	v_add_f32_e32 v21, 1.0, v21
	v_add_f32_e32 v22, 1.0, v22
	v_add_f32_e32 v23, 1.0, v23
	v_add_f32_e32 v24, 1.0, v24
	v_add_f32_e32 v25, 1.0, v25
	v_rcp_f32_e32 v18, v18
	v_rcp_f32_e32 v19, v19
	v_rcp_f32_e32 v20, v20
	v_rcp_f32_e32 v21, v21
	v_rcp_f32_e32 v22, v22
	v_rcp_f32_e32 v23, v23
	v_rcp_f32_e32 v24, v24
	v_rcp_f32_e32 v25, v25
	v_mul_f32_e32 v18, v2, v18
	v_mul_f32_e32 v19, v3, v19
	v_mul_f32_e32 v20, v4, v20
	v_mul_f32_e32 v21, v5, v21
	v_mul_f32_e32 v22, v6, v22
	v_mul_f32_e32 v23, v7, v23
	v_mul_f32_e32 v24, v8, v24
	v_mul_f32_e32 v25, v9, v25
	v_mul_f32_e32 v18, v10, v18
	v_mul_f32_e32 v19, v11, v19
	v_mul_f32_e32 v20, v12, v20
	v_mul_f32_e32 v21, v13, v21
	v_mul_f32_e32 v22, v14, v22
	v_mul_f32_e32 v23, v15, v23
	v_mul_f32_e32 v24, v16, v24
	v_mul_f32_e32 v25, v17, v25
	v_cvt_pk_bf16_f32 v26, v18, v19
	v_cvt_pk_bf16_f32 v27, v20, v21
	v_cvt_pk_bf16_f32 v28, v22, v23
	v_cvt_pk_bf16_f32 v29, v24, v25
	global_store_dwordx4 v[162:163], v[26:29], off sc1
	v_lshl_add_u64 v[162:163], v[162:163], 0, v[30:31]
	global_load_dwordx4 v[68:71], v[158:159], off
	global_load_dwordx4 v[72:75], v[160:161], off
	v_lshl_add_u64 v[158:159], v[158:159], 0, v[164:165]
	v_lshl_add_u64 v[160:161], v[160:161], 0, v[164:165]
	global_load_dwordx4 v[76:79], v[158:159], off
	global_load_dwordx4 v[80:83], v[160:161], off
	v_lshl_add_u64 v[158:159], v[158:159], 0, v[164:165]
	v_lshl_add_u64 v[160:161], v[160:161], 0, v[164:165]
	global_load_dwordx4 v[88:91], v[158:159], off
	global_load_dwordx4 v[92:95], v[160:161], off
	v_lshl_add_u64 v[158:159], v[158:159], 0, v[164:165]
	v_lshl_add_u64 v[160:161], v[160:161], 0, v[164:165]
	global_load_dwordx4 v[96:99], v[158:159], off
	global_load_dwordx4 v[100:103], v[160:161], off
	v_lshl_add_u64 v[158:159], v[158:159], 0, v[164:165]
	v_lshl_add_u64 v[160:161], v[160:161], 0, v[164:165]
	s_waitcnt vmcnt(12)
	v_lshlrev_b32_e32 v222, 16, v36
	v_and_b32_e32 v223, 0xffff0000, v36
	v_lshlrev_b32_e32 v224, 16, v37
	v_and_b32_e32 v225, 0xffff0000, v37
	v_lshlrev_b32_e32 v226, 16, v38
	v_and_b32_e32 v227, 0xffff0000, v38
	v_lshlrev_b32_e32 v228, 16, v39
	v_and_b32_e32 v229, 0xffff0000, v39
	v_lshlrev_b32_e32 v230, 16, v40
	v_and_b32_e32 v231, 0xffff0000, v40
	v_lshlrev_b32_e32 v232, 16, v41
	v_and_b32_e32 v233, 0xffff0000, v41
	v_lshlrev_b32_e32 v234, 16, v42
	v_and_b32_e32 v235, 0xffff0000, v42
	v_lshlrev_b32_e32 v236, 16, v43
	v_and_b32_e32 v237, 0xffff0000, v43
	v_pk_fma_f32 v[2:3], v[104:105], v[190:191], v[174:175]
	v_pk_fma_f32 v[4:5], v[106:107], v[192:193], v[176:177]
	v_pk_fma_f32 v[6:7], v[108:109], v[194:195], v[178:179]
	v_pk_fma_f32 v[8:9], v[110:111], v[196:197], v[180:181]
	v_pk_fma_f32 v[10:11], v[112:113], v[198:199], v[182:183]
	v_pk_fma_f32 v[12:13], v[114:115], v[200:201], v[184:185]
	v_pk_fma_f32 v[14:15], v[116:117], v[202:203], v[186:187]
	v_pk_fma_f32 v[16:17], v[118:119], v[204:205], v[188:189]
	v_pk_fma_f32 v[2:3], v[120:121], v[206:207], v[2:3]
	v_pk_fma_f32 v[4:5], v[122:123], v[208:209], v[4:5]
	v_pk_fma_f32 v[6:7], v[124:125], v[210:211], v[6:7]
	v_pk_fma_f32 v[8:9], v[126:127], v[212:213], v[8:9]
	v_pk_fma_f32 v[10:11], v[128:129], v[214:215], v[10:11]
	v_pk_fma_f32 v[12:13], v[130:131], v[216:217], v[12:13]
	v_pk_fma_f32 v[14:15], v[132:133], v[218:219], v[14:15]
	v_pk_fma_f32 v[16:17], v[134:135], v[220:221], v[16:17]
	v_pk_fma_f32 v[2:3], v[136:137], v[222:223], v[2:3]
	v_pk_fma_f32 v[4:5], v[138:139], v[224:225], v[4:5]
	v_pk_fma_f32 v[6:7], v[140:141], v[226:227], v[6:7]
	v_pk_fma_f32 v[8:9], v[142:143], v[228:229], v[8:9]
	v_pk_fma_f32 v[10:11], v[144:145], v[230:231], v[10:11]
	v_pk_fma_f32 v[12:13], v[146:147], v[232:233], v[12:13]
	v_pk_fma_f32 v[14:15], v[148:149], v[234:235], v[14:15]
	v_pk_fma_f32 v[16:17], v[150:151], v[236:237], v[16:17]
	v_mul_f32_e32 v18, 0xbfb8aa3b, v2
	v_mul_f32_e32 v19, 0xbfb8aa3b, v3
	v_mul_f32_e32 v20, 0xbfb8aa3b, v4
	v_mul_f32_e32 v21, 0xbfb8aa3b, v5
	v_mul_f32_e32 v22, 0xbfb8aa3b, v6
	v_mul_f32_e32 v23, 0xbfb8aa3b, v7
	v_mul_f32_e32 v24, 0xbfb8aa3b, v8
	v_mul_f32_e32 v25, 0xbfb8aa3b, v9
	v_exp_f32_e32 v18, v18
	v_exp_f32_e32 v19, v19
	v_exp_f32_e32 v20, v20
	v_exp_f32_e32 v21, v21
	v_exp_f32_e32 v22, v22
	v_exp_f32_e32 v23, v23
	v_exp_f32_e32 v24, v24
	v_exp_f32_e32 v25, v25
	v_add_f32_e32 v18, 1.0, v18
	v_add_f32_e32 v19, 1.0, v19
	v_add_f32_e32 v20, 1.0, v20
	v_add_f32_e32 v21, 1.0, v21
	v_add_f32_e32 v22, 1.0, v22
	v_add_f32_e32 v23, 1.0, v23
	v_add_f32_e32 v24, 1.0, v24
	v_add_f32_e32 v25, 1.0, v25
	v_rcp_f32_e32 v18, v18
	v_rcp_f32_e32 v19, v19
	v_rcp_f32_e32 v20, v20
	v_rcp_f32_e32 v21, v21
	v_rcp_f32_e32 v22, v22
	v_rcp_f32_e32 v23, v23
	v_rcp_f32_e32 v24, v24
	v_rcp_f32_e32 v25, v25
	v_mul_f32_e32 v18, v2, v18
	v_mul_f32_e32 v19, v3, v19
	v_mul_f32_e32 v20, v4, v20
	v_mul_f32_e32 v21, v5, v21
	v_mul_f32_e32 v22, v6, v22
	v_mul_f32_e32 v23, v7, v23
	v_mul_f32_e32 v24, v8, v24
	v_mul_f32_e32 v25, v9, v25
	v_mul_f32_e32 v18, v10, v18
	v_mul_f32_e32 v19, v11, v19
	v_mul_f32_e32 v20, v12, v20
	v_mul_f32_e32 v21, v13, v21
	v_mul_f32_e32 v22, v14, v22
	v_mul_f32_e32 v23, v15, v23
	v_mul_f32_e32 v24, v16, v24
	v_mul_f32_e32 v25, v17, v25
	v_cvt_pk_bf16_f32 v26, v18, v19
	v_cvt_pk_bf16_f32 v27, v20, v21
	v_cvt_pk_bf16_f32 v28, v22, v23
	v_cvt_pk_bf16_f32 v29, v24, v25
	global_store_dwordx4 v[162:163], v[26:29], off sc1
	v_lshl_add_u64 v[162:163], v[162:163], 0, v[30:31]
	v_lshlrev_b32_e32 v190, 16, v44
	v_and_b32_e32 v191, 0xffff0000, v44
	v_lshlrev_b32_e32 v192, 16, v45
	v_and_b32_e32 v193, 0xffff0000, v45
	v_lshlrev_b32_e32 v194, 16, v46
	v_and_b32_e32 v195, 0xffff0000, v46
	v_lshlrev_b32_e32 v196, 16, v47
	v_and_b32_e32 v197, 0xffff0000, v47
	v_lshlrev_b32_e32 v198, 16, v48
	v_and_b32_e32 v199, 0xffff0000, v48
	v_lshlrev_b32_e32 v200, 16, v49
	v_and_b32_e32 v201, 0xffff0000, v49
	v_lshlrev_b32_e32 v202, 16, v50
	v_and_b32_e32 v203, 0xffff0000, v50
	v_lshlrev_b32_e32 v204, 16, v51
	v_and_b32_e32 v205, 0xffff0000, v51
	v_pk_fma_f32 v[2:3], v[104:105], v[206:207], v[174:175]
	v_pk_fma_f32 v[4:5], v[106:107], v[208:209], v[176:177]
	v_pk_fma_f32 v[6:7], v[108:109], v[210:211], v[178:179]
	v_pk_fma_f32 v[8:9], v[110:111], v[212:213], v[180:181]
	v_pk_fma_f32 v[10:11], v[112:113], v[214:215], v[182:183]
	v_pk_fma_f32 v[12:13], v[114:115], v[216:217], v[184:185]
	v_pk_fma_f32 v[14:15], v[116:117], v[218:219], v[186:187]
	v_pk_fma_f32 v[16:17], v[118:119], v[220:221], v[188:189]
	v_pk_fma_f32 v[2:3], v[120:121], v[222:223], v[2:3]
	v_pk_fma_f32 v[4:5], v[122:123], v[224:225], v[4:5]
	v_pk_fma_f32 v[6:7], v[124:125], v[226:227], v[6:7]
	v_pk_fma_f32 v[8:9], v[126:127], v[228:229], v[8:9]
	v_pk_fma_f32 v[10:11], v[128:129], v[230:231], v[10:11]
	v_pk_fma_f32 v[12:13], v[130:131], v[232:233], v[12:13]
	v_pk_fma_f32 v[14:15], v[132:133], v[234:235], v[14:15]
	v_pk_fma_f32 v[16:17], v[134:135], v[236:237], v[16:17]
	v_pk_fma_f32 v[2:3], v[136:137], v[190:191], v[2:3]
	v_pk_fma_f32 v[4:5], v[138:139], v[192:193], v[4:5]
	v_pk_fma_f32 v[6:7], v[140:141], v[194:195], v[6:7]
	v_pk_fma_f32 v[8:9], v[142:143], v[196:197], v[8:9]
	v_pk_fma_f32 v[10:11], v[144:145], v[198:199], v[10:11]
	v_pk_fma_f32 v[12:13], v[146:147], v[200:201], v[12:13]
	v_pk_fma_f32 v[14:15], v[148:149], v[202:203], v[14:15]
	v_pk_fma_f32 v[16:17], v[150:151], v[204:205], v[16:17]
	v_mul_f32_e32 v18, 0xbfb8aa3b, v2
	v_mul_f32_e32 v19, 0xbfb8aa3b, v3
	v_mul_f32_e32 v20, 0xbfb8aa3b, v4
	v_mul_f32_e32 v21, 0xbfb8aa3b, v5
	v_mul_f32_e32 v22, 0xbfb8aa3b, v6
	v_mul_f32_e32 v23, 0xbfb8aa3b, v7
	v_mul_f32_e32 v24, 0xbfb8aa3b, v8
	v_mul_f32_e32 v25, 0xbfb8aa3b, v9
	v_exp_f32_e32 v18, v18
	v_exp_f32_e32 v19, v19
	v_exp_f32_e32 v20, v20
	v_exp_f32_e32 v21, v21
	v_exp_f32_e32 v22, v22
	v_exp_f32_e32 v23, v23
	v_exp_f32_e32 v24, v24
	v_exp_f32_e32 v25, v25
	v_add_f32_e32 v18, 1.0, v18
	v_add_f32_e32 v19, 1.0, v19
	v_add_f32_e32 v20, 1.0, v20
	v_add_f32_e32 v21, 1.0, v21
	v_add_f32_e32 v22, 1.0, v22
	v_add_f32_e32 v23, 1.0, v23
	v_add_f32_e32 v24, 1.0, v24
	v_add_f32_e32 v25, 1.0, v25
	v_rcp_f32_e32 v18, v18
	v_rcp_f32_e32 v19, v19
	v_rcp_f32_e32 v20, v20
	v_rcp_f32_e32 v21, v21
	v_rcp_f32_e32 v22, v22
	v_rcp_f32_e32 v23, v23
	v_rcp_f32_e32 v24, v24
	v_rcp_f32_e32 v25, v25
	v_mul_f32_e32 v18, v2, v18
	v_mul_f32_e32 v19, v3, v19
	v_mul_f32_e32 v20, v4, v20
	v_mul_f32_e32 v21, v5, v21
	v_mul_f32_e32 v22, v6, v22
	v_mul_f32_e32 v23, v7, v23
	v_mul_f32_e32 v24, v8, v24
	v_mul_f32_e32 v25, v9, v25
	v_mul_f32_e32 v18, v10, v18
	v_mul_f32_e32 v19, v11, v19
	v_mul_f32_e32 v20, v12, v20
	v_mul_f32_e32 v21, v13, v21
	v_mul_f32_e32 v22, v14, v22
	v_mul_f32_e32 v23, v15, v23
	v_mul_f32_e32 v24, v16, v24
	v_mul_f32_e32 v25, v17, v25
	v_cvt_pk_bf16_f32 v26, v18, v19
	v_cvt_pk_bf16_f32 v27, v20, v21
	v_cvt_pk_bf16_f32 v28, v22, v23
	v_cvt_pk_bf16_f32 v29, v24, v25
	global_store_dwordx4 v[162:163], v[26:29], off sc1
	v_lshl_add_u64 v[162:163], v[162:163], 0, v[30:31]
	v_lshlrev_b32_e32 v206, 16, v52
	v_and_b32_e32 v207, 0xffff0000, v52
	v_lshlrev_b32_e32 v208, 16, v53
	v_and_b32_e32 v209, 0xffff0000, v53
	v_lshlrev_b32_e32 v210, 16, v54
	v_and_b32_e32 v211, 0xffff0000, v54
	v_lshlrev_b32_e32 v212, 16, v55
	v_and_b32_e32 v213, 0xffff0000, v55
	v_lshlrev_b32_e32 v214, 16, v56
	v_and_b32_e32 v215, 0xffff0000, v56
	v_lshlrev_b32_e32 v216, 16, v57
	v_and_b32_e32 v217, 0xffff0000, v57
	v_lshlrev_b32_e32 v218, 16, v58
	v_and_b32_e32 v219, 0xffff0000, v58
	v_lshlrev_b32_e32 v220, 16, v59
	v_and_b32_e32 v221, 0xffff0000, v59
	v_pk_fma_f32 v[2:3], v[104:105], v[222:223], v[174:175]
	v_pk_fma_f32 v[4:5], v[106:107], v[224:225], v[176:177]
	v_pk_fma_f32 v[6:7], v[108:109], v[226:227], v[178:179]
	v_pk_fma_f32 v[8:9], v[110:111], v[228:229], v[180:181]
	v_pk_fma_f32 v[10:11], v[112:113], v[230:231], v[182:183]
	v_pk_fma_f32 v[12:13], v[114:115], v[232:233], v[184:185]
	v_pk_fma_f32 v[14:15], v[116:117], v[234:235], v[186:187]
	v_pk_fma_f32 v[16:17], v[118:119], v[236:237], v[188:189]
	v_pk_fma_f32 v[2:3], v[120:121], v[190:191], v[2:3]
	v_pk_fma_f32 v[4:5], v[122:123], v[192:193], v[4:5]
	v_pk_fma_f32 v[6:7], v[124:125], v[194:195], v[6:7]
	v_pk_fma_f32 v[8:9], v[126:127], v[196:197], v[8:9]
	v_pk_fma_f32 v[10:11], v[128:129], v[198:199], v[10:11]
	v_pk_fma_f32 v[12:13], v[130:131], v[200:201], v[12:13]
	v_pk_fma_f32 v[14:15], v[132:133], v[202:203], v[14:15]
	v_pk_fma_f32 v[16:17], v[134:135], v[204:205], v[16:17]
	v_pk_fma_f32 v[2:3], v[136:137], v[206:207], v[2:3]
	v_pk_fma_f32 v[4:5], v[138:139], v[208:209], v[4:5]
	v_pk_fma_f32 v[6:7], v[140:141], v[210:211], v[6:7]
	v_pk_fma_f32 v[8:9], v[142:143], v[212:213], v[8:9]
	v_pk_fma_f32 v[10:11], v[144:145], v[214:215], v[10:11]
	v_pk_fma_f32 v[12:13], v[146:147], v[216:217], v[12:13]
	v_pk_fma_f32 v[14:15], v[148:149], v[218:219], v[14:15]
	v_pk_fma_f32 v[16:17], v[150:151], v[220:221], v[16:17]
	v_mul_f32_e32 v18, 0xbfb8aa3b, v2
	v_mul_f32_e32 v19, 0xbfb8aa3b, v3
	v_mul_f32_e32 v20, 0xbfb8aa3b, v4
	v_mul_f32_e32 v21, 0xbfb8aa3b, v5
	v_mul_f32_e32 v22, 0xbfb8aa3b, v6
	v_mul_f32_e32 v23, 0xbfb8aa3b, v7
	v_mul_f32_e32 v24, 0xbfb8aa3b, v8
	v_mul_f32_e32 v25, 0xbfb8aa3b, v9
	v_exp_f32_e32 v18, v18
	v_exp_f32_e32 v19, v19
	v_exp_f32_e32 v20, v20
	v_exp_f32_e32 v21, v21
	v_exp_f32_e32 v22, v22
	v_exp_f32_e32 v23, v23
	v_exp_f32_e32 v24, v24
	v_exp_f32_e32 v25, v25
	v_add_f32_e32 v18, 1.0, v18
	v_add_f32_e32 v19, 1.0, v19
	v_add_f32_e32 v20, 1.0, v20
	v_add_f32_e32 v21, 1.0, v21
	v_add_f32_e32 v22, 1.0, v22
	v_add_f32_e32 v23, 1.0, v23
	v_add_f32_e32 v24, 1.0, v24
	v_add_f32_e32 v25, 1.0, v25
	v_rcp_f32_e32 v18, v18
	v_rcp_f32_e32 v19, v19
	v_rcp_f32_e32 v20, v20
	v_rcp_f32_e32 v21, v21
	v_rcp_f32_e32 v22, v22
	v_rcp_f32_e32 v23, v23
	v_rcp_f32_e32 v24, v24
	v_rcp_f32_e32 v25, v25
	v_mul_f32_e32 v18, v2, v18
	v_mul_f32_e32 v19, v3, v19
	v_mul_f32_e32 v20, v4, v20
	v_mul_f32_e32 v21, v5, v21
	v_mul_f32_e32 v22, v6, v22
	v_mul_f32_e32 v23, v7, v23
	v_mul_f32_e32 v24, v8, v24
	v_mul_f32_e32 v25, v9, v25
	v_mul_f32_e32 v18, v10, v18
	v_mul_f32_e32 v19, v11, v19
	v_mul_f32_e32 v20, v12, v20
	v_mul_f32_e32 v21, v13, v21
	v_mul_f32_e32 v22, v14, v22
	v_mul_f32_e32 v23, v15, v23
	v_mul_f32_e32 v24, v16, v24
	v_mul_f32_e32 v25, v17, v25
	v_cvt_pk_bf16_f32 v26, v18, v19
	v_cvt_pk_bf16_f32 v27, v20, v21
	v_cvt_pk_bf16_f32 v28, v22, v23
	v_cvt_pk_bf16_f32 v29, v24, v25
	global_store_dwordx4 v[162:163], v[26:29], off sc1
	v_lshl_add_u64 v[162:163], v[162:163], 0, v[30:31]
	v_lshlrev_b32_e32 v222, 16, v60
	v_and_b32_e32 v223, 0xffff0000, v60
	v_lshlrev_b32_e32 v224, 16, v61
	v_and_b32_e32 v225, 0xffff0000, v61
	v_lshlrev_b32_e32 v226, 16, v62
	v_and_b32_e32 v227, 0xffff0000, v62
	v_lshlrev_b32_e32 v228, 16, v63
	v_and_b32_e32 v229, 0xffff0000, v63
	v_lshlrev_b32_e32 v230, 16, v64
	v_and_b32_e32 v231, 0xffff0000, v64
	v_lshlrev_b32_e32 v232, 16, v65
	v_and_b32_e32 v233, 0xffff0000, v65
	v_lshlrev_b32_e32 v234, 16, v66
	v_and_b32_e32 v235, 0xffff0000, v66
	v_lshlrev_b32_e32 v236, 16, v67
	v_and_b32_e32 v237, 0xffff0000, v67
	v_pk_fma_f32 v[2:3], v[104:105], v[190:191], v[174:175]
	v_pk_fma_f32 v[4:5], v[106:107], v[192:193], v[176:177]
	v_pk_fma_f32 v[6:7], v[108:109], v[194:195], v[178:179]
	v_pk_fma_f32 v[8:9], v[110:111], v[196:197], v[180:181]
	v_pk_fma_f32 v[10:11], v[112:113], v[198:199], v[182:183]
	v_pk_fma_f32 v[12:13], v[114:115], v[200:201], v[184:185]
	v_pk_fma_f32 v[14:15], v[116:117], v[202:203], v[186:187]
	v_pk_fma_f32 v[16:17], v[118:119], v[204:205], v[188:189]
	v_pk_fma_f32 v[2:3], v[120:121], v[206:207], v[2:3]
	v_pk_fma_f32 v[4:5], v[122:123], v[208:209], v[4:5]
	v_pk_fma_f32 v[6:7], v[124:125], v[210:211], v[6:7]
	v_pk_fma_f32 v[8:9], v[126:127], v[212:213], v[8:9]
	v_pk_fma_f32 v[10:11], v[128:129], v[214:215], v[10:11]
	v_pk_fma_f32 v[12:13], v[130:131], v[216:217], v[12:13]
	v_pk_fma_f32 v[14:15], v[132:133], v[218:219], v[14:15]
	v_pk_fma_f32 v[16:17], v[134:135], v[220:221], v[16:17]
	v_pk_fma_f32 v[2:3], v[136:137], v[222:223], v[2:3]
	v_pk_fma_f32 v[4:5], v[138:139], v[224:225], v[4:5]
	v_pk_fma_f32 v[6:7], v[140:141], v[226:227], v[6:7]
	v_pk_fma_f32 v[8:9], v[142:143], v[228:229], v[8:9]
	v_pk_fma_f32 v[10:11], v[144:145], v[230:231], v[10:11]
	v_pk_fma_f32 v[12:13], v[146:147], v[232:233], v[12:13]
	v_pk_fma_f32 v[14:15], v[148:149], v[234:235], v[14:15]
	v_pk_fma_f32 v[16:17], v[150:151], v[236:237], v[16:17]
	v_mul_f32_e32 v18, 0xbfb8aa3b, v2
	v_mul_f32_e32 v19, 0xbfb8aa3b, v3
	v_mul_f32_e32 v20, 0xbfb8aa3b, v4
	v_mul_f32_e32 v21, 0xbfb8aa3b, v5
	v_mul_f32_e32 v22, 0xbfb8aa3b, v6
	v_mul_f32_e32 v23, 0xbfb8aa3b, v7
	v_mul_f32_e32 v24, 0xbfb8aa3b, v8
	v_mul_f32_e32 v25, 0xbfb8aa3b, v9
	v_exp_f32_e32 v18, v18
	v_exp_f32_e32 v19, v19
	v_exp_f32_e32 v20, v20
	v_exp_f32_e32 v21, v21
	v_exp_f32_e32 v22, v22
	v_exp_f32_e32 v23, v23
	v_exp_f32_e32 v24, v24
	v_exp_f32_e32 v25, v25
	v_add_f32_e32 v18, 1.0, v18
	v_add_f32_e32 v19, 1.0, v19
	v_add_f32_e32 v20, 1.0, v20
	v_add_f32_e32 v21, 1.0, v21
	v_add_f32_e32 v22, 1.0, v22
	v_add_f32_e32 v23, 1.0, v23
	v_add_f32_e32 v24, 1.0, v24
	v_add_f32_e32 v25, 1.0, v25
	v_rcp_f32_e32 v18, v18
	v_rcp_f32_e32 v19, v19
	v_rcp_f32_e32 v20, v20
	v_rcp_f32_e32 v21, v21
	v_rcp_f32_e32 v22, v22
	v_rcp_f32_e32 v23, v23
	v_rcp_f32_e32 v24, v24
	v_rcp_f32_e32 v25, v25
	v_mul_f32_e32 v18, v2, v18
	v_mul_f32_e32 v19, v3, v19
	v_mul_f32_e32 v20, v4, v20
	v_mul_f32_e32 v21, v5, v21
	v_mul_f32_e32 v22, v6, v22
	v_mul_f32_e32 v23, v7, v23
	v_mul_f32_e32 v24, v8, v24
	v_mul_f32_e32 v25, v9, v25
	v_mul_f32_e32 v18, v10, v18
	v_mul_f32_e32 v19, v11, v19
	v_mul_f32_e32 v20, v12, v20
	v_mul_f32_e32 v21, v13, v21
	v_mul_f32_e32 v22, v14, v22
	v_mul_f32_e32 v23, v15, v23
	v_mul_f32_e32 v24, v16, v24
	v_mul_f32_e32 v25, v17, v25
	v_cvt_pk_bf16_f32 v26, v18, v19
	v_cvt_pk_bf16_f32 v27, v20, v21
	v_cvt_pk_bf16_f32 v28, v22, v23
	v_cvt_pk_bf16_f32 v29, v24, v25
	global_store_dwordx4 v[162:163], v[26:29], off sc1
	v_lshl_add_u64 v[162:163], v[162:163], 0, v[30:31]
	s_waitcnt vmcnt(4)
	v_lshlrev_b32_e32 v190, 16, v68
	v_and_b32_e32 v191, 0xffff0000, v68
	v_lshlrev_b32_e32 v192, 16, v69
	v_and_b32_e32 v193, 0xffff0000, v69
	v_lshlrev_b32_e32 v194, 16, v70
	v_and_b32_e32 v195, 0xffff0000, v70
	v_lshlrev_b32_e32 v196, 16, v71
	v_and_b32_e32 v197, 0xffff0000, v71
	v_lshlrev_b32_e32 v198, 16, v72
	v_and_b32_e32 v199, 0xffff0000, v72
	v_lshlrev_b32_e32 v200, 16, v73
	v_and_b32_e32 v201, 0xffff0000, v73
	v_lshlrev_b32_e32 v202, 16, v74
	v_and_b32_e32 v203, 0xffff0000, v74
	v_lshlrev_b32_e32 v204, 16, v75
	v_and_b32_e32 v205, 0xffff0000, v75
	v_pk_fma_f32 v[2:3], v[104:105], v[206:207], v[174:175]
	v_pk_fma_f32 v[4:5], v[106:107], v[208:209], v[176:177]
	v_pk_fma_f32 v[6:7], v[108:109], v[210:211], v[178:179]
	v_pk_fma_f32 v[8:9], v[110:111], v[212:213], v[180:181]
	v_pk_fma_f32 v[10:11], v[112:113], v[214:215], v[182:183]
	v_pk_fma_f32 v[12:13], v[114:115], v[216:217], v[184:185]
	v_pk_fma_f32 v[14:15], v[116:117], v[218:219], v[186:187]
	v_pk_fma_f32 v[16:17], v[118:119], v[220:221], v[188:189]
	v_pk_fma_f32 v[2:3], v[120:121], v[222:223], v[2:3]
	v_pk_fma_f32 v[4:5], v[122:123], v[224:225], v[4:5]
	v_pk_fma_f32 v[6:7], v[124:125], v[226:227], v[6:7]
	v_pk_fma_f32 v[8:9], v[126:127], v[228:229], v[8:9]
	v_pk_fma_f32 v[10:11], v[128:129], v[230:231], v[10:11]
	v_pk_fma_f32 v[12:13], v[130:131], v[232:233], v[12:13]
	v_pk_fma_f32 v[14:15], v[132:133], v[234:235], v[14:15]
	v_pk_fma_f32 v[16:17], v[134:135], v[236:237], v[16:17]
	v_pk_fma_f32 v[2:3], v[136:137], v[190:191], v[2:3]
	v_pk_fma_f32 v[4:5], v[138:139], v[192:193], v[4:5]
	v_pk_fma_f32 v[6:7], v[140:141], v[194:195], v[6:7]
	v_pk_fma_f32 v[8:9], v[142:143], v[196:197], v[8:9]
	v_pk_fma_f32 v[10:11], v[144:145], v[198:199], v[10:11]
	v_pk_fma_f32 v[12:13], v[146:147], v[200:201], v[12:13]
	v_pk_fma_f32 v[14:15], v[148:149], v[202:203], v[14:15]
	v_pk_fma_f32 v[16:17], v[150:151], v[204:205], v[16:17]
	v_mul_f32_e32 v18, 0xbfb8aa3b, v2
	v_mul_f32_e32 v19, 0xbfb8aa3b, v3
	v_mul_f32_e32 v20, 0xbfb8aa3b, v4
	v_mul_f32_e32 v21, 0xbfb8aa3b, v5
	v_mul_f32_e32 v22, 0xbfb8aa3b, v6
	v_mul_f32_e32 v23, 0xbfb8aa3b, v7
	v_mul_f32_e32 v24, 0xbfb8aa3b, v8
	v_mul_f32_e32 v25, 0xbfb8aa3b, v9
	v_exp_f32_e32 v18, v18
	v_exp_f32_e32 v19, v19
	v_exp_f32_e32 v20, v20
	v_exp_f32_e32 v21, v21
	v_exp_f32_e32 v22, v22
	v_exp_f32_e32 v23, v23
	v_exp_f32_e32 v24, v24
	v_exp_f32_e32 v25, v25
	v_add_f32_e32 v18, 1.0, v18
	v_add_f32_e32 v19, 1.0, v19
	v_add_f32_e32 v20, 1.0, v20
	v_add_f32_e32 v21, 1.0, v21
	v_add_f32_e32 v22, 1.0, v22
	v_add_f32_e32 v23, 1.0, v23
	v_add_f32_e32 v24, 1.0, v24
	v_add_f32_e32 v25, 1.0, v25
	v_rcp_f32_e32 v18, v18
	v_rcp_f32_e32 v19, v19
	v_rcp_f32_e32 v20, v20
	v_rcp_f32_e32 v21, v21
	v_rcp_f32_e32 v22, v22
	v_rcp_f32_e32 v23, v23
	v_rcp_f32_e32 v24, v24
	v_rcp_f32_e32 v25, v25
	v_mul_f32_e32 v18, v2, v18
	v_mul_f32_e32 v19, v3, v19
	v_mul_f32_e32 v20, v4, v20
	v_mul_f32_e32 v21, v5, v21
	v_mul_f32_e32 v22, v6, v22
	v_mul_f32_e32 v23, v7, v23
	v_mul_f32_e32 v24, v8, v24
	v_mul_f32_e32 v25, v9, v25
	v_mul_f32_e32 v18, v10, v18
	v_mul_f32_e32 v19, v11, v19
	v_mul_f32_e32 v20, v12, v20
	v_mul_f32_e32 v21, v13, v21
	v_mul_f32_e32 v22, v14, v22
	v_mul_f32_e32 v23, v15, v23
	v_mul_f32_e32 v24, v16, v24
	v_mul_f32_e32 v25, v17, v25
	v_cvt_pk_bf16_f32 v26, v18, v19
	v_cvt_pk_bf16_f32 v27, v20, v21
	v_cvt_pk_bf16_f32 v28, v22, v23
	v_cvt_pk_bf16_f32 v29, v24, v25
	global_store_dwordx4 v[162:163], v[26:29], off sc1
	v_lshl_add_u64 v[162:163], v[162:163], 0, v[30:31]
	v_lshlrev_b32_e32 v206, 16, v76
	v_and_b32_e32 v207, 0xffff0000, v76
	v_lshlrev_b32_e32 v208, 16, v77
	v_and_b32_e32 v209, 0xffff0000, v77
	v_lshlrev_b32_e32 v210, 16, v78
	v_and_b32_e32 v211, 0xffff0000, v78
	v_lshlrev_b32_e32 v212, 16, v79
	v_and_b32_e32 v213, 0xffff0000, v79
	v_lshlrev_b32_e32 v214, 16, v80
	v_and_b32_e32 v215, 0xffff0000, v80
	v_lshlrev_b32_e32 v216, 16, v81
	v_and_b32_e32 v217, 0xffff0000, v81
	v_lshlrev_b32_e32 v218, 16, v82
	v_and_b32_e32 v219, 0xffff0000, v82
	v_lshlrev_b32_e32 v220, 16, v83
	v_and_b32_e32 v221, 0xffff0000, v83
	v_pk_fma_f32 v[2:3], v[104:105], v[222:223], v[174:175]
	v_pk_fma_f32 v[4:5], v[106:107], v[224:225], v[176:177]
	v_pk_fma_f32 v[6:7], v[108:109], v[226:227], v[178:179]
	v_pk_fma_f32 v[8:9], v[110:111], v[228:229], v[180:181]
	v_pk_fma_f32 v[10:11], v[112:113], v[230:231], v[182:183]
	v_pk_fma_f32 v[12:13], v[114:115], v[232:233], v[184:185]
	v_pk_fma_f32 v[14:15], v[116:117], v[234:235], v[186:187]
	v_pk_fma_f32 v[16:17], v[118:119], v[236:237], v[188:189]
	v_pk_fma_f32 v[2:3], v[120:121], v[190:191], v[2:3]
	v_pk_fma_f32 v[4:5], v[122:123], v[192:193], v[4:5]
	v_pk_fma_f32 v[6:7], v[124:125], v[194:195], v[6:7]
	v_pk_fma_f32 v[8:9], v[126:127], v[196:197], v[8:9]
	v_pk_fma_f32 v[10:11], v[128:129], v[198:199], v[10:11]
	v_pk_fma_f32 v[12:13], v[130:131], v[200:201], v[12:13]
	v_pk_fma_f32 v[14:15], v[132:133], v[202:203], v[14:15]
	v_pk_fma_f32 v[16:17], v[134:135], v[204:205], v[16:17]
	v_pk_fma_f32 v[2:3], v[136:137], v[206:207], v[2:3]
	v_pk_fma_f32 v[4:5], v[138:139], v[208:209], v[4:5]
	v_pk_fma_f32 v[6:7], v[140:141], v[210:211], v[6:7]
	v_pk_fma_f32 v[8:9], v[142:143], v[212:213], v[8:9]
	v_pk_fma_f32 v[10:11], v[144:145], v[214:215], v[10:11]
	v_pk_fma_f32 v[12:13], v[146:147], v[216:217], v[12:13]
	v_pk_fma_f32 v[14:15], v[148:149], v[218:219], v[14:15]
	v_pk_fma_f32 v[16:17], v[150:151], v[220:221], v[16:17]
	v_mul_f32_e32 v18, 0xbfb8aa3b, v2
	v_mul_f32_e32 v19, 0xbfb8aa3b, v3
	v_mul_f32_e32 v20, 0xbfb8aa3b, v4
	v_mul_f32_e32 v21, 0xbfb8aa3b, v5
	v_mul_f32_e32 v22, 0xbfb8aa3b, v6
	v_mul_f32_e32 v23, 0xbfb8aa3b, v7
	v_mul_f32_e32 v24, 0xbfb8aa3b, v8
	v_mul_f32_e32 v25, 0xbfb8aa3b, v9
	v_exp_f32_e32 v18, v18
	v_exp_f32_e32 v19, v19
	v_exp_f32_e32 v20, v20
	v_exp_f32_e32 v21, v21
	v_exp_f32_e32 v22, v22
	v_exp_f32_e32 v23, v23
	v_exp_f32_e32 v24, v24
	v_exp_f32_e32 v25, v25
	v_add_f32_e32 v18, 1.0, v18
	v_add_f32_e32 v19, 1.0, v19
	v_add_f32_e32 v20, 1.0, v20
	v_add_f32_e32 v21, 1.0, v21
	v_add_f32_e32 v22, 1.0, v22
	v_add_f32_e32 v23, 1.0, v23
	v_add_f32_e32 v24, 1.0, v24
	v_add_f32_e32 v25, 1.0, v25
	v_rcp_f32_e32 v18, v18
	v_rcp_f32_e32 v19, v19
	v_rcp_f32_e32 v20, v20
	v_rcp_f32_e32 v21, v21
	v_rcp_f32_e32 v22, v22
	v_rcp_f32_e32 v23, v23
	v_rcp_f32_e32 v24, v24
	v_rcp_f32_e32 v25, v25
	v_mul_f32_e32 v18, v2, v18
	v_mul_f32_e32 v19, v3, v19
	v_mul_f32_e32 v20, v4, v20
	v_mul_f32_e32 v21, v5, v21
	v_mul_f32_e32 v22, v6, v22
	v_mul_f32_e32 v23, v7, v23
	v_mul_f32_e32 v24, v8, v24
	v_mul_f32_e32 v25, v9, v25
	v_mul_f32_e32 v18, v10, v18
	v_mul_f32_e32 v19, v11, v19
	v_mul_f32_e32 v20, v12, v20
	v_mul_f32_e32 v21, v13, v21
	v_mul_f32_e32 v22, v14, v22
	v_mul_f32_e32 v23, v15, v23
	v_mul_f32_e32 v24, v16, v24
	v_mul_f32_e32 v25, v17, v25
	v_cvt_pk_bf16_f32 v26, v18, v19
	v_cvt_pk_bf16_f32 v27, v20, v21
	v_cvt_pk_bf16_f32 v28, v22, v23
	v_cvt_pk_bf16_f32 v29, v24, v25
	global_store_dwordx4 v[162:163], v[26:29], off sc1
	v_lshl_add_u64 v[162:163], v[162:163], 0, v[30:31]
	v_lshlrev_b32_e32 v222, 16, v88
	v_and_b32_e32 v223, 0xffff0000, v88
	v_lshlrev_b32_e32 v224, 16, v89
	v_and_b32_e32 v225, 0xffff0000, v89
	v_lshlrev_b32_e32 v226, 16, v90
	v_and_b32_e32 v227, 0xffff0000, v90
	v_lshlrev_b32_e32 v228, 16, v91
	v_and_b32_e32 v229, 0xffff0000, v91
	v_lshlrev_b32_e32 v230, 16, v92
	v_and_b32_e32 v231, 0xffff0000, v92
	v_lshlrev_b32_e32 v232, 16, v93
	v_and_b32_e32 v233, 0xffff0000, v93
	v_lshlrev_b32_e32 v234, 16, v94
	v_and_b32_e32 v235, 0xffff0000, v94
	v_lshlrev_b32_e32 v236, 16, v95
	v_and_b32_e32 v237, 0xffff0000, v95
	v_pk_fma_f32 v[2:3], v[104:105], v[190:191], v[174:175]
	v_pk_fma_f32 v[4:5], v[106:107], v[192:193], v[176:177]
	v_pk_fma_f32 v[6:7], v[108:109], v[194:195], v[178:179]
	v_pk_fma_f32 v[8:9], v[110:111], v[196:197], v[180:181]
	v_pk_fma_f32 v[10:11], v[112:113], v[198:199], v[182:183]
	v_pk_fma_f32 v[12:13], v[114:115], v[200:201], v[184:185]
	v_pk_fma_f32 v[14:15], v[116:117], v[202:203], v[186:187]
	v_pk_fma_f32 v[16:17], v[118:119], v[204:205], v[188:189]
	v_pk_fma_f32 v[2:3], v[120:121], v[206:207], v[2:3]
	v_pk_fma_f32 v[4:5], v[122:123], v[208:209], v[4:5]
	v_pk_fma_f32 v[6:7], v[124:125], v[210:211], v[6:7]
	v_pk_fma_f32 v[8:9], v[126:127], v[212:213], v[8:9]
	v_pk_fma_f32 v[10:11], v[128:129], v[214:215], v[10:11]
	v_pk_fma_f32 v[12:13], v[130:131], v[216:217], v[12:13]
	v_pk_fma_f32 v[14:15], v[132:133], v[218:219], v[14:15]
	v_pk_fma_f32 v[16:17], v[134:135], v[220:221], v[16:17]
	v_pk_fma_f32 v[2:3], v[136:137], v[222:223], v[2:3]
	v_pk_fma_f32 v[4:5], v[138:139], v[224:225], v[4:5]
	v_pk_fma_f32 v[6:7], v[140:141], v[226:227], v[6:7]
	v_pk_fma_f32 v[8:9], v[142:143], v[228:229], v[8:9]
	v_pk_fma_f32 v[10:11], v[144:145], v[230:231], v[10:11]
	v_pk_fma_f32 v[12:13], v[146:147], v[232:233], v[12:13]
	v_pk_fma_f32 v[14:15], v[148:149], v[234:235], v[14:15]
	v_pk_fma_f32 v[16:17], v[150:151], v[236:237], v[16:17]
	v_mul_f32_e32 v18, 0xbfb8aa3b, v2
	v_mul_f32_e32 v19, 0xbfb8aa3b, v3
	v_mul_f32_e32 v20, 0xbfb8aa3b, v4
	v_mul_f32_e32 v21, 0xbfb8aa3b, v5
	v_mul_f32_e32 v22, 0xbfb8aa3b, v6
	v_mul_f32_e32 v23, 0xbfb8aa3b, v7
	v_mul_f32_e32 v24, 0xbfb8aa3b, v8
	v_mul_f32_e32 v25, 0xbfb8aa3b, v9
	v_exp_f32_e32 v18, v18
	v_exp_f32_e32 v19, v19
	v_exp_f32_e32 v20, v20
	v_exp_f32_e32 v21, v21
	v_exp_f32_e32 v22, v22
	v_exp_f32_e32 v23, v23
	v_exp_f32_e32 v24, v24
	v_exp_f32_e32 v25, v25
	v_add_f32_e32 v18, 1.0, v18
	v_add_f32_e32 v19, 1.0, v19
	v_add_f32_e32 v20, 1.0, v20
	v_add_f32_e32 v21, 1.0, v21
	v_add_f32_e32 v22, 1.0, v22
	v_add_f32_e32 v23, 1.0, v23
	v_add_f32_e32 v24, 1.0, v24
	v_add_f32_e32 v25, 1.0, v25
	v_rcp_f32_e32 v18, v18
	v_rcp_f32_e32 v19, v19
	v_rcp_f32_e32 v20, v20
	v_rcp_f32_e32 v21, v21
	v_rcp_f32_e32 v22, v22
	v_rcp_f32_e32 v23, v23
	v_rcp_f32_e32 v24, v24
	v_rcp_f32_e32 v25, v25
	v_mul_f32_e32 v18, v2, v18
	v_mul_f32_e32 v19, v3, v19
	v_mul_f32_e32 v20, v4, v20
	v_mul_f32_e32 v21, v5, v21
	v_mul_f32_e32 v22, v6, v22
	v_mul_f32_e32 v23, v7, v23
	v_mul_f32_e32 v24, v8, v24
	v_mul_f32_e32 v25, v9, v25
	v_mul_f32_e32 v18, v10, v18
	v_mul_f32_e32 v19, v11, v19
	v_mul_f32_e32 v20, v12, v20
	v_mul_f32_e32 v21, v13, v21
	v_mul_f32_e32 v22, v14, v22
	v_mul_f32_e32 v23, v15, v23
	v_mul_f32_e32 v24, v16, v24
	v_mul_f32_e32 v25, v17, v25
	v_cvt_pk_bf16_f32 v26, v18, v19
	v_cvt_pk_bf16_f32 v27, v20, v21
	v_cvt_pk_bf16_f32 v28, v22, v23
	v_cvt_pk_bf16_f32 v29, v24, v25
	global_store_dwordx4 v[162:163], v[26:29], off sc1
	v_lshl_add_u64 v[162:163], v[162:163], 0, v[30:31]
	v_lshlrev_b32_e32 v190, 16, v96
	v_and_b32_e32 v191, 0xffff0000, v96
	v_lshlrev_b32_e32 v192, 16, v97
	v_and_b32_e32 v193, 0xffff0000, v97
	v_lshlrev_b32_e32 v194, 16, v98
	v_and_b32_e32 v195, 0xffff0000, v98
	v_lshlrev_b32_e32 v196, 16, v99
	v_and_b32_e32 v197, 0xffff0000, v99
	v_lshlrev_b32_e32 v198, 16, v100
	v_and_b32_e32 v199, 0xffff0000, v100
	v_lshlrev_b32_e32 v200, 16, v101
	v_and_b32_e32 v201, 0xffff0000, v101
	v_lshlrev_b32_e32 v202, 16, v102
	v_and_b32_e32 v203, 0xffff0000, v102
	v_lshlrev_b32_e32 v204, 16, v103
	v_and_b32_e32 v205, 0xffff0000, v103
	v_pk_fma_f32 v[2:3], v[104:105], v[206:207], v[174:175]
	v_pk_fma_f32 v[4:5], v[106:107], v[208:209], v[176:177]
	v_pk_fma_f32 v[6:7], v[108:109], v[210:211], v[178:179]
	v_pk_fma_f32 v[8:9], v[110:111], v[212:213], v[180:181]
	v_pk_fma_f32 v[10:11], v[112:113], v[214:215], v[182:183]
	v_pk_fma_f32 v[12:13], v[114:115], v[216:217], v[184:185]
	v_pk_fma_f32 v[14:15], v[116:117], v[218:219], v[186:187]
	v_pk_fma_f32 v[16:17], v[118:119], v[220:221], v[188:189]
	v_pk_fma_f32 v[2:3], v[120:121], v[222:223], v[2:3]
	v_pk_fma_f32 v[4:5], v[122:123], v[224:225], v[4:5]
	v_pk_fma_f32 v[6:7], v[124:125], v[226:227], v[6:7]
	v_pk_fma_f32 v[8:9], v[126:127], v[228:229], v[8:9]
	v_pk_fma_f32 v[10:11], v[128:129], v[230:231], v[10:11]
	v_pk_fma_f32 v[12:13], v[130:131], v[232:233], v[12:13]
	v_pk_fma_f32 v[14:15], v[132:133], v[234:235], v[14:15]
	v_pk_fma_f32 v[16:17], v[134:135], v[236:237], v[16:17]
	v_pk_fma_f32 v[2:3], v[136:137], v[190:191], v[2:3]
	v_pk_fma_f32 v[4:5], v[138:139], v[192:193], v[4:5]
	v_pk_fma_f32 v[6:7], v[140:141], v[194:195], v[6:7]
	v_pk_fma_f32 v[8:9], v[142:143], v[196:197], v[8:9]
	v_pk_fma_f32 v[10:11], v[144:145], v[198:199], v[10:11]
	v_pk_fma_f32 v[12:13], v[146:147], v[200:201], v[12:13]
	v_pk_fma_f32 v[14:15], v[148:149], v[202:203], v[14:15]
	v_pk_fma_f32 v[16:17], v[150:151], v[204:205], v[16:17]
	v_mul_f32_e32 v18, 0xbfb8aa3b, v2
	v_mul_f32_e32 v19, 0xbfb8aa3b, v3
	v_mul_f32_e32 v20, 0xbfb8aa3b, v4
	v_mul_f32_e32 v21, 0xbfb8aa3b, v5
	v_mul_f32_e32 v22, 0xbfb8aa3b, v6
	v_mul_f32_e32 v23, 0xbfb8aa3b, v7
	v_mul_f32_e32 v24, 0xbfb8aa3b, v8
	v_mul_f32_e32 v25, 0xbfb8aa3b, v9
	v_exp_f32_e32 v18, v18
	v_exp_f32_e32 v19, v19
	v_exp_f32_e32 v20, v20
	v_exp_f32_e32 v21, v21
	v_exp_f32_e32 v22, v22
	v_exp_f32_e32 v23, v23
	v_exp_f32_e32 v24, v24
	v_exp_f32_e32 v25, v25
	v_add_f32_e32 v18, 1.0, v18
	v_add_f32_e32 v19, 1.0, v19
	v_add_f32_e32 v20, 1.0, v20
	v_add_f32_e32 v21, 1.0, v21
	v_add_f32_e32 v22, 1.0, v22
	v_add_f32_e32 v23, 1.0, v23
	v_add_f32_e32 v24, 1.0, v24
	v_add_f32_e32 v25, 1.0, v25
	v_rcp_f32_e32 v18, v18
	v_rcp_f32_e32 v19, v19
	v_rcp_f32_e32 v20, v20
	v_rcp_f32_e32 v21, v21
	v_rcp_f32_e32 v22, v22
	v_rcp_f32_e32 v23, v23
	v_rcp_f32_e32 v24, v24
	v_rcp_f32_e32 v25, v25
	v_mul_f32_e32 v18, v2, v18
	v_mul_f32_e32 v19, v3, v19
	v_mul_f32_e32 v20, v4, v20
	v_mul_f32_e32 v21, v5, v21
	v_mul_f32_e32 v22, v6, v22
	v_mul_f32_e32 v23, v7, v23
	v_mul_f32_e32 v24, v8, v24
	v_mul_f32_e32 v25, v9, v25
	v_mul_f32_e32 v18, v10, v18
	v_mul_f32_e32 v19, v11, v19
	v_mul_f32_e32 v20, v12, v20
	v_mul_f32_e32 v21, v13, v21
	v_mul_f32_e32 v22, v14, v22
	v_mul_f32_e32 v23, v15, v23
	v_mul_f32_e32 v24, v16, v24
	v_mul_f32_e32 v25, v17, v25
	v_cvt_pk_bf16_f32 v26, v18, v19
	v_cvt_pk_bf16_f32 v27, v20, v21
	v_cvt_pk_bf16_f32 v28, v22, v23
	v_cvt_pk_bf16_f32 v29, v24, v25
	global_store_dwordx4 v[162:163], v[26:29], off sc1
	v_lshl_add_u64 v[162:163], v[162:163], 0, v[30:31]
	s_branch .LBB0_2504
